# v1 + write-through (sc1) stores in the GEMM epilogues A/E/F/G so the seam's L2 writeback is short
# baseline (speedup 1.0000x reference)
; __device__ __forceinline__ unsigned cvt_pk_bf16(float lo, float hi) { f32x2 v = {lo, hi}; bf16x2_t b = __builtin_convertvector(v, bf16x2_t); return __builtin_bit_cast(unsigned, b); }
;     __device__ __forceinline__ void operator()(const f32x4 (&acc)[2][2][4][2], const Unit& u, int wr, int wc, int fr, int fq, int buf) const {
;     ...
;             for (int m = 0; m < 4; ++m) { const int row = row0 + ai * HALF + m * 16;
;                 const float sc = rtab[buf * BM + wr * 64 + fr + ai * HALF + m * 16];
;                 int prow = row;
;                 if (PERMROWS && u.pn >= 24) { const int sh = 2 * ((u.pn - 24) / 6), t = row & 8191; prow = (row & ~8191) + ((t & ((1 << sh) - 1)) << (13 - sh)) + (t >> sh); }
;                 bf16_t* rowp = BLK ? O + ((size_t)(2 * u.pn) * ldc + prow) * 128 + wc * 32 + 8 * fq : O + (size_t)row * ldc + col0;
; #pragma unroll
;                 for (int bj = 0; bj < 2; ++bj) { f32x4 v0 = acc[ai][bj][m][0] * sc, v1 = acc[ai][bj][m][1] * sc;
;                     if (ACT == 1) {
; #pragma unroll
;                         for (int e = 0; e < 4; ++e) { float a = v0[e] > 0.f ? v0[e] : 0.f; v0[e] = a * a; float b = v1[e] > 0.f ? v1[e] : 0.f; v1[e] = b * b; } }
;                     u32x4 w; w.x = cvt_pk_bf16(v0[0], v0[1]); w.y = cvt_pk_bf16(v0[2], v0[3]); w.z = cvt_pk_bf16(v1[0], v1[1]); w.w = cvt_pk_bf16(v1[2], v1[3]);
;                     *(u32x4*)(rowp + (BLK ? (size_t)bj * ldc * 128 : (size_t)bj * HALF)) = w; } }
.LBB0_144:
	s_lshl_b32 s30, s63, 1
	s_ashr_i32 s31, s30, 31
	s_lshl_b64 s[30:31], s[30:31], 14
	v_ashrrev_i32_e32 v145, 31, v144
	v_lshl_add_u64 v[144:145], s[30:31], 0, v[144:145]
	v_lshlrev_b64 v[144:145], 8, v[144:145]
	s_waitcnt lgkmcnt(0)
	v_pk_mul_f32 v[128:129], v[128:129], v[142:143] op_sel_hi:[1,0]
	v_pk_mul_f32 v[126:127], v[126:127], v[142:143] op_sel_hi:[1,0]
	v_pk_mul_f32 v[156:157], v[124:125], v[142:143] op_sel_hi:[1,0]
	v_pk_mul_f32 v[124:125], v[122:123], v[142:143] op_sel_hi:[1,0]
	v_lshl_add_u64 v[144:145], v[136:137], 0, v[144:145]
	v_cvt_pk_bf16_f32 v122, v126, v127
	v_cvt_pk_bf16_f32 v123, v128, v129
	v_cvt_pk_bf16_f32 v124, v124, v125
	v_cvt_pk_bf16_f32 v125, v156, v157
	v_pk_mul_f32 v[118:119], v[118:119], v[142:143] op_sel_hi:[1,0]
	global_store_dwordx4 v[144:145], v[122:125], off sc1
	v_pk_mul_f32 v[120:121], v[120:121], v[142:143] op_sel_hi:[1,0]
	s_nop 0
	v_pk_mul_f32 v[122:123], v[116:117], v[142:143] op_sel_hi:[1,0]
	v_pk_mul_f32 v[116:117], v[114:115], v[142:143] op_sel_hi:[1,0]
	v_cvt_pk_bf16_f32 v114, v118, v119
	v_add_co_u32_e32 v118, vcc, 0x400000, v144
	v_cvt_pk_bf16_f32 v115, v120, v121
	v_cvt_pk_bf16_f32 v116, v116, v117
	v_cvt_pk_bf16_f32 v117, v122, v123
	v_addc_co_u32_e32 v119, vcc, 0, v145, vcc
	global_store_dwordx4 v[118:119], v[114:117], off sc1
	ds_read_b32 v114, v152 offset:64
	s_andn2_b64 vcc, exec, s[36:37]
	v_cndmask_b32_e64 v115, 0, 1, s[36:37]
	v_cmp_ne_u32_e64 s[44:45], 1, v115
	v_or_b32_e32 v116, 16, v153
	s_cbranch_vccnz .LBB0_146
	s_sub_i32 s23, s63, 24
	s_mul_hi_u32 s23, s23, 0xaaaaaaab
	s_lshr_b32 s23, s23, 1
	s_and_b32 s23, s23, 0x7ffffffe
	v_and_b32_e32 v115, 0x1fdf, v116
	s_sub_i32 s25, 13, s23
	v_lshlrev_b32_e32 v116, s25, v116
	v_lshrrev_b32_e32 v115, s23, v115
	v_and_b32_e32 v116, 0x1ffe, v116
	v_or_b32_e32 v115, v115, v154
	v_add_u32_e32 v116, v115, v116
.LBB0_146:
	v_ashrrev_i32_e32 v117, 31, v116
	v_lshl_add_u64 v[116:117], s[30:31], 0, v[116:117]
	v_lshlrev_b64 v[116:117], 8, v[116:117]
	s_waitcnt lgkmcnt(0)
	v_pk_mul_f32 v[112:113], v[112:113], v[114:115] op_sel_hi:[1,0]
	v_pk_mul_f32 v[110:111], v[110:111], v[114:115] op_sel_hi:[1,0]
	v_pk_mul_f32 v[118:119], v[108:109], v[114:115] op_sel_hi:[1,0]
	v_pk_mul_f32 v[108:109], v[106:107], v[114:115] op_sel_hi:[1,0]
	v_lshl_add_u64 v[116:117], v[136:137], 0, v[116:117]
	v_cvt_pk_bf16_f32 v106, v110, v111
	v_cvt_pk_bf16_f32 v107, v112, v113
	v_cvt_pk_bf16_f32 v108, v108, v109
	v_cvt_pk_bf16_f32 v109, v118, v119
	v_pk_mul_f32 v[102:103], v[102:103], v[114:115] op_sel_hi:[1,0]
	v_pk_mul_f32 v[98:99], v[98:99], v[114:115] op_sel_hi:[1,0]
	global_store_dwordx4 v[116:117], v[106:109], off sc1
	v_pk_mul_f32 v[104:105], v[104:105], v[114:115] op_sel_hi:[1,0]
	s_nop 0
	v_pk_mul_f32 v[106:107], v[100:101], v[114:115] op_sel_hi:[1,0]
	v_cvt_pk_bf16_f32 v100, v102, v103
	v_cvt_pk_bf16_f32 v102, v98, v99
	ds_read_b32 v98, v152 offset:128
	v_cvt_pk_bf16_f32 v101, v104, v105
	v_add_co_u32_e32 v104, vcc, 0x400000, v116
	v_cvt_pk_bf16_f32 v103, v106, v107
	s_nop 0
	v_addc_co_u32_e32 v105, vcc, 0, v117, vcc
	global_store_dwordx4 v[104:105], v[100:103], off sc1
	s_and_b64 vcc, exec, s[44:45]
	s_nop 0
	v_or_b32_e32 v100, 32, v153
	s_cbranch_vccnz .LBB0_148
	s_sub_i32 s23, s63, 24
	s_mul_hi_u32 s23, s23, 0xaaaaaaab
	s_lshr_b32 s23, s23, 1
	s_and_b32 s23, s23, 0x7ffffffe
	v_and_b32_e32 v99, 0x1fef, v100
	s_sub_i32 s25, 13, s23
	v_lshlrev_b32_e32 v100, s25, v100
	v_lshrrev_b32_e32 v99, s23, v99
	v_and_b32_e32 v100, 0x1ffe, v100
	v_or_b32_e32 v99, v99, v154
	v_add_u32_e32 v100, v99, v100
.LBB0_148:
	v_ashrrev_i32_e32 v101, 31, v100
	v_lshl_add_u64 v[100:101], s[30:31], 0, v[100:101]
	v_lshlrev_b64 v[100:101], 8, v[100:101]
	s_waitcnt lgkmcnt(0)
	v_pk_mul_f32 v[96:97], v[96:97], v[98:99] op_sel_hi:[1,0]
	v_pk_mul_f32 v[94:95], v[94:95], v[98:99] op_sel_hi:[1,0]
	v_pk_mul_f32 v[102:103], v[92:93], v[98:99] op_sel_hi:[1,0]
	v_pk_mul_f32 v[92:93], v[90:91], v[98:99] op_sel_hi:[1,0]
	v_lshl_add_u64 v[100:101], v[136:137], 0, v[100:101]
	v_cvt_pk_bf16_f32 v90, v94, v95
	v_cvt_pk_bf16_f32 v91, v96, v97
	v_cvt_pk_bf16_f32 v92, v92, v93
	v_cvt_pk_bf16_f32 v93, v102, v103
	v_pk_mul_f32 v[86:87], v[86:87], v[98:99] op_sel_hi:[1,0]
	v_pk_mul_f32 v[82:83], v[82:83], v[98:99] op_sel_hi:[1,0]
	global_store_dwordx4 v[100:101], v[90:93], off sc1
	v_pk_mul_f32 v[88:89], v[88:89], v[98:99] op_sel_hi:[1,0]
	s_nop 0
	v_pk_mul_f32 v[90:91], v[84:85], v[98:99] op_sel_hi:[1,0]
	v_cvt_pk_bf16_f32 v84, v86, v87
	v_cvt_pk_bf16_f32 v86, v82, v83
	ds_read_b32 v82, v152 offset:192
	v_cvt_pk_bf16_f32 v85, v88, v89
	v_add_co_u32_e32 v88, vcc, 0x400000, v100
	v_cvt_pk_bf16_f32 v87, v90, v91
	s_nop 0
	v_addc_co_u32_e32 v89, vcc, 0, v101, vcc
	global_store_dwordx4 v[88:89], v[84:87], off sc1
	s_and_b64 vcc, exec, s[44:45]
	s_nop 0
	v_or_b32_e32 v84, 48, v153
	s_cbranch_vccnz .LBB0_150
	s_sub_i32 s23, s63, 24
	s_mul_hi_u32 s23, s23, 0xaaaaaaab
	s_lshr_b32 s23, s23, 1
	s_and_b32 s23, s23, 0x7ffffffe
	v_and_b32_e32 v83, 0x1fff, v84
	s_sub_i32 s25, 13, s23
	v_lshlrev_b32_e32 v84, s25, v84
	v_lshrrev_b32_e32 v83, s23, v83
	v_and_b32_e32 v84, 0x1ffe, v84
	v_or_b32_e32 v83, v83, v154
	v_add_u32_e32 v84, v83, v84
; __device__ __forceinline__ unsigned cvt_pk_bf16(float lo, float hi) { f32x2 v = {lo, hi}; bf16x2_t b = __builtin_convertvector(v, bf16x2_t); return __builtin_bit_cast(unsigned, b); }
;     __device__ __forceinline__ void operator()(const f32x4 (&acc)[2][2][4][2], const Unit& u, int wr, int wc, int fr, int fq, int buf) const {
;     ...
;             for (int m = 0; m < 4; ++m) { const int row = row0 + ai * HALF + m * 16;
;                 const float sc = rtab[buf * BM + wr * 64 + fr + ai * HALF + m * 16];
;                 int prow = row;
;                 if (PERMROWS && u.pn >= 24) { const int sh = 2 * ((u.pn - 24) / 6), t = row & 8191; prow = (row & ~8191) + ((t & ((1 << sh) - 1)) << (13 - sh)) + (t >> sh); }
;                 bf16_t* rowp = BLK ? O + ((size_t)(2 * u.pn) * ldc + prow) * 128 + wc * 32 + 8 * fq : O + (size_t)row * ldc + col0;
; #pragma unroll
;                 for (int bj = 0; bj < 2; ++bj) { f32x4 v0 = acc[ai][bj][m][0] * sc, v1 = acc[ai][bj][m][1] * sc;
;                     if (ACT == 1) {
; #pragma unroll
;                         for (int e = 0; e < 4; ++e) { float a = v0[e] > 0.f ? v0[e] : 0.f; v0[e] = a * a; float b = v1[e] > 0.f ? v1[e] : 0.f; v1[e] = b * b; } }
;                     u32x4 w; w.x = cvt_pk_bf16(v0[0], v0[1]); w.y = cvt_pk_bf16(v0[2], v0[3]); w.z = cvt_pk_bf16(v1[0], v1[1]); w.w = cvt_pk_bf16(v1[2], v1[3]);
;                     *(u32x4*)(rowp + (BLK ? (size_t)bj * ldc * 128 : (size_t)bj * HALF)) = w; } }
.LBB0_150:
	v_ashrrev_i32_e32 v85, 31, v84
	v_lshl_add_u64 v[84:85], s[30:31], 0, v[84:85]
	v_lshlrev_b64 v[84:85], 8, v[84:85]
	s_waitcnt lgkmcnt(0)
	v_pk_mul_f32 v[80:81], v[80:81], v[82:83] op_sel_hi:[1,0]
	v_pk_mul_f32 v[78:79], v[78:79], v[82:83] op_sel_hi:[1,0]
	v_pk_mul_f32 v[86:87], v[76:77], v[82:83] op_sel_hi:[1,0]
	v_pk_mul_f32 v[76:77], v[74:75], v[82:83] op_sel_hi:[1,0]
	v_lshl_add_u64 v[84:85], v[136:137], 0, v[84:85]
	v_cvt_pk_bf16_f32 v74, v78, v79
	v_cvt_pk_bf16_f32 v75, v80, v81
	v_cvt_pk_bf16_f32 v76, v76, v77
	v_cvt_pk_bf16_f32 v77, v86, v87
	v_pk_mul_f32 v[70:71], v[70:71], v[82:83] op_sel_hi:[1,0]
	global_store_dwordx4 v[84:85], v[74:77], off sc1
	v_pk_mul_f32 v[72:73], v[72:73], v[82:83] op_sel_hi:[1,0]
	s_nop 0
	v_pk_mul_f32 v[74:75], v[68:69], v[82:83] op_sel_hi:[1,0]
	v_pk_mul_f32 v[68:69], v[66:67], v[82:83] op_sel_hi:[1,0]
	v_cvt_pk_bf16_f32 v66, v70, v71
	v_add_co_u32_e32 v70, vcc, 0x400000, v84
	v_cvt_pk_bf16_f32 v67, v72, v73
	v_cvt_pk_bf16_f32 v68, v68, v69
	v_cvt_pk_bf16_f32 v69, v74, v75
	v_addc_co_u32_e32 v71, vcc, 0, v85, vcc
	global_store_dwordx4 v[70:71], v[66:69], off sc1
	ds_read_b32 v66, v152 offset:512
	v_add_u32_e32 v70, 0x80, v153
	v_and_b32_e32 v67, 0xffffe000, v70
	s_and_b64 vcc, exec, s[44:45]
	v_mov_b32_e32 v68, v70
	s_cbranch_vccnz .LBB0_152
	s_sub_i32 s23, s63, 24
	s_mul_hi_u32 s23, s23, 0xaaaaaaab
	s_lshr_b32 s23, s23, 1
	s_and_b32 s23, s23, 0x7ffffffe
	v_and_b32_e32 v68, 0x1fcf, v70
	s_sub_i32 s25, 13, s23
	v_lshlrev_b32_e32 v69, s25, v70
	v_lshrrev_b32_e32 v68, s23, v68
	v_and_b32_e32 v69, 0x1ffe, v69
	v_or_b32_e32 v68, v68, v67
	v_add_u32_e32 v68, v68, v69
.LBB0_152:
	v_ashrrev_i32_e32 v69, 31, v68
	v_lshl_add_u64 v[68:69], s[30:31], 0, v[68:69]
	v_lshlrev_b64 v[68:69], 8, v[68:69]
	s_waitcnt lgkmcnt(0)
	v_pk_mul_f32 v[64:65], v[64:65], v[66:67] op_sel_hi:[1,0]
	v_pk_mul_f32 v[62:63], v[62:63], v[66:67] op_sel_hi:[1,0]
	v_pk_mul_f32 v[72:73], v[60:61], v[66:67] op_sel_hi:[1,0]
	v_pk_mul_f32 v[60:61], v[58:59], v[66:67] op_sel_hi:[1,0]
	v_lshl_add_u64 v[68:69], v[136:137], 0, v[68:69]
	v_cvt_pk_bf16_f32 v58, v62, v63
	v_cvt_pk_bf16_f32 v59, v64, v65
	v_cvt_pk_bf16_f32 v60, v60, v61
	v_cvt_pk_bf16_f32 v61, v72, v73
	v_pk_mul_f32 v[54:55], v[54:55], v[66:67] op_sel_hi:[1,0]
	v_pk_mul_f32 v[50:51], v[50:51], v[66:67] op_sel_hi:[1,0]
	global_store_dwordx4 v[68:69], v[58:61], off sc1
	v_pk_mul_f32 v[56:57], v[56:57], v[66:67] op_sel_hi:[1,0]
	s_nop 0
	v_pk_mul_f32 v[58:59], v[52:53], v[66:67] op_sel_hi:[1,0]
	v_cvt_pk_bf16_f32 v52, v54, v55
	v_cvt_pk_bf16_f32 v54, v50, v51
	ds_read_b32 v50, v152 offset:576
	v_cvt_pk_bf16_f32 v53, v56, v57
	v_add_co_u32_e32 v56, vcc, 0x400000, v68
	v_cvt_pk_bf16_f32 v55, v58, v59
	s_nop 0
	v_addc_co_u32_e32 v57, vcc, 0, v69, vcc
	global_store_dwordx4 v[56:57], v[52:55], off sc1
	s_and_b64 vcc, exec, s[44:45]
	s_nop 0
	v_or_b32_e32 v52, 16, v70
	s_cbranch_vccnz .LBB0_154
	s_sub_i32 s23, s63, 24
	s_mul_hi_u32 s23, s23, 0xaaaaaaab
	s_lshr_b32 s23, s23, 1
	s_and_b32 s23, s23, 0x7ffffffe
	v_and_b32_e32 v51, 0x1fdf, v52
	s_sub_i32 s25, 13, s23
	v_lshlrev_b32_e32 v52, s25, v52
	v_lshrrev_b32_e32 v51, s23, v51
	v_and_b32_e32 v52, 0x1ffe, v52
	v_or_b32_e32 v51, v51, v67
	v_add_u32_e32 v52, v51, v52
.LBB0_154:
	v_ashrrev_i32_e32 v53, 31, v52
	v_lshl_add_u64 v[52:53], s[30:31], 0, v[52:53]
	v_lshlrev_b64 v[52:53], 8, v[52:53]
	s_waitcnt lgkmcnt(0)
	v_pk_mul_f32 v[48:49], v[48:49], v[50:51] op_sel_hi:[1,0]
	v_pk_mul_f32 v[46:47], v[46:47], v[50:51] op_sel_hi:[1,0]
	v_pk_mul_f32 v[54:55], v[44:45], v[50:51] op_sel_hi:[1,0]
	v_pk_mul_f32 v[44:45], v[42:43], v[50:51] op_sel_hi:[1,0]
	v_lshl_add_u64 v[52:53], v[136:137], 0, v[52:53]
	v_cvt_pk_bf16_f32 v42, v46, v47
	v_cvt_pk_bf16_f32 v43, v48, v49
	v_cvt_pk_bf16_f32 v44, v44, v45
	v_cvt_pk_bf16_f32 v45, v54, v55
	v_pk_mul_f32 v[38:39], v[38:39], v[50:51] op_sel_hi:[1,0]
	v_pk_mul_f32 v[34:35], v[34:35], v[50:51] op_sel_hi:[1,0]
	global_store_dwordx4 v[52:53], v[42:45], off sc1
	v_pk_mul_f32 v[40:41], v[40:41], v[50:51] op_sel_hi:[1,0]
	s_nop 0
	v_pk_mul_f32 v[42:43], v[36:37], v[50:51] op_sel_hi:[1,0]
	v_cvt_pk_bf16_f32 v36, v38, v39
	v_cvt_pk_bf16_f32 v38, v34, v35
	ds_read_b32 v34, v152 offset:640
	v_cvt_pk_bf16_f32 v37, v40, v41
	v_add_co_u32_e32 v40, vcc, 0x400000, v52
	v_cvt_pk_bf16_f32 v39, v42, v43
	s_nop 0
	v_addc_co_u32_e32 v41, vcc, 0, v53, vcc
	global_store_dwordx4 v[40:41], v[36:39], off sc1
	s_and_b64 vcc, exec, s[44:45]
	s_nop 0
	v_or_b32_e32 v36, 32, v70
	s_cbranch_vccnz .LBB0_156
	s_sub_i32 s23, s63, 24
	s_mul_hi_u32 s23, s23, 0xaaaaaaab
	s_lshr_b32 s23, s23, 1
	s_and_b32 s23, s23, 0x7ffffffe
	v_and_b32_e32 v35, 0x1fef, v36
	s_sub_i32 s25, 13, s23
	v_lshlrev_b32_e32 v36, s25, v36
	v_lshrrev_b32_e32 v35, s23, v35
	v_and_b32_e32 v36, 0x1ffe, v36
	v_or_b32_e32 v35, v35, v67
	v_add_u32_e32 v36, v35, v36
; __device__ __forceinline__ unsigned cvt_pk_bf16(float lo, float hi) { f32x2 v = {lo, hi}; bf16x2_t b = __builtin_convertvector(v, bf16x2_t); return __builtin_bit_cast(unsigned, b); }
;     __device__ __forceinline__ void prep(const Unit& u, int tid, int buf) const {
;         if (tid < BM) { const float* p = ss + (size_t)(u.pm * BM + tid) * 32; float sq = 0.f;
; #pragma unroll
;             for (int i = 0; i < 8; ++i) { const f32x4 v = *(const f32x4*)(p + 4 * i); sq += (v[0] + v[1]) + (v[2] + v[3]); }
;             rtab[buf * BM + tid] = __builtin_amdgcn_rsqf(sq * (1.0f / 2048.0f) + 1e-6f); }
;     __device__ __forceinline__ void operator()(const f32x4 (&acc)[2][2][4][2], const Unit& u, int wr, int wc, int fr, int fq, int buf) const {
;     ...
;                 for (int bj = 0; bj < 2; ++bj) { f32x4 v0 = acc[ai][bj][m][0] * sc, v1 = acc[ai][bj][m][1] * sc;
;                     if (ACT == 1) {
; #pragma unroll
;                         for (int e = 0; e < 4; ++e) { float a = v0[e] > 0.f ? v0[e] : 0.f; v0[e] = a * a; float b = v1[e] > 0.f ? v1[e] : 0.f; v1[e] = b * b; } }
;                     u32x4 w; w.x = cvt_pk_bf16(v0[0], v0[1]); w.y = cvt_pk_bf16(v0[2], v0[3]); w.z = cvt_pk_bf16(v1[0], v1[1]); w.w = cvt_pk_bf16(v1[2], v1[3]);
;                     *(u32x4*)(rowp + (BLK ? (size_t)bj * ldc * 128 : (size_t)bj * HALF)) = w; } }
.LBB0_156:
	v_ashrrev_i32_e32 v37, 31, v36
	v_lshl_add_u64 v[36:37], s[30:31], 0, v[36:37]
	v_lshlrev_b64 v[36:37], 8, v[36:37]
	s_waitcnt lgkmcnt(0)
	v_pk_mul_f32 v[32:33], v[32:33], v[34:35] op_sel_hi:[1,0]
	v_pk_mul_f32 v[30:31], v[30:31], v[34:35] op_sel_hi:[1,0]
	v_pk_mul_f32 v[38:39], v[28:29], v[34:35] op_sel_hi:[1,0]
	v_pk_mul_f32 v[28:29], v[26:27], v[34:35] op_sel_hi:[1,0]
	v_lshl_add_u64 v[36:37], v[136:137], 0, v[36:37]
	v_cvt_pk_bf16_f32 v26, v30, v31
	v_cvt_pk_bf16_f32 v27, v32, v33
	v_cvt_pk_bf16_f32 v28, v28, v29
	v_cvt_pk_bf16_f32 v29, v38, v39
	v_pk_mul_f32 v[22:23], v[22:23], v[34:35] op_sel_hi:[1,0]
	v_pk_mul_f32 v[18:19], v[18:19], v[34:35] op_sel_hi:[1,0]
	global_store_dwordx4 v[36:37], v[26:29], off sc1
	v_pk_mul_f32 v[24:25], v[24:25], v[34:35] op_sel_hi:[1,0]
	s_nop 0
	v_pk_mul_f32 v[26:27], v[20:21], v[34:35] op_sel_hi:[1,0]
	v_cvt_pk_bf16_f32 v20, v22, v23
	v_cvt_pk_bf16_f32 v22, v18, v19
	ds_read_b32 v18, v152 offset:704
	v_cvt_pk_bf16_f32 v21, v24, v25
	v_add_co_u32_e32 v24, vcc, 0x400000, v36
	v_cvt_pk_bf16_f32 v23, v26, v27
	s_nop 0
	v_addc_co_u32_e32 v25, vcc, 0, v37, vcc
	global_store_dwordx4 v[24:25], v[20:23], off sc1
	s_and_b64 vcc, exec, s[44:45]
	s_nop 0
	v_or_b32_e32 v20, 48, v70
	s_cbranch_vccnz .LBB0_158
	s_sub_i32 s23, s63, 24
	s_mul_hi_u32 s23, s23, 0xaaaaaaab
	s_lshr_b32 s23, s23, 1
	s_and_b32 s23, s23, 0x7ffffffe
	v_and_b32_e32 v19, 0x1fff, v20
	s_sub_i32 s25, 13, s23
	v_lshlrev_b32_e32 v20, s25, v20
	v_lshrrev_b32_e32 v19, s23, v19
	v_and_b32_e32 v20, 0x1ffe, v20
	v_or_b32_e32 v19, v19, v67
	v_add_u32_e32 v20, v19, v20
.LBB0_158:
	v_ashrrev_i32_e32 v21, 31, v20
	v_lshl_add_u64 v[20:21], s[30:31], 0, v[20:21]
	v_lshlrev_b64 v[20:21], 8, v[20:21]
	s_waitcnt lgkmcnt(0)
	v_pk_mul_f32 v[16:17], v[16:17], v[18:19] op_sel_hi:[1,0]
	v_pk_mul_f32 v[14:15], v[14:15], v[18:19] op_sel_hi:[1,0]
	v_pk_mul_f32 v[22:23], v[12:13], v[18:19] op_sel_hi:[1,0]
	v_pk_mul_f32 v[12:13], v[10:11], v[18:19] op_sel_hi:[1,0]
	v_lshl_add_u64 v[20:21], v[136:137], 0, v[20:21]
	v_cvt_pk_bf16_f32 v10, v14, v15
	v_cvt_pk_bf16_f32 v11, v16, v17
	v_cvt_pk_bf16_f32 v12, v12, v13
	v_cvt_pk_bf16_f32 v13, v22, v23
	v_pk_mul_f32 v[6:7], v[6:7], v[18:19] op_sel_hi:[1,0]
	global_store_dwordx4 v[20:21], v[10:13], off sc1
	v_pk_mul_f32 v[8:9], v[8:9], v[18:19] op_sel_hi:[1,0]
	s_mov_b64 s[30:31], -1
	v_pk_mul_f32 v[10:11], v[4:5], v[18:19] op_sel_hi:[1,0]
	v_pk_mul_f32 v[4:5], v[2:3], v[18:19] op_sel_hi:[1,0]
	v_cvt_pk_bf16_f32 v2, v6, v7
	v_add_co_u32_e32 v6, vcc, 0x400000, v20
	v_cvt_pk_bf16_f32 v3, v8, v9
	s_nop 0
	v_addc_co_u32_e32 v7, vcc, 0, v21, vcc
	v_cvt_pk_bf16_f32 v4, v4, v5
	v_cvt_pk_bf16_f32 v5, v10, v11
	s_andn2_b64 vcc, exec, s[42:43]
	global_store_dwordx4 v[6:7], v[2:5], off sc1
	s_cbranch_vccnz .LBB0_135
	s_cmp_eq_u32 s24, s62
	s_cbranch_scc1 .LBB0_163
	s_add_i32 s60, s60, 1
	s_and_saveexec_b64 s[30:31], s[40:41]
	s_cbranch_execz .LBB0_162
	v_lshl_add_u32 v2, s24, 8, v146
	v_ashrrev_i32_e32 v3, 31, v2
	v_lshlrev_b64 v[2:3], 7, v[2:3]
	v_lshl_add_u64 v[18:19], s[12:13], 0, v[2:3]
	global_load_dwordx4 v[2:5], v[18:19], off offset:48
	global_load_dwordx4 v[6:9], v[18:19], off offset:32
	global_load_dwordx4 v[10:13], v[18:19], off
	global_load_dwordx4 v[14:17], v[18:19], off offset:16
	s_lshl_b32 s23, s60, 10
	s_and_b32 s23, s23, 0x400
	s_waitcnt vmcnt(0)
	v_add_f32_e32 v24, v2, v3
	v_add_f32_e32 v26, v4, v5
	v_mov_b32_e32 v20, v10
	v_mov_b32_e32 v21, v14
	v_mov_b32_e32 v14, v11
	v_pk_add_f32 v[10:11], v[20:21], v[14:15]
	v_mov_b32_e32 v14, v12
	v_mov_b32_e32 v15, v16
	v_mov_b32_e32 v16, v13
	v_pk_add_f32 v[12:13], v[14:15], v[16:17]
	s_nop 0
	v_pk_add_f32 v[10:11], v[10:11], v[12:13]
	s_nop 0
	v_add_f32_e32 v10, 0, v10
	v_add_f32_e32 v20, v10, v11
	v_mov_b32_e32 v10, v7
	v_mov_b32_e32 v11, v8
	v_mov_b32_e32 v7, v9
	v_pk_add_f32 v[6:7], v[10:11], v[6:7]
	s_nop 0
	v_pk_add_f32 v[22:23], v[6:7], v[6:7] op_sel:[0,1] op_sel_hi:[1,0]
	global_load_dwordx4 v[2:5], v[18:19], off offset:112
	global_load_dwordx4 v[6:9], v[18:19], off offset:96
	global_load_dwordx4 v[10:13], v[18:19], off offset:80
	global_load_dwordx4 v[14:17], v[18:19], off offset:64
	s_waitcnt vmcnt(2)
	v_add_f32_e32 v6, v6, v7
	v_add_f32_e32 v8, v8, v9
	s_waitcnt vmcnt(0)
	v_mov_b32_e32 v21, v14
	v_mov_b32_e32 v23, v15
	v_mov_b32_e32 v25, v16
	v_mov_b32_e32 v27, v17
	v_pk_add_f32 v[14:15], v[20:21], v[22:23]
	v_pk_add_f32 v[16:17], v[24:25], v[26:27]
	v_mov_b32_e32 v7, v4
	v_pk_add_f32 v[14:15], v[14:15], v[16:17]
	v_mov_b32_e32 v16, v11
	v_mov_b32_e32 v17, v12
	v_mov_b32_e32 v11, v13
	v_pk_add_f32 v[10:11], v[16:17], v[10:11]
	v_pk_add_f32 v[14:15], v[14:15], v[14:15] op_sel:[0,1] op_sel_hi:[1,0]
	v_pk_add_f32 v[10:11], v[10:11], v[10:11] op_sel:[0,1] op_sel_hi:[1,0]
	v_mov_b32_e32 v15, v2
	v_mov_b32_e32 v11, v3
	v_mov_b32_e32 v9, v5
	v_pk_add_f32 v[2:3], v[14:15], v[10:11]
	v_pk_add_f32 v[4:5], v[6:7], v[8:9]
	s_nop 0
	v_pk_add_f32 v[2:3], v[2:3], v[4:5]
	s_nop 0
	v_add_f32_e32 v2, v2, v3
	v_fmamk_f32 v2, v2, 0x3a000000, v1
	v_rsq_f32_e32 v2, v2
	v_add_u32_e32 v3, s23, v150
	ds_write_b32 v3, v2

; __device__ __forceinline__ unsigned cvt_pk_bf16(float lo, float hi) { f32x2 v = {lo, hi}; bf16x2_t b = __builtin_convertvector(v, bf16x2_t); return __builtin_bit_cast(unsigned, b); }
;     __device__ __forceinline__ void operator()(const f32x4 (&acc)[2][2][4][2], const Unit& u, int wr, int wc, int fr, int fq) const {
;     ...
;         for (int ai = 0; ai < 2; ++ai) {
;             u32x4 xr[4][2];
; #pragma unroll
;             for (int m = 0; m < 4; ++m)
; #pragma unroll
;                 for (int bj = 0; bj < 2; ++bj) xr[m][bj] = *(const u32x4*)(xb + (size_t)(u.pm * BM + ai * HALF + wr * 64 + m * 16 + fr) * 2048 + col0 + bj * HALF);
; #pragma unroll
;             for (int m = 0; m < 4; ++m) { const int row = u.pm * BM + ai * HALF + wr * 64 + m * 16 + fr; const size_t off = (size_t)row * 2048 + col0; float sq = 0.f;
; #pragma unroll
;                 for (int bj = 0; bj < 2; ++bj) { const size_t o2 = off + bj * HALF; const u32x4 xw = xr[m][bj];
;                     f32x4 x0, x1; x0[0] = __uint_as_float(xw.x << 16); x0[1] = __uint_as_float(xw.x & 0xffff0000u); x0[2] = __uint_as_float(xw.y << 16); x0[3] = __uint_as_float(xw.y & 0xffff0000u);
;                     x1[0] = __uint_as_float(xw.z << 16); x1[1] = __uint_as_float(xw.z & 0xffff0000u); x1[2] = __uint_as_float(xw.w << 16); x1[3] = __uint_as_float(xw.w & 0xffff0000u);
;                     x0 = x0 + acc[ai][bj][m][0]; x1 = x1 + acc[ai][bj][m][1];
;                     if (FINAL) { *(f32x4*)(out + o2) = x0; *(f32x4*)(out + o2 + 4) = x1; }
;                     else { u32x4 w; w.x = cvt_pk_bf16(x0[0], x0[1]); w.y = cvt_pk_bf16(x0[2], x0[3]); w.z = cvt_pk_bf16(x1[0], x1[1]); w.w = cvt_pk_bf16(x1[2], x1[3]); *(u32x4*)(xb + o2) = w; }
;                     sq += ((x0[0] * x0[0] + x0[1] * x0[1]) + (x0[2] * x0[2] + x0[3] * x0[3])) + ((x1[0] * x1[0] + x1[1] * x1[1]) + (x1[2] * x1[2] + x1[3] * x1[3])); }
;                 sq += __shfl_xor(sq, 16); sq += __shfl_xor(sq, 32);
;                 if (!FINAL && fq == 0) ssn[(size_t)row * 32 + u.pn * 4 + wc] = sq; }
.LBB0_670:
	v_and_b32_e32 v131, 64, v195
	v_xor_b32_e32 v130, 16, v195
	v_add_u32_e32 v131, 64, v131
	v_cmp_lt_i32_e32 vcc, v130, v131
	v_lshl_or_b32 v176, s34, 8, v200
	v_lshl_add_u32 v178, s58, 8, v161
	v_cndmask_b32_e32 v130, v195, v130, vcc
	v_ashrrev_i32_e32 v177, 31, v176
	v_lshlrev_b32_e32 v203, 2, v130
	v_xor_b32_e32 v130, 32, v195
	v_cmp_lt_i32_e32 vcc, v130, v131
	v_lshlrev_b64 v[204:205], 1, v[176:177]
	v_ashrrev_i32_e32 v179, 31, v178
	v_cndmask_b32_e32 v130, v195, v130, vcc
	v_lshl_add_u64 v[180:181], s[12:13], 0, v[204:205]
	v_lshlrev_b64 v[206:207], 12, v[178:179]
	v_lshlrev_b32_e32 v202, 2, v130
	v_lshl_add_u64 v[130:131], v[180:181], 0, v[206:207]
	global_load_dwordx4 v[162:165], v[130:131], off
	global_load_dwordx4 v[154:157], v[130:131], off offset:256
	v_or_b32_e32 v190, 16, v178
	v_ashrrev_i32_e32 v191, 31, v190
	v_or_b32_e32 v186, 32, v178
	v_lshlrev_b64 v[192:193], 12, v[190:191]
	v_ashrrev_i32_e32 v187, 31, v186
	v_or_b32_e32 v182, 48, v178
	v_lshl_add_u64 v[130:131], v[180:181], 0, v[192:193]
	v_lshlrev_b64 v[188:189], 12, v[186:187]
	v_ashrrev_i32_e32 v183, 31, v182
	global_load_dwordx4 v[150:153], v[130:131], off
	global_load_dwordx4 v[146:149], v[130:131], off offset:256
	v_lshl_add_u64 v[130:131], v[180:181], 0, v[188:189]
	v_lshlrev_b64 v[184:185], 12, v[182:183]
	global_load_dwordx4 v[142:145], v[130:131], off
	global_load_dwordx4 v[138:141], v[130:131], off offset:256
	v_lshl_add_u64 v[130:131], v[180:181], 0, v[184:185]
	global_load_dwordx4 v[134:137], v[130:131], off
	s_nop 0
	global_load_dwordx4 v[130:133], v[130:131], off offset:256
	v_lshl_add_u64 v[206:207], s[12:13], 0, v[206:207]
	v_lshl_add_u64 v[204:205], v[206:207], 0, v[204:205]
	s_lshl_b32 s0, s34, 2
	s_ashr_i32 s1, s0, 31
	s_waitcnt vmcnt(0)
	v_lshlrev_b32_e32 v208, 16, v162
	v_and_b32_e32 v209, 0xffff0000, v162
	v_lshlrev_b32_e32 v162, 16, v163
	v_and_b32_e32 v163, 0xffff0000, v163
	v_lshlrev_b32_e32 v210, 16, v164
	v_and_b32_e32 v211, 0xffff0000, v164
	v_lshlrev_b32_e32 v164, 16, v165
	v_and_b32_e32 v165, 0xffff0000, v165
	v_pk_add_f32 v[128:129], v[128:129], v[162:163]
	v_pk_add_f32 v[126:127], v[126:127], v[208:209]
	v_pk_add_f32 v[162:163], v[124:125], v[164:165]
	v_pk_add_f32 v[164:165], v[122:123], v[210:211]
	v_cvt_pk_bf16_f32 v122, v126, v127
	v_cvt_pk_bf16_f32 v123, v128, v129
	v_cvt_pk_bf16_f32 v124, v164, v165
	v_cvt_pk_bf16_f32 v125, v162, v163
	global_store_dwordx4 v[204:205], v[122:125], off sc1
	s_nop 1
	v_mul_f32_e32 v122, v127, v127
	v_mul_f32_e32 v123, v129, v129
	v_fmac_f32_e32 v122, v126, v126
	v_fmac_f32_e32 v123, v128, v128
	v_add_f32_e32 v122, v122, v123
	v_mul_f32_e32 v123, v165, v165
	v_mul_f32_e32 v124, v163, v163
	v_fmac_f32_e32 v123, v164, v164
	v_fmac_f32_e32 v124, v162, v162
	v_add_f32_e32 v123, v123, v124
	v_add_f32_e32 v162, v122, v123
	v_lshlrev_b32_e32 v122, 16, v154
	v_and_b32_e32 v123, 0xffff0000, v154
	v_lshlrev_b32_e32 v124, 16, v155
	v_and_b32_e32 v125, 0xffff0000, v155
	v_lshlrev_b32_e32 v126, 16, v156
	v_and_b32_e32 v127, 0xffff0000, v156
	v_lshlrev_b32_e32 v128, 16, v157
	v_and_b32_e32 v129, 0xffff0000, v157
	v_pk_add_f32 v[120:121], v[120:121], v[124:125]
	v_pk_add_f32 v[118:119], v[118:119], v[122:123]
	v_pk_add_f32 v[122:123], v[116:117], v[128:129]
	v_pk_add_f32 v[124:125], v[114:115], v[126:127]
	v_cvt_pk_bf16_f32 v114, v118, v119
	v_cvt_pk_bf16_f32 v115, v120, v121
	v_cvt_pk_bf16_f32 v116, v124, v125
	v_cvt_pk_bf16_f32 v117, v122, v123
	global_store_dwordx4 v[204:205], v[114:117], off offset:256 sc1
	s_nop 1
	v_mul_f32_e32 v114, v119, v119
	v_mul_f32_e32 v115, v121, v121
	v_fmac_f32_e32 v114, v118, v118
	v_fmac_f32_e32 v115, v120, v120
	v_add_f32_e32 v114, v114, v115
	v_mul_f32_e32 v115, v125, v125
	v_mul_f32_e32 v116, v123, v123
	v_fmac_f32_e32 v115, v124, v124
	v_fmac_f32_e32 v116, v122, v122
	v_add_f32_e32 v115, v115, v116
	v_add_f32_e32 v114, v114, v115
	v_add_f32_e32 v114, v162, v114
	ds_bpermute_b32 v115, v203, v114
	s_waitcnt lgkmcnt(0)
	v_add_f32_e32 v114, v114, v115
	ds_bpermute_b32 v115, v202, v114
	s_and_saveexec_b64 s[30:31], s[42:43]
	s_mov_b64 s[60:61], s[90:91]
	s_mov_b64 s[62:63], s[88:89]
	s_cbranch_execz .LBB0_672
	s_waitcnt lgkmcnt(0)
	v_add_f32_e32 v116, v114, v115
	v_lshlrev_b64 v[114:115], 7, v[178:179]
	v_lshl_add_u64 v[114:115], s[14:15], 0, v[114:115]
	v_lshl_add_u64 v[114:115], s[0:1], 2, v[114:115]
	s_lshl_b32 s34, s53, 2
	v_lshl_add_u64 v[114:115], v[114:115], 0, s[34:35]
	global_store_dword v[114:115], v116, off sc1
; __device__ __forceinline__ unsigned cvt_pk_bf16(float lo, float hi) { f32x2 v = {lo, hi}; bf16x2_t b = __builtin_convertvector(v, bf16x2_t); return __builtin_bit_cast(unsigned, b); }
;     __device__ __forceinline__ void operator()(const f32x4 (&acc)[2][2][4][2], const Unit& u, int wr, int wc, int fr, int fq) const {
;     ...
;         for (int ai = 0; ai < 2; ++ai) {
;             u32x4 xr[4][2];
; #pragma unroll
;             for (int m = 0; m < 4; ++m)
; #pragma unroll
;                 for (int bj = 0; bj < 2; ++bj) xr[m][bj] = *(const u32x4*)(xb + (size_t)(u.pm * BM + ai * HALF + wr * 64 + m * 16 + fr) * 2048 + col0 + bj * HALF);
; #pragma unroll
;             for (int m = 0; m < 4; ++m) { const int row = u.pm * BM + ai * HALF + wr * 64 + m * 16 + fr; const size_t off = (size_t)row * 2048 + col0; float sq = 0.f;
; #pragma unroll
;                 for (int bj = 0; bj < 2; ++bj) { const size_t o2 = off + bj * HALF; const u32x4 xw = xr[m][bj];
;                     f32x4 x0, x1; x0[0] = __uint_as_float(xw.x << 16); x0[1] = __uint_as_float(xw.x & 0xffff0000u); x0[2] = __uint_as_float(xw.y << 16); x0[3] = __uint_as_float(xw.y & 0xffff0000u);
;                     x1[0] = __uint_as_float(xw.z << 16); x1[1] = __uint_as_float(xw.z & 0xffff0000u); x1[2] = __uint_as_float(xw.w << 16); x1[3] = __uint_as_float(xw.w & 0xffff0000u);
;                     x0 = x0 + acc[ai][bj][m][0]; x1 = x1 + acc[ai][bj][m][1];
;                     if (FINAL) { *(f32x4*)(out + o2) = x0; *(f32x4*)(out + o2 + 4) = x1; }
;                     else { u32x4 w; w.x = cvt_pk_bf16(x0[0], x0[1]); w.y = cvt_pk_bf16(x0[2], x0[3]); w.z = cvt_pk_bf16(x1[0], x1[1]); w.w = cvt_pk_bf16(x1[2], x1[3]); *(u32x4*)(xb + o2) = w; }
;                     sq += ((x0[0] * x0[0] + x0[1] * x0[1]) + (x0[2] * x0[2] + x0[3] * x0[3])) + ((x1[0] * x1[0] + x1[1] * x1[1]) + (x1[2] * x1[2] + x1[3] * x1[3])); }
;                 sq += __shfl_xor(sq, 16); sq += __shfl_xor(sq, 32);
;                 if (!FINAL && fq == 0) ssn[(size_t)row * 32 + u.pn * 4 + wc] = sq; }
.LBB0_672:
	s_or_b64 exec, exec, s[30:31]
	v_lshlrev_b32_e32 v114, 16, v150
	s_waitcnt lgkmcnt(0)
	v_and_b32_e32 v115, 0xffff0000, v150
	v_lshlrev_b32_e32 v116, 16, v151
	v_and_b32_e32 v117, 0xffff0000, v151
	v_lshlrev_b32_e32 v118, 16, v152
	v_and_b32_e32 v119, 0xffff0000, v152
	v_pk_add_f32 v[110:111], v[110:111], v[114:115]
	v_pk_add_f32 v[112:113], v[112:113], v[116:117]
	v_pk_add_f32 v[116:117], v[106:107], v[118:119]
	v_cvt_pk_bf16_f32 v106, v110, v111
	v_mul_f32_e32 v111, v111, v111
	v_lshlrev_b32_e32 v120, 16, v153
	v_and_b32_e32 v121, 0xffff0000, v153
	v_fmac_f32_e32 v111, v110, v110
	v_mul_f32_e32 v110, v113, v113
	v_pk_add_f32 v[114:115], v[108:109], v[120:121]
	v_fmac_f32_e32 v110, v112, v112
	v_cvt_pk_bf16_f32 v107, v112, v113
	v_add_f32_e32 v110, v111, v110
	v_mul_f32_e32 v111, v117, v117
	v_mul_f32_e32 v112, v115, v115
	v_fmac_f32_e32 v111, v116, v116
	v_fmac_f32_e32 v112, v114, v114
	v_add_f32_e32 v111, v111, v112
	v_add_f32_e32 v118, v110, v111
	v_lshlrev_b32_e32 v110, 16, v146
	v_and_b32_e32 v111, 0xffff0000, v146
	v_lshlrev_b32_e32 v112, 16, v147
	v_and_b32_e32 v113, 0xffff0000, v147
	v_cvt_pk_bf16_f32 v109, v114, v115
	v_lshlrev_b32_e32 v114, 16, v148
	v_and_b32_e32 v115, 0xffff0000, v148
	v_pk_add_f32 v[104:105], v[104:105], v[112:113]
	v_pk_add_f32 v[102:103], v[102:103], v[110:111]
	v_cvt_pk_bf16_f32 v108, v116, v117
	v_lshlrev_b32_e32 v116, 16, v149
	v_and_b32_e32 v117, 0xffff0000, v149
	v_pk_add_f32 v[112:113], v[98:99], v[114:115]
	v_mul_f32_e32 v98, v103, v103
	v_mul_f32_e32 v99, v105, v105
	v_pk_add_f32 v[110:111], v[100:101], v[116:117]
	v_fmac_f32_e32 v98, v102, v102
	v_fmac_f32_e32 v99, v104, v104
	v_add_f32_e32 v98, v98, v99
	v_mul_f32_e32 v99, v113, v113
	v_mul_f32_e32 v100, v111, v111
	v_fmac_f32_e32 v99, v112, v112
	v_fmac_f32_e32 v100, v110, v110
	v_add_f32_e32 v99, v99, v100
	v_add_f32_e32 v98, v98, v99
	v_add_f32_e32 v101, v118, v98
	ds_bpermute_b32 v116, v203, v101
	v_lshl_add_u64 v[98:99], s[12:13], 0, v[192:193]
	v_lshl_add_u64 v[114:115], v[176:177], 1, v[98:99]
	v_cvt_pk_bf16_f32 v100, v102, v103
	v_cvt_pk_bf16_f32 v102, v112, v113
	s_waitcnt lgkmcnt(0)
	v_add_f32_e32 v98, v101, v116
	ds_bpermute_b32 v99, v202, v98
	v_cvt_pk_bf16_f32 v101, v104, v105
	v_cvt_pk_bf16_f32 v103, v110, v111
	global_store_dwordx4 v[114:115], v[106:109], off sc1
	global_store_dwordx4 v[114:115], v[100:103], off offset:256 sc1
	s_and_saveexec_b64 s[30:31], s[42:43]
	s_cbranch_execz .LBB0_674
	s_waitcnt lgkmcnt(0)
	v_add_f32_e32 v100, v98, v99
	v_lshlrev_b64 v[98:99], 7, v[190:191]
	v_lshl_add_u64 v[98:99], s[14:15], 0, v[98:99]
	v_lshl_add_u64 v[98:99], s[0:1], 2, v[98:99]
	s_lshl_b32 s34, s53, 2
	v_lshl_add_u64 v[98:99], v[98:99], 0, s[34:35]
	global_store_dword v[98:99], v100, off sc1
.LBB0_674:
	s_or_b64 exec, exec, s[30:31]
	v_lshlrev_b32_e32 v98, 16, v142
	s_waitcnt lgkmcnt(0)
	v_and_b32_e32 v99, 0xffff0000, v142
	v_lshlrev_b32_e32 v100, 16, v143
	v_and_b32_e32 v101, 0xffff0000, v143
	v_lshlrev_b32_e32 v102, 16, v144
	v_and_b32_e32 v103, 0xffff0000, v144
	v_pk_add_f32 v[94:95], v[94:95], v[98:99]
	v_pk_add_f32 v[96:97], v[96:97], v[100:101]
	v_pk_add_f32 v[100:101], v[90:91], v[102:103]
	v_cvt_pk_bf16_f32 v90, v94, v95
	v_mul_f32_e32 v95, v95, v95
	v_lshlrev_b32_e32 v104, 16, v145
	v_and_b32_e32 v105, 0xffff0000, v145
	v_fmac_f32_e32 v95, v94, v94
	v_mul_f32_e32 v94, v97, v97
	v_pk_add_f32 v[98:99], v[92:93], v[104:105]
	v_fmac_f32_e32 v94, v96, v96
	v_cvt_pk_bf16_f32 v91, v96, v97
	v_add_f32_e32 v94, v95, v94
	v_mul_f32_e32 v95, v101, v101
	v_mul_f32_e32 v96, v99, v99
	v_fmac_f32_e32 v95, v100, v100
	v_fmac_f32_e32 v96, v98, v98
	v_add_f32_e32 v95, v95, v96
	v_add_f32_e32 v102, v94, v95
	v_lshlrev_b32_e32 v94, 16, v138
	v_and_b32_e32 v95, 0xffff0000, v138
	v_lshlrev_b32_e32 v96, 16, v139
	v_and_b32_e32 v97, 0xffff0000, v139
	v_cvt_pk_bf16_f32 v93, v98, v99
	v_lshlrev_b32_e32 v98, 16, v140
	v_and_b32_e32 v99, 0xffff0000, v140
	v_pk_add_f32 v[88:89], v[88:89], v[96:97]
	v_pk_add_f32 v[86:87], v[86:87], v[94:95]
	v_cvt_pk_bf16_f32 v92, v100, v101
	v_lshlrev_b32_e32 v100, 16, v141
	v_and_b32_e32 v101, 0xffff0000, v141
	v_pk_add_f32 v[96:97], v[82:83], v[98:99]
	v_mul_f32_e32 v82, v87, v87
	v_mul_f32_e32 v83, v89, v89
	v_pk_add_f32 v[94:95], v[84:85], v[100:101]
	v_fmac_f32_e32 v82, v86, v86
	v_fmac_f32_e32 v83, v88, v88
	v_add_f32_e32 v82, v82, v83
	v_mul_f32_e32 v83, v97, v97
	v_mul_f32_e32 v84, v95, v95
	v_fmac_f32_e32 v83, v96, v96
	v_fmac_f32_e32 v84, v94, v94
	v_add_f32_e32 v83, v83, v84
	v_add_f32_e32 v82, v82, v83
	v_add_f32_e32 v85, v102, v82
	ds_bpermute_b32 v100, v203, v85
	v_lshl_add_u64 v[82:83], s[12:13], 0, v[188:189]
	v_lshl_add_u64 v[98:99], v[176:177], 1, v[82:83]
	v_cvt_pk_bf16_f32 v84, v86, v87
	v_cvt_pk_bf16_f32 v86, v96, v97
	s_waitcnt lgkmcnt(0)
	v_add_f32_e32 v82, v85, v100
	ds_bpermute_b32 v83, v202, v82
	v_cvt_pk_bf16_f32 v85, v88, v89
	v_cvt_pk_bf16_f32 v87, v94, v95
	global_store_dwordx4 v[98:99], v[90:93], off sc1
	global_store_dwordx4 v[98:99], v[84:87], off offset:256 sc1
	s_and_saveexec_b64 s[30:31], s[42:43]
	s_cbranch_execz .LBB0_676
	s_waitcnt lgkmcnt(0)
	v_add_f32_e32 v84, v82, v83
	v_lshlrev_b64 v[82:83], 7, v[186:187]
	v_lshl_add_u64 v[82:83], s[14:15], 0, v[82:83]
	v_lshl_add_u64 v[82:83], s[0:1], 2, v[82:83]
	s_lshl_b32 s34, s53, 2
	v_lshl_add_u64 v[82:83], v[82:83], 0, s[34:35]
	global_store_dword v[82:83], v84, off sc1
; __device__ __forceinline__ unsigned cvt_pk_bf16(float lo, float hi) { f32x2 v = {lo, hi}; bf16x2_t b = __builtin_convertvector(v, bf16x2_t); return __builtin_bit_cast(unsigned, b); }
;     __device__ __forceinline__ void operator()(const f32x4 (&acc)[2][2][4][2], const Unit& u, int wr, int wc, int fr, int fq) const {
;     ...
;         for (int ai = 0; ai < 2; ++ai) {
;             u32x4 xr[4][2];
; #pragma unroll
;             for (int m = 0; m < 4; ++m)
; #pragma unroll
;                 for (int bj = 0; bj < 2; ++bj) xr[m][bj] = *(const u32x4*)(xb + (size_t)(u.pm * BM + ai * HALF + wr * 64 + m * 16 + fr) * 2048 + col0 + bj * HALF);
; #pragma unroll
;             for (int m = 0; m < 4; ++m) { const int row = u.pm * BM + ai * HALF + wr * 64 + m * 16 + fr; const size_t off = (size_t)row * 2048 + col0; float sq = 0.f;
; #pragma unroll
;                 for (int bj = 0; bj < 2; ++bj) { const size_t o2 = off + bj * HALF; const u32x4 xw = xr[m][bj];
;                     f32x4 x0, x1; x0[0] = __uint_as_float(xw.x << 16); x0[1] = __uint_as_float(xw.x & 0xffff0000u); x0[2] = __uint_as_float(xw.y << 16); x0[3] = __uint_as_float(xw.y & 0xffff0000u);
;                     x1[0] = __uint_as_float(xw.z << 16); x1[1] = __uint_as_float(xw.z & 0xffff0000u); x1[2] = __uint_as_float(xw.w << 16); x1[3] = __uint_as_float(xw.w & 0xffff0000u);
;                     x0 = x0 + acc[ai][bj][m][0]; x1 = x1 + acc[ai][bj][m][1];
;                     if (FINAL) { *(f32x4*)(out + o2) = x0; *(f32x4*)(out + o2 + 4) = x1; }
;                     else { u32x4 w; w.x = cvt_pk_bf16(x0[0], x0[1]); w.y = cvt_pk_bf16(x0[2], x0[3]); w.z = cvt_pk_bf16(x1[0], x1[1]); w.w = cvt_pk_bf16(x1[2], x1[3]); *(u32x4*)(xb + o2) = w; }
;                     sq += ((x0[0] * x0[0] + x0[1] * x0[1]) + (x0[2] * x0[2] + x0[3] * x0[3])) + ((x1[0] * x1[0] + x1[1] * x1[1]) + (x1[2] * x1[2] + x1[3] * x1[3])); }
;                 sq += __shfl_xor(sq, 16); sq += __shfl_xor(sq, 32);
;                 if (!FINAL && fq == 0) ssn[(size_t)row * 32 + u.pn * 4 + wc] = sq; }
.LBB0_676:
	s_or_b64 exec, exec, s[30:31]
	v_lshlrev_b32_e32 v82, 16, v134
	s_waitcnt lgkmcnt(0)
	v_and_b32_e32 v83, 0xffff0000, v134
	v_lshlrev_b32_e32 v84, 16, v135
	v_and_b32_e32 v85, 0xffff0000, v135
	v_lshlrev_b32_e32 v86, 16, v136
	v_and_b32_e32 v87, 0xffff0000, v136
	v_pk_add_f32 v[78:79], v[78:79], v[82:83]
	v_pk_add_f32 v[80:81], v[80:81], v[84:85]
	v_pk_add_f32 v[84:85], v[74:75], v[86:87]
	v_cvt_pk_bf16_f32 v74, v78, v79
	v_mul_f32_e32 v79, v79, v79
	v_lshlrev_b32_e32 v88, 16, v137
	v_and_b32_e32 v89, 0xffff0000, v137
	v_fmac_f32_e32 v79, v78, v78
	v_mul_f32_e32 v78, v81, v81
	v_pk_add_f32 v[82:83], v[76:77], v[88:89]
	v_fmac_f32_e32 v78, v80, v80
	v_cvt_pk_bf16_f32 v75, v80, v81
	v_add_f32_e32 v78, v79, v78
	v_mul_f32_e32 v79, v85, v85
	v_mul_f32_e32 v80, v83, v83
	v_fmac_f32_e32 v79, v84, v84
	v_fmac_f32_e32 v80, v82, v82
	v_add_f32_e32 v79, v79, v80
	v_add_f32_e32 v86, v78, v79
	v_lshlrev_b32_e32 v78, 16, v130
	v_and_b32_e32 v79, 0xffff0000, v130
	v_lshlrev_b32_e32 v80, 16, v131
	v_and_b32_e32 v81, 0xffff0000, v131
	v_cvt_pk_bf16_f32 v77, v82, v83
	v_lshlrev_b32_e32 v82, 16, v132
	v_and_b32_e32 v83, 0xffff0000, v132
	v_pk_add_f32 v[72:73], v[72:73], v[80:81]
	v_pk_add_f32 v[70:71], v[70:71], v[78:79]
	v_cvt_pk_bf16_f32 v76, v84, v85
	v_lshlrev_b32_e32 v84, 16, v133
	v_and_b32_e32 v85, 0xffff0000, v133
	v_pk_add_f32 v[80:81], v[66:67], v[82:83]
	v_mul_f32_e32 v66, v71, v71
	v_mul_f32_e32 v67, v73, v73
	v_pk_add_f32 v[78:79], v[68:69], v[84:85]
	v_fmac_f32_e32 v66, v70, v70
	v_fmac_f32_e32 v67, v72, v72
	v_add_f32_e32 v66, v66, v67
	v_mul_f32_e32 v67, v81, v81
	v_mul_f32_e32 v68, v79, v79
	v_fmac_f32_e32 v67, v80, v80
	v_fmac_f32_e32 v68, v78, v78
	v_add_f32_e32 v67, v67, v68
	v_add_f32_e32 v66, v66, v67
	v_add_f32_e32 v69, v86, v66
	ds_bpermute_b32 v84, v203, v69
	v_lshl_add_u64 v[66:67], s[12:13], 0, v[184:185]
	v_lshl_add_u64 v[82:83], v[176:177], 1, v[66:67]
	v_cvt_pk_bf16_f32 v68, v70, v71
	v_cvt_pk_bf16_f32 v70, v80, v81
	s_waitcnt lgkmcnt(0)
	v_add_f32_e32 v66, v69, v84
	ds_bpermute_b32 v67, v202, v66
	v_cvt_pk_bf16_f32 v69, v72, v73
	v_cvt_pk_bf16_f32 v71, v78, v79
	global_store_dwordx4 v[82:83], v[74:77], off sc1
	global_store_dwordx4 v[82:83], v[68:71], off offset:256 sc1
	s_and_saveexec_b64 s[30:31], s[42:43]
	s_cbranch_execz .LBB0_678
	s_waitcnt lgkmcnt(0)
	v_add_f32_e32 v68, v66, v67
	v_lshlrev_b64 v[66:67], 7, v[182:183]
	v_lshl_add_u64 v[66:67], s[14:15], 0, v[66:67]
	v_lshl_add_u64 v[66:67], s[0:1], 2, v[66:67]
	s_lshl_b32 s34, s53, 2
	v_lshl_add_u64 v[66:67], v[66:67], 0, s[34:35]
	global_store_dword v[66:67], v68, off sc1
.LBB0_678:
	s_or_b64 exec, exec, s[30:31]
	v_add_u32_e32 v102, 0x80, v178
	v_ashrrev_i32_e32 v103, 31, v102
	v_lshlrev_b64 v[112:113], 12, v[102:103]
	s_waitcnt lgkmcnt(0)
	v_lshl_add_u64 v[66:67], v[180:181], 0, v[112:113]
	global_load_dwordx4 v[104:107], v[66:67], off
	global_load_dwordx4 v[108:111], v[66:67], off offset:256
	v_add_u32_e32 v98, 0x90, v178
	v_ashrrev_i32_e32 v99, 31, v98
	v_add_u32_e32 v94, 0xa0, v178
	v_lshlrev_b64 v[100:101], 12, v[98:99]
	v_ashrrev_i32_e32 v95, 31, v94
	v_add_u32_e32 v90, 0xb0, v178
	v_lshl_add_u64 v[66:67], v[180:181], 0, v[100:101]
	v_lshlrev_b64 v[96:97], 12, v[94:95]
	v_ashrrev_i32_e32 v91, 31, v90
	global_load_dwordx4 v[86:89], v[66:67], off
	global_load_dwordx4 v[82:85], v[66:67], off offset:256
	v_lshl_add_u64 v[66:67], v[180:181], 0, v[96:97]
	v_lshlrev_b64 v[92:93], 12, v[90:91]
	global_load_dwordx4 v[78:81], v[66:67], off
	global_load_dwordx4 v[74:77], v[66:67], off offset:256
	v_lshl_add_u64 v[66:67], v[180:181], 0, v[92:93]
	global_load_dwordx4 v[70:73], v[66:67], off
	s_nop 0
	global_load_dwordx4 v[66:69], v[66:67], off offset:256
	v_lshl_add_u64 v[112:113], s[12:13], 0, v[112:113]
	v_lshl_add_u64 v[112:113], v[176:177], 1, v[112:113]
	s_waitcnt vmcnt(7)
	v_lshlrev_b32_e32 v114, 16, v104
	v_and_b32_e32 v115, 0xffff0000, v104
	v_lshlrev_b32_e32 v104, 16, v105
	v_and_b32_e32 v105, 0xffff0000, v105
	v_lshlrev_b32_e32 v116, 16, v106
	v_and_b32_e32 v117, 0xffff0000, v106
	v_lshlrev_b32_e32 v106, 16, v107
	v_and_b32_e32 v107, 0xffff0000, v107
	v_pk_add_f32 v[64:65], v[64:65], v[104:105]
	v_pk_add_f32 v[62:63], v[62:63], v[114:115]
	v_pk_add_f32 v[104:105], v[60:61], v[106:107]
	v_pk_add_f32 v[106:107], v[58:59], v[116:117]
	v_cvt_pk_bf16_f32 v58, v62, v63
	v_cvt_pk_bf16_f32 v59, v64, v65
	v_cvt_pk_bf16_f32 v60, v106, v107
	v_cvt_pk_bf16_f32 v61, v104, v105
	global_store_dwordx4 v[112:113], v[58:61], off sc1
	s_nop 1
	v_mul_f32_e32 v58, v63, v63
	v_mul_f32_e32 v59, v65, v65
	v_fmac_f32_e32 v58, v62, v62
	v_fmac_f32_e32 v59, v64, v64
	v_add_f32_e32 v58, v58, v59
	v_mul_f32_e32 v59, v107, v107
	v_mul_f32_e32 v60, v105, v105
	v_fmac_f32_e32 v59, v106, v106
	v_fmac_f32_e32 v60, v104, v104
	v_add_f32_e32 v59, v59, v60
	v_add_f32_e32 v104, v58, v59
	s_waitcnt vmcnt(7)
	v_lshlrev_b32_e32 v58, 16, v108
	v_and_b32_e32 v59, 0xffff0000, v108
	v_lshlrev_b32_e32 v60, 16, v109
	v_and_b32_e32 v61, 0xffff0000, v109
	v_lshlrev_b32_e32 v62, 16, v110
	v_and_b32_e32 v63, 0xffff0000, v110
	v_lshlrev_b32_e32 v64, 16, v111
	v_and_b32_e32 v65, 0xffff0000, v111
	v_pk_add_f32 v[56:57], v[56:57], v[60:61]
	v_pk_add_f32 v[54:55], v[54:55], v[58:59]
	v_pk_add_f32 v[58:59], v[52:53], v[64:65]
	v_pk_add_f32 v[60:61], v[50:51], v[62:63]
	v_cvt_pk_bf16_f32 v50, v54, v55
	v_cvt_pk_bf16_f32 v51, v56, v57
	v_cvt_pk_bf16_f32 v52, v60, v61
	v_cvt_pk_bf16_f32 v53, v58, v59
	global_store_dwordx4 v[112:113], v[50:53], off offset:256 sc1
	s_nop 1
	v_mul_f32_e32 v50, v55, v55
	v_mul_f32_e32 v51, v57, v57
	v_fmac_f32_e32 v50, v54, v54
	v_fmac_f32_e32 v51, v56, v56
	v_add_f32_e32 v50, v50, v51
	v_mul_f32_e32 v51, v61, v61
	v_mul_f32_e32 v52, v59, v59
	v_fmac_f32_e32 v51, v60, v60
	v_fmac_f32_e32 v52, v58, v58
	v_add_f32_e32 v51, v51, v52
	v_add_f32_e32 v50, v50, v51
	v_add_f32_e32 v50, v104, v50
	ds_bpermute_b32 v51, v203, v50
	s_waitcnt lgkmcnt(0)
	v_add_f32_e32 v50, v50, v51
	ds_bpermute_b32 v51, v202, v50
	s_and_saveexec_b64 s[30:31], s[42:43]
	s_cbranch_execz .LBB0_680
	s_waitcnt lgkmcnt(0)
	v_add_f32_e32 v52, v50, v51
	v_lshlrev_b64 v[50:51], 7, v[102:103]
	v_lshl_add_u64 v[50:51], s[14:15], 0, v[50:51]
	v_lshl_add_u64 v[50:51], s[0:1], 2, v[50:51]
	s_lshl_b32 s34, s53, 2
	v_lshl_add_u64 v[50:51], v[50:51], 0, s[34:35]
	global_store_dword v[50:51], v52, off sc1
; __device__ __forceinline__ unsigned cvt_pk_bf16(float lo, float hi) { f32x2 v = {lo, hi}; bf16x2_t b = __builtin_convertvector(v, bf16x2_t); return __builtin_bit_cast(unsigned, b); }
;     __device__ __forceinline__ void operator()(const f32x4 (&acc)[2][2][4][2], const Unit& u, int wr, int wc, int fr, int fq) const {
;     ...
;         for (int ai = 0; ai < 2; ++ai) {
;             u32x4 xr[4][2];
; #pragma unroll
;             for (int m = 0; m < 4; ++m)
; #pragma unroll
;                 for (int bj = 0; bj < 2; ++bj) xr[m][bj] = *(const u32x4*)(xb + (size_t)(u.pm * BM + ai * HALF + wr * 64 + m * 16 + fr) * 2048 + col0 + bj * HALF);
; #pragma unroll
;             for (int m = 0; m < 4; ++m) { const int row = u.pm * BM + ai * HALF + wr * 64 + m * 16 + fr; const size_t off = (size_t)row * 2048 + col0; float sq = 0.f;
; #pragma unroll
;                 for (int bj = 0; bj < 2; ++bj) { const size_t o2 = off + bj * HALF; const u32x4 xw = xr[m][bj];
;                     f32x4 x0, x1; x0[0] = __uint_as_float(xw.x << 16); x0[1] = __uint_as_float(xw.x & 0xffff0000u); x0[2] = __uint_as_float(xw.y << 16); x0[3] = __uint_as_float(xw.y & 0xffff0000u);
;                     x1[0] = __uint_as_float(xw.z << 16); x1[1] = __uint_as_float(xw.z & 0xffff0000u); x1[2] = __uint_as_float(xw.w << 16); x1[3] = __uint_as_float(xw.w & 0xffff0000u);
;                     x0 = x0 + acc[ai][bj][m][0]; x1 = x1 + acc[ai][bj][m][1];
;                     if (FINAL) { *(f32x4*)(out + o2) = x0; *(f32x4*)(out + o2 + 4) = x1; }
;                     else { u32x4 w; w.x = cvt_pk_bf16(x0[0], x0[1]); w.y = cvt_pk_bf16(x0[2], x0[3]); w.z = cvt_pk_bf16(x1[0], x1[1]); w.w = cvt_pk_bf16(x1[2], x1[3]); *(u32x4*)(xb + o2) = w; }
;                     sq += ((x0[0] * x0[0] + x0[1] * x0[1]) + (x0[2] * x0[2] + x0[3] * x0[3])) + ((x1[0] * x1[0] + x1[1] * x1[1]) + (x1[2] * x1[2] + x1[3] * x1[3])); }
;                 sq += __shfl_xor(sq, 16); sq += __shfl_xor(sq, 32);
;                 if (!FINAL && fq == 0) ssn[(size_t)row * 32 + u.pn * 4 + wc] = sq; }
.LBB0_680:
	s_or_b64 exec, exec, s[30:31]
	s_waitcnt vmcnt(7)
	v_lshlrev_b32_e32 v50, 16, v86
	s_waitcnt lgkmcnt(0)
	v_and_b32_e32 v51, 0xffff0000, v86
	v_lshlrev_b32_e32 v52, 16, v87
	v_and_b32_e32 v53, 0xffff0000, v87
	v_lshlrev_b32_e32 v54, 16, v88
	v_and_b32_e32 v55, 0xffff0000, v88
	v_pk_add_f32 v[46:47], v[46:47], v[50:51]
	v_pk_add_f32 v[48:49], v[48:49], v[52:53]
	v_pk_add_f32 v[52:53], v[42:43], v[54:55]
	v_cvt_pk_bf16_f32 v42, v46, v47
	v_mul_f32_e32 v47, v47, v47
	v_lshlrev_b32_e32 v56, 16, v89
	v_and_b32_e32 v57, 0xffff0000, v89
	v_fmac_f32_e32 v47, v46, v46
	v_mul_f32_e32 v46, v49, v49
	v_pk_add_f32 v[50:51], v[44:45], v[56:57]
	v_fmac_f32_e32 v46, v48, v48
	v_cvt_pk_bf16_f32 v43, v48, v49
	v_add_f32_e32 v46, v47, v46
	v_mul_f32_e32 v47, v53, v53
	v_mul_f32_e32 v48, v51, v51
	v_fmac_f32_e32 v47, v52, v52
	v_fmac_f32_e32 v48, v50, v50
	v_add_f32_e32 v47, v47, v48
	v_add_f32_e32 v54, v46, v47
	s_waitcnt vmcnt(6)
	v_lshlrev_b32_e32 v46, 16, v82
	v_and_b32_e32 v47, 0xffff0000, v82
	v_lshlrev_b32_e32 v48, 16, v83
	v_and_b32_e32 v49, 0xffff0000, v83
	v_cvt_pk_bf16_f32 v45, v50, v51
	v_lshlrev_b32_e32 v50, 16, v84
	v_and_b32_e32 v51, 0xffff0000, v84
	v_pk_add_f32 v[40:41], v[40:41], v[48:49]
	v_pk_add_f32 v[38:39], v[38:39], v[46:47]
	v_cvt_pk_bf16_f32 v44, v52, v53
	v_lshlrev_b32_e32 v52, 16, v85
	v_and_b32_e32 v53, 0xffff0000, v85
	v_pk_add_f32 v[48:49], v[34:35], v[50:51]
	v_mul_f32_e32 v34, v39, v39
	v_mul_f32_e32 v35, v41, v41
	v_pk_add_f32 v[46:47], v[36:37], v[52:53]
	v_fmac_f32_e32 v34, v38, v38
	v_fmac_f32_e32 v35, v40, v40
	v_add_f32_e32 v34, v34, v35
	v_mul_f32_e32 v35, v49, v49
	v_mul_f32_e32 v36, v47, v47
	v_fmac_f32_e32 v35, v48, v48
	v_fmac_f32_e32 v36, v46, v46
	v_add_f32_e32 v35, v35, v36
	v_add_f32_e32 v34, v34, v35
	v_add_f32_e32 v37, v54, v34
	ds_bpermute_b32 v52, v203, v37
	v_lshl_add_u64 v[34:35], s[12:13], 0, v[100:101]
	v_lshl_add_u64 v[50:51], v[176:177], 1, v[34:35]
	v_cvt_pk_bf16_f32 v36, v38, v39
	v_cvt_pk_bf16_f32 v38, v48, v49
	s_waitcnt lgkmcnt(0)
	v_add_f32_e32 v34, v37, v52
	ds_bpermute_b32 v35, v202, v34
	v_cvt_pk_bf16_f32 v37, v40, v41
	v_cvt_pk_bf16_f32 v39, v46, v47
	global_store_dwordx4 v[50:51], v[42:45], off sc1
	global_store_dwordx4 v[50:51], v[36:39], off offset:256 sc1
	s_and_saveexec_b64 s[30:31], s[42:43]
	s_cbranch_execz .LBB0_682
	s_waitcnt lgkmcnt(0)
	v_add_f32_e32 v36, v34, v35
	v_lshlrev_b64 v[34:35], 7, v[98:99]
	v_lshl_add_u64 v[34:35], s[14:15], 0, v[34:35]
	v_lshl_add_u64 v[34:35], s[0:1], 2, v[34:35]
	s_lshl_b32 s34, s53, 2
	v_lshl_add_u64 v[34:35], v[34:35], 0, s[34:35]
	global_store_dword v[34:35], v36, off sc1
; __device__ __forceinline__ unsigned cvt_pk_bf16(float lo, float hi) { f32x2 v = {lo, hi}; bf16x2_t b = __builtin_convertvector(v, bf16x2_t); return __builtin_bit_cast(unsigned, b); }
;     __device__ __forceinline__ void operator()(const f32x4 (&acc)[2][2][4][2], const Unit& u, int wr, int wc, int fr, int fq) const {
;     ...
;         for (int ai = 0; ai < 2; ++ai) {
;             u32x4 xr[4][2];
; #pragma unroll
;             for (int m = 0; m < 4; ++m)
; #pragma unroll
;                 for (int bj = 0; bj < 2; ++bj) xr[m][bj] = *(const u32x4*)(xb + (size_t)(u.pm * BM + ai * HALF + wr * 64 + m * 16 + fr) * 2048 + col0 + bj * HALF);
; #pragma unroll
;             for (int m = 0; m < 4; ++m) { const int row = u.pm * BM + ai * HALF + wr * 64 + m * 16 + fr; const size_t off = (size_t)row * 2048 + col0; float sq = 0.f;
; #pragma unroll
;                 for (int bj = 0; bj < 2; ++bj) { const size_t o2 = off + bj * HALF; const u32x4 xw = xr[m][bj];
;                     f32x4 x0, x1; x0[0] = __uint_as_float(xw.x << 16); x0[1] = __uint_as_float(xw.x & 0xffff0000u); x0[2] = __uint_as_float(xw.y << 16); x0[3] = __uint_as_float(xw.y & 0xffff0000u);
;                     x1[0] = __uint_as_float(xw.z << 16); x1[1] = __uint_as_float(xw.z & 0xffff0000u); x1[2] = __uint_as_float(xw.w << 16); x1[3] = __uint_as_float(xw.w & 0xffff0000u);
;                     x0 = x0 + acc[ai][bj][m][0]; x1 = x1 + acc[ai][bj][m][1];
;                     if (FINAL) { *(f32x4*)(out + o2) = x0; *(f32x4*)(out + o2 + 4) = x1; }
;                     else { u32x4 w; w.x = cvt_pk_bf16(x0[0], x0[1]); w.y = cvt_pk_bf16(x0[2], x0[3]); w.z = cvt_pk_bf16(x1[0], x1[1]); w.w = cvt_pk_bf16(x1[2], x1[3]); *(u32x4*)(xb + o2) = w; }
;                     sq += ((x0[0] * x0[0] + x0[1] * x0[1]) + (x0[2] * x0[2] + x0[3] * x0[3])) + ((x1[0] * x1[0] + x1[1] * x1[1]) + (x1[2] * x1[2] + x1[3] * x1[3])); }
;                 sq += __shfl_xor(sq, 16); sq += __shfl_xor(sq, 32);
;                 if (!FINAL && fq == 0) ssn[(size_t)row * 32 + u.pn * 4 + wc] = sq; }
.LBB0_682:
	s_or_b64 exec, exec, s[30:31]
	s_waitcnt vmcnt(7)
	v_lshlrev_b32_e32 v34, 16, v78
	s_waitcnt lgkmcnt(0)
	v_and_b32_e32 v35, 0xffff0000, v78
	v_lshlrev_b32_e32 v36, 16, v79
	v_and_b32_e32 v37, 0xffff0000, v79
	v_lshlrev_b32_e32 v38, 16, v80
	v_and_b32_e32 v39, 0xffff0000, v80
	v_pk_add_f32 v[30:31], v[30:31], v[34:35]
	v_pk_add_f32 v[32:33], v[32:33], v[36:37]
	v_pk_add_f32 v[36:37], v[26:27], v[38:39]
	v_cvt_pk_bf16_f32 v26, v30, v31
	v_mul_f32_e32 v31, v31, v31
	v_lshlrev_b32_e32 v40, 16, v81
	v_and_b32_e32 v41, 0xffff0000, v81
	v_fmac_f32_e32 v31, v30, v30
	v_mul_f32_e32 v30, v33, v33
	v_pk_add_f32 v[34:35], v[28:29], v[40:41]
	v_fmac_f32_e32 v30, v32, v32
	v_cvt_pk_bf16_f32 v27, v32, v33
	v_add_f32_e32 v30, v31, v30
	v_mul_f32_e32 v31, v37, v37
	v_mul_f32_e32 v32, v35, v35
	v_fmac_f32_e32 v31, v36, v36
	v_fmac_f32_e32 v32, v34, v34
	v_add_f32_e32 v31, v31, v32
	v_add_f32_e32 v38, v30, v31
	s_waitcnt vmcnt(6)
	v_lshlrev_b32_e32 v30, 16, v74
	v_and_b32_e32 v31, 0xffff0000, v74
	v_lshlrev_b32_e32 v32, 16, v75
	v_and_b32_e32 v33, 0xffff0000, v75
	v_cvt_pk_bf16_f32 v29, v34, v35
	v_lshlrev_b32_e32 v34, 16, v76
	v_and_b32_e32 v35, 0xffff0000, v76
	v_pk_add_f32 v[24:25], v[24:25], v[32:33]
	v_pk_add_f32 v[22:23], v[22:23], v[30:31]
	v_cvt_pk_bf16_f32 v28, v36, v37
	v_lshlrev_b32_e32 v36, 16, v77
	v_and_b32_e32 v37, 0xffff0000, v77
	v_pk_add_f32 v[32:33], v[18:19], v[34:35]
	v_mul_f32_e32 v18, v23, v23
	v_mul_f32_e32 v19, v25, v25
	v_pk_add_f32 v[30:31], v[20:21], v[36:37]
	v_fmac_f32_e32 v18, v22, v22
	v_fmac_f32_e32 v19, v24, v24
	v_add_f32_e32 v18, v18, v19
	v_mul_f32_e32 v19, v33, v33
	v_mul_f32_e32 v20, v31, v31
	v_fmac_f32_e32 v19, v32, v32
	v_fmac_f32_e32 v20, v30, v30
	v_add_f32_e32 v19, v19, v20
	v_add_f32_e32 v18, v18, v19
	v_add_f32_e32 v21, v38, v18
	ds_bpermute_b32 v36, v203, v21
	v_lshl_add_u64 v[18:19], s[12:13], 0, v[96:97]
	v_lshl_add_u64 v[34:35], v[176:177], 1, v[18:19]
	v_cvt_pk_bf16_f32 v20, v22, v23
	v_cvt_pk_bf16_f32 v22, v32, v33
	s_waitcnt lgkmcnt(0)
	v_add_f32_e32 v18, v21, v36
	ds_bpermute_b32 v19, v202, v18
	v_cvt_pk_bf16_f32 v21, v24, v25
	v_cvt_pk_bf16_f32 v23, v30, v31
	global_store_dwordx4 v[34:35], v[26:29], off sc1
	global_store_dwordx4 v[34:35], v[20:23], off offset:256 sc1
	s_and_saveexec_b64 s[30:31], s[42:43]
	s_cbranch_execz .LBB0_684
	s_waitcnt lgkmcnt(0)
	v_add_f32_e32 v20, v18, v19
	v_lshlrev_b64 v[18:19], 7, v[94:95]
	v_lshl_add_u64 v[18:19], s[14:15], 0, v[18:19]
	v_lshl_add_u64 v[18:19], s[0:1], 2, v[18:19]
	s_lshl_b32 s34, s53, 2
	v_lshl_add_u64 v[18:19], v[18:19], 0, s[34:35]
	global_store_dword v[18:19], v20, off sc1
.LBB0_684:
	s_or_b64 exec, exec, s[30:31]
	s_waitcnt vmcnt(7)
	v_lshlrev_b32_e32 v18, 16, v70
	s_waitcnt lgkmcnt(0)
	v_and_b32_e32 v19, 0xffff0000, v70
	v_lshlrev_b32_e32 v20, 16, v71
	v_and_b32_e32 v21, 0xffff0000, v71
	v_lshlrev_b32_e32 v22, 16, v72
	v_and_b32_e32 v23, 0xffff0000, v72
	v_pk_add_f32 v[14:15], v[14:15], v[18:19]
	v_pk_add_f32 v[16:17], v[16:17], v[20:21]
	v_pk_add_f32 v[20:21], v[10:11], v[22:23]
	v_cvt_pk_bf16_f32 v10, v14, v15
	v_mul_f32_e32 v15, v15, v15
	v_lshlrev_b32_e32 v24, 16, v73
	v_and_b32_e32 v25, 0xffff0000, v73
	v_fmac_f32_e32 v15, v14, v14
	v_mul_f32_e32 v14, v17, v17
	v_pk_add_f32 v[18:19], v[12:13], v[24:25]
	v_fmac_f32_e32 v14, v16, v16
	v_cvt_pk_bf16_f32 v11, v16, v17
	v_add_f32_e32 v14, v15, v14
	v_mul_f32_e32 v15, v21, v21
	v_mul_f32_e32 v16, v19, v19
	v_fmac_f32_e32 v15, v20, v20
	v_fmac_f32_e32 v16, v18, v18
	v_add_f32_e32 v15, v15, v16
	v_add_f32_e32 v22, v14, v15
	s_waitcnt vmcnt(6)
	v_lshlrev_b32_e32 v14, 16, v66
	v_and_b32_e32 v15, 0xffff0000, v66
	v_lshlrev_b32_e32 v16, 16, v67
	v_and_b32_e32 v17, 0xffff0000, v67
	v_cvt_pk_bf16_f32 v13, v18, v19
	v_lshlrev_b32_e32 v18, 16, v68
	v_and_b32_e32 v19, 0xffff0000, v68
	v_pk_add_f32 v[8:9], v[8:9], v[16:17]
	v_pk_add_f32 v[6:7], v[6:7], v[14:15]
	v_cvt_pk_bf16_f32 v12, v20, v21
	v_lshlrev_b32_e32 v20, 16, v69
	v_and_b32_e32 v21, 0xffff0000, v69
	v_pk_add_f32 v[16:17], v[2:3], v[18:19]
	v_mul_f32_e32 v2, v7, v7
	v_mul_f32_e32 v3, v9, v9
	v_pk_add_f32 v[14:15], v[4:5], v[20:21]
	v_fmac_f32_e32 v2, v6, v6
	v_fmac_f32_e32 v3, v8, v8
	v_add_f32_e32 v2, v2, v3
	v_mul_f32_e32 v3, v17, v17
	v_mul_f32_e32 v4, v15, v15
	v_fmac_f32_e32 v3, v16, v16
	v_fmac_f32_e32 v4, v14, v14
	v_add_f32_e32 v3, v3, v4
	v_add_f32_e32 v2, v2, v3
	v_add_f32_e32 v5, v22, v2
	ds_bpermute_b32 v20, v203, v5
	v_lshl_add_u64 v[2:3], s[12:13], 0, v[92:93]
	v_lshl_add_u64 v[18:19], v[176:177], 1, v[2:3]
	v_cvt_pk_bf16_f32 v4, v6, v7
	v_cvt_pk_bf16_f32 v6, v16, v17
	s_waitcnt lgkmcnt(0)
	v_add_f32_e32 v2, v5, v20
	ds_bpermute_b32 v3, v202, v2
	v_cvt_pk_bf16_f32 v5, v8, v9
	v_cvt_pk_bf16_f32 v7, v14, v15
	global_store_dwordx4 v[18:19], v[10:13], off sc1
	global_store_dwordx4 v[18:19], v[4:7], off offset:256 sc1
	s_and_saveexec_b64 s[30:31], s[42:43]
	s_cbranch_execz .LBB0_686
	s_waitcnt lgkmcnt(0)
	v_add_f32_e32 v4, v2, v3
	v_lshlrev_b64 v[2:3], 7, v[90:91]
	v_lshl_add_u64 v[2:3], s[14:15], 0, v[2:3]
	v_lshl_add_u64 v[2:3], s[0:1], 2, v[2:3]
	s_lshl_b32 s34, s53, 2
	v_lshl_add_u64 v[2:3], v[2:3], 0, s[34:35]
	global_store_dword v[2:3], v4, off sc1

; __device__ __forceinline__ unsigned cvt_pk_bf16(float lo, float hi) { f32x2 v = {lo, hi}; bf16x2_t b = __builtin_convertvector(v, bf16x2_t); return __builtin_bit_cast(unsigned, b); }
;     __device__ __forceinline__ void operator()(const f32x4 (&acc)[2][2][4][2], const Unit& u, int wr, int wc, int fr, int fq, int buf) const {
;     ...
;             for (int m = 0; m < 4; ++m) { const int row = row0 + ai * HALF + m * 16;
;                 const float sc = rtab[buf * BM + wr * 64 + fr + ai * HALF + m * 16];
;                 int prow = row;
;                 if (PERMROWS && u.pn >= 24) { const int sh = 2 * ((u.pn - 24) / 6), t = row & 8191; prow = (row & ~8191) + ((t & ((1 << sh) - 1)) << (13 - sh)) + (t >> sh); }
;                 bf16_t* rowp = BLK ? O + ((size_t)(2 * u.pn) * ldc + prow) * 128 + wc * 32 + 8 * fq : O + (size_t)row * ldc + col0;
; #pragma unroll
;                 for (int bj = 0; bj < 2; ++bj) { f32x4 v0 = acc[ai][bj][m][0] * sc, v1 = acc[ai][bj][m][1] * sc;
;                     if (ACT == 1) {
; #pragma unroll
;                         for (int e = 0; e < 4; ++e) { float a = v0[e] > 0.f ? v0[e] : 0.f; v0[e] = a * a; float b = v1[e] > 0.f ? v1[e] : 0.f; v1[e] = b * b; } }
;                     u32x4 w; w.x = cvt_pk_bf16(v0[0], v0[1]); w.y = cvt_pk_bf16(v0[2], v0[3]); w.z = cvt_pk_bf16(v1[0], v1[1]); w.w = cvt_pk_bf16(v1[2], v1[3]);
;                     *(u32x4*)(rowp + (BLK ? (size_t)bj * ldc * 128 : (size_t)bj * HALF)) = w; } }
.LBB0_765:
	s_lshl_b32 s0, s55, 10
	s_and_b32 s0, s0, 0x400
	v_add_u32_e32 v151, s0, v147
	ds_read2_b32 v[152:153], v151 offset1:16
	v_lshl_add_u32 v142, s59, 8, v145
	v_lshl_or_b32 v140, s58, 8, v149
	v_ashrrev_i32_e32 v143, 31, v142
	v_ashrrev_i32_e32 v141, 31, v140
	v_lshlrev_b64 v[154:155], 14, v[142:143]
	s_waitcnt lgkmcnt(0)
	v_pk_mul_f32 v[122:123], v[122:123], v[152:153] op_sel_hi:[1,0]
	v_lshl_add_u64 v[154:155], s[14:15], 0, v[154:155]
	v_lshlrev_b64 v[156:157], 1, v[140:141]
	v_pk_mul_f32 v[128:129], v[128:129], v[152:153] op_sel_hi:[1,0]
	v_max_f32_e32 v123, 0, v123
	v_max_f32_e32 v122, 0, v122
	v_lshl_add_u64 v[140:141], v[154:155], 0, v[156:157]
	v_pk_mul_f32 v[126:127], v[126:127], v[152:153] op_sel_hi:[1,0]
	v_pk_mul_f32 v[124:125], v[124:125], v[152:153] op_sel_hi:[1,0]
	v_pk_mul_f32 v[154:155], v[122:123], v[122:123]
	v_max_f32_e32 v123, 0, v129
	v_max_f32_e32 v122, 0, v128
	v_max_f32_e32 v127, 0, v127
	v_max_f32_e32 v126, 0, v126
	v_pk_mul_f32 v[128:129], v[122:123], v[122:123]
	v_max_f32_e32 v123, 0, v125
	v_max_f32_e32 v122, 0, v124
	v_pk_mul_f32 v[126:127], v[126:127], v[126:127]
	v_pk_mul_f32 v[162:163], v[122:123], v[122:123]
	v_pk_mul_f32 v[114:115], v[114:115], v[152:153] op_sel_hi:[1,0]
	v_cvt_pk_bf16_f32 v122, v126, v127
	v_cvt_pk_bf16_f32 v123, v128, v129
	v_cvt_pk_bf16_f32 v124, v154, v155
	v_cvt_pk_bf16_f32 v125, v162, v163
	v_pk_mul_f32 v[120:121], v[120:121], v[152:153] op_sel_hi:[1,0]
	v_max_f32_e32 v115, 0, v115
	v_max_f32_e32 v114, 0, v114
	global_store_dwordx4 v[140:141], v[122:125], off sc1
	v_pk_mul_f32 v[118:119], v[118:119], v[152:153] op_sel_hi:[1,0]
	v_pk_mul_f32 v[116:117], v[116:117], v[152:153] op_sel_hi:[1,0]
	v_pk_mul_f32 v[122:123], v[114:115], v[114:115]
	v_max_f32_e32 v115, 0, v121
	v_max_f32_e32 v114, 0, v120
	v_max_f32_e32 v119, 0, v119
	v_max_f32_e32 v118, 0, v118
	v_pk_mul_f32 v[120:121], v[114:115], v[114:115]
	v_max_f32_e32 v115, 0, v117
	v_max_f32_e32 v114, 0, v116
	v_pk_mul_f32 v[118:119], v[118:119], v[118:119]
	v_pk_mul_f32 v[124:125], v[114:115], v[114:115]
	v_cvt_pk_bf16_f32 v114, v118, v119
	v_cvt_pk_bf16_f32 v115, v120, v121
	v_cvt_pk_bf16_f32 v116, v122, v123
	v_cvt_pk_bf16_f32 v117, v124, v125
	global_store_dwordx4 v[140:141], v[114:117], off offset:256 sc1
	s_mov_b64 s[0:1], 0x200000
	s_nop 0
	v_mov_b32_e32 v116, v153
	v_pk_mul_f32 v[106:107], v[106:107], v[116:117] op_sel_hi:[1,0]
	v_or_b32_e32 v114, 16, v142
	v_pk_mul_f32 v[112:113], v[112:113], v[116:117] op_sel_hi:[1,0]
	v_max_f32_e32 v107, 0, v107
	v_max_f32_e32 v106, 0, v106
	v_ashrrev_i32_e32 v115, 31, v114
	v_pk_mul_f32 v[110:111], v[110:111], v[116:117] op_sel_hi:[1,0]
	v_pk_mul_f32 v[108:109], v[108:109], v[116:117] op_sel_hi:[1,0]
	v_pk_mul_f32 v[118:119], v[106:107], v[106:107]
	v_max_f32_e32 v107, 0, v113
	v_max_f32_e32 v106, 0, v112
	v_lshlrev_b64 v[114:115], 14, v[114:115]
	v_max_f32_e32 v111, 0, v111
	v_max_f32_e32 v110, 0, v110
	v_pk_mul_f32 v[112:113], v[106:107], v[106:107]
	v_max_f32_e32 v107, 0, v109
	v_max_f32_e32 v106, 0, v108
	v_lshl_add_u64 v[114:115], s[14:15], 0, v[114:115]
	v_pk_mul_f32 v[110:111], v[110:111], v[110:111]
	v_pk_mul_f32 v[120:121], v[106:107], v[106:107]
	v_pk_mul_f32 v[98:99], v[98:99], v[116:117] op_sel_hi:[1,0]
	v_lshl_add_u64 v[114:115], v[114:115], 0, v[156:157]
	v_cvt_pk_bf16_f32 v106, v110, v111
	v_cvt_pk_bf16_f32 v107, v112, v113
	v_cvt_pk_bf16_f32 v108, v118, v119
	v_cvt_pk_bf16_f32 v109, v120, v121
	v_pk_mul_f32 v[104:105], v[104:105], v[116:117] op_sel_hi:[1,0]
	v_max_f32_e32 v99, 0, v99
	v_max_f32_e32 v98, 0, v98
	global_store_dwordx4 v[114:115], v[106:109], off sc1
	v_pk_mul_f32 v[102:103], v[102:103], v[116:117] op_sel_hi:[1,0]
	v_pk_mul_f32 v[100:101], v[100:101], v[116:117] op_sel_hi:[1,0]
	v_pk_mul_f32 v[106:107], v[98:99], v[98:99]
	v_max_f32_e32 v99, 0, v105
	v_max_f32_e32 v98, 0, v104
	v_max_f32_e32 v103, 0, v103
	v_max_f32_e32 v102, 0, v102
	v_pk_mul_f32 v[104:105], v[98:99], v[98:99]
	v_max_f32_e32 v99, 0, v101
	v_max_f32_e32 v98, 0, v100
	v_pk_mul_f32 v[102:103], v[102:103], v[102:103]
	v_pk_mul_f32 v[108:109], v[98:99], v[98:99]
	v_cvt_pk_bf16_f32 v98, v102, v103
	v_cvt_pk_bf16_f32 v99, v104, v105
	v_cvt_pk_bf16_f32 v100, v106, v107
	v_cvt_pk_bf16_f32 v101, v108, v109
	global_store_dwordx4 v[114:115], v[98:101], off offset:256 sc1
	ds_read2_b32 v[100:101], v151 offset0:32 offset1:48
	s_waitcnt lgkmcnt(0)
; __device__ __forceinline__ unsigned cvt_pk_bf16(float lo, float hi) { f32x2 v = {lo, hi}; bf16x2_t b = __builtin_convertvector(v, bf16x2_t); return __builtin_bit_cast(unsigned, b); }
;     __device__ __forceinline__ void operator()(const f32x4 (&acc)[2][2][4][2], const Unit& u, int wr, int wc, int fr, int fq, int buf) const {
;     ...
;             for (int m = 0; m < 4; ++m) { const int row = row0 + ai * HALF + m * 16;
;                 const float sc = rtab[buf * BM + wr * 64 + fr + ai * HALF + m * 16];
;                 int prow = row;
;                 if (PERMROWS && u.pn >= 24) { const int sh = 2 * ((u.pn - 24) / 6), t = row & 8191; prow = (row & ~8191) + ((t & ((1 << sh) - 1)) << (13 - sh)) + (t >> sh); }
;                 bf16_t* rowp = BLK ? O + ((size_t)(2 * u.pn) * ldc + prow) * 128 + wc * 32 + 8 * fq : O + (size_t)row * ldc + col0;
; #pragma unroll
;                 for (int bj = 0; bj < 2; ++bj) { f32x4 v0 = acc[ai][bj][m][0] * sc, v1 = acc[ai][bj][m][1] * sc;
;                     if (ACT == 1) {
; #pragma unroll
;                         for (int e = 0; e < 4; ++e) { float a = v0[e] > 0.f ? v0[e] : 0.f; v0[e] = a * a; float b = v1[e] > 0.f ? v1[e] : 0.f; v1[e] = b * b; } }
;                     u32x4 w; w.x = cvt_pk_bf16(v0[0], v0[1]); w.y = cvt_pk_bf16(v0[2], v0[3]); w.z = cvt_pk_bf16(v1[0], v1[1]); w.w = cvt_pk_bf16(v1[2], v1[3]);
;                     *(u32x4*)(rowp + (BLK ? (size_t)bj * ldc * 128 : (size_t)bj * HALF)) = w; } }
	v_pk_mul_f32 v[90:91], v[90:91], v[100:101] op_sel_hi:[1,0]
	v_or_b32_e32 v98, 32, v142
	v_pk_mul_f32 v[96:97], v[96:97], v[100:101] op_sel_hi:[1,0]
	v_max_f32_e32 v91, 0, v91
	v_max_f32_e32 v90, 0, v90
	v_ashrrev_i32_e32 v99, 31, v98
	v_pk_mul_f32 v[94:95], v[94:95], v[100:101] op_sel_hi:[1,0]
	v_pk_mul_f32 v[92:93], v[92:93], v[100:101] op_sel_hi:[1,0]
	v_pk_mul_f32 v[102:103], v[90:91], v[90:91]
	v_max_f32_e32 v91, 0, v97
	v_max_f32_e32 v90, 0, v96
	v_lshlrev_b64 v[98:99], 14, v[98:99]
	v_max_f32_e32 v95, 0, v95
	v_max_f32_e32 v94, 0, v94
	v_pk_mul_f32 v[96:97], v[90:91], v[90:91]
	v_max_f32_e32 v91, 0, v93
	v_max_f32_e32 v90, 0, v92
	v_lshl_add_u64 v[98:99], s[14:15], 0, v[98:99]
	v_pk_mul_f32 v[94:95], v[94:95], v[94:95]
	v_pk_mul_f32 v[104:105], v[90:91], v[90:91]
	v_pk_mul_f32 v[82:83], v[82:83], v[100:101] op_sel_hi:[1,0]
	v_lshl_add_u64 v[98:99], v[98:99], 0, v[156:157]
	v_cvt_pk_bf16_f32 v90, v94, v95
	v_cvt_pk_bf16_f32 v91, v96, v97
	v_cvt_pk_bf16_f32 v92, v102, v103
	v_cvt_pk_bf16_f32 v93, v104, v105
	v_pk_mul_f32 v[88:89], v[88:89], v[100:101] op_sel_hi:[1,0]
	v_max_f32_e32 v83, 0, v83
	v_max_f32_e32 v82, 0, v82
	global_store_dwordx4 v[98:99], v[90:93], off sc1
	v_pk_mul_f32 v[86:87], v[86:87], v[100:101] op_sel_hi:[1,0]
	v_pk_mul_f32 v[84:85], v[84:85], v[100:101] op_sel_hi:[1,0]
	v_pk_mul_f32 v[90:91], v[82:83], v[82:83]
	v_max_f32_e32 v83, 0, v89
	v_max_f32_e32 v82, 0, v88
	v_max_f32_e32 v87, 0, v87
	v_max_f32_e32 v86, 0, v86
	v_pk_mul_f32 v[88:89], v[82:83], v[82:83]
	v_max_f32_e32 v83, 0, v85
	v_max_f32_e32 v82, 0, v84
	v_pk_mul_f32 v[86:87], v[86:87], v[86:87]
	v_pk_mul_f32 v[92:93], v[82:83], v[82:83]
	v_cvt_pk_bf16_f32 v82, v86, v87
	v_cvt_pk_bf16_f32 v83, v88, v89
	v_cvt_pk_bf16_f32 v84, v90, v91
	v_cvt_pk_bf16_f32 v85, v92, v93
	global_store_dwordx4 v[98:99], v[82:85], off offset:256 sc1
	s_nop 1
	v_mov_b32_e32 v84, v101
	v_pk_mul_f32 v[74:75], v[74:75], v[84:85] op_sel_hi:[1,0]
	v_or_b32_e32 v82, 48, v142
	v_pk_mul_f32 v[80:81], v[80:81], v[84:85] op_sel_hi:[1,0]
	v_max_f32_e32 v75, 0, v75
	v_max_f32_e32 v74, 0, v74
	v_ashrrev_i32_e32 v83, 31, v82
	v_pk_mul_f32 v[78:79], v[78:79], v[84:85] op_sel_hi:[1,0]
	v_pk_mul_f32 v[76:77], v[76:77], v[84:85] op_sel_hi:[1,0]
	v_pk_mul_f32 v[86:87], v[74:75], v[74:75]
	v_max_f32_e32 v75, 0, v81
	v_max_f32_e32 v74, 0, v80
	v_lshlrev_b64 v[82:83], 14, v[82:83]
	v_max_f32_e32 v79, 0, v79
	v_max_f32_e32 v78, 0, v78
	v_pk_mul_f32 v[80:81], v[74:75], v[74:75]
	v_max_f32_e32 v75, 0, v77
	v_max_f32_e32 v74, 0, v76
	v_lshl_add_u64 v[82:83], s[14:15], 0, v[82:83]
	v_pk_mul_f32 v[78:79], v[78:79], v[78:79]
	v_pk_mul_f32 v[88:89], v[74:75], v[74:75]
	v_pk_mul_f32 v[66:67], v[66:67], v[84:85] op_sel_hi:[1,0]
	v_lshl_add_u64 v[82:83], v[82:83], 0, v[156:157]
	v_cvt_pk_bf16_f32 v74, v78, v79
	v_cvt_pk_bf16_f32 v75, v80, v81
	v_cvt_pk_bf16_f32 v76, v86, v87
	v_cvt_pk_bf16_f32 v77, v88, v89
	v_pk_mul_f32 v[72:73], v[72:73], v[84:85] op_sel_hi:[1,0]
	v_pk_mul_f32 v[70:71], v[70:71], v[84:85] op_sel_hi:[1,0]
	v_max_f32_e32 v67, 0, v67
	v_max_f32_e32 v66, 0, v66
	global_store_dwordx4 v[82:83], v[74:77], off sc1
	v_pk_mul_f32 v[68:69], v[68:69], v[84:85] op_sel_hi:[1,0]
	v_max_f32_e32 v71, 0, v71
	v_max_f32_e32 v70, 0, v70
	v_pk_mul_f32 v[74:75], v[66:67], v[66:67]
	v_max_f32_e32 v67, 0, v73
	v_max_f32_e32 v66, 0, v72
	v_pk_mul_f32 v[70:71], v[70:71], v[70:71]
	v_pk_mul_f32 v[72:73], v[66:67], v[66:67]
	v_max_f32_e32 v67, 0, v69
	v_max_f32_e32 v66, 0, v68
	v_pk_mul_f32 v[76:77], v[66:67], v[66:67]
	v_cvt_pk_bf16_f32 v66, v70, v71
	ds_read2_b32 v[70:71], v151 offset0:128 offset1:144
	v_cvt_pk_bf16_f32 v67, v72, v73
	v_cvt_pk_bf16_f32 v68, v74, v75
	v_cvt_pk_bf16_f32 v69, v76, v77
	global_store_dwordx4 v[82:83], v[66:69], off offset:256 sc1
	s_waitcnt lgkmcnt(0)
	v_pk_mul_f32 v[58:59], v[58:59], v[70:71] op_sel_hi:[1,0]
	v_pk_mul_f32 v[64:65], v[64:65], v[70:71] op_sel_hi:[1,0]
	v_pk_mul_f32 v[62:63], v[62:63], v[70:71] op_sel_hi:[1,0]
	v_max_f32_e32 v59, 0, v59
	v_max_f32_e32 v58, 0, v58
	v_pk_mul_f32 v[60:61], v[60:61], v[70:71] op_sel_hi:[1,0]
	v_max_f32_e32 v63, 0, v63
	v_max_f32_e32 v62, 0, v62
	v_pk_mul_f32 v[68:69], v[58:59], v[58:59]
	v_max_f32_e32 v59, 0, v65
	v_max_f32_e32 v58, 0, v64
	v_lshl_add_u64 v[66:67], v[140:141], 0, s[0:1]
	v_pk_mul_f32 v[62:63], v[62:63], v[62:63]
	v_pk_mul_f32 v[64:65], v[58:59], v[58:59]
	v_max_f32_e32 v59, 0, v61
	v_max_f32_e32 v58, 0, v60
	s_mov_b32 s0, 0x200000
	v_pk_mul_f32 v[72:73], v[58:59], v[58:59]
	v_cvt_pk_bf16_f32 v58, v62, v63
	v_add_co_u32_e32 v62, vcc, s0, v140
	v_pk_mul_f32 v[50:51], v[50:51], v[70:71] op_sel_hi:[1,0]
	v_cvt_pk_bf16_f32 v59, v64, v65
	v_cvt_pk_bf16_f32 v60, v68, v69
	v_cvt_pk_bf16_f32 v61, v72, v73
	v_addc_co_u32_e32 v63, vcc, 0, v141, vcc
	v_pk_mul_f32 v[56:57], v[56:57], v[70:71] op_sel_hi:[1,0]
	v_max_f32_e32 v51, 0, v51
	v_max_f32_e32 v50, 0, v50
	global_store_dwordx4 v[62:63], v[58:61], off sc1
	v_pk_mul_f32 v[54:55], v[54:55], v[70:71] op_sel_hi:[1,0]
	v_pk_mul_f32 v[52:53], v[52:53], v[70:71] op_sel_hi:[1,0]
	v_pk_mul_f32 v[58:59], v[50:51], v[50:51]
	v_max_f32_e32 v51, 0, v57
	v_max_f32_e32 v50, 0, v56
	v_max_f32_e32 v55, 0, v55
	v_max_f32_e32 v54, 0, v54
	v_pk_mul_f32 v[56:57], v[50:51], v[50:51]
	v_max_f32_e32 v51, 0, v53
	v_max_f32_e32 v50, 0, v52
	v_pk_mul_f32 v[54:55], v[54:55], v[54:55]
	v_pk_mul_f32 v[60:61], v[50:51], v[50:51]
	v_cvt_pk_bf16_f32 v50, v54, v55
	v_cvt_pk_bf16_f32 v51, v56, v57
	v_cvt_pk_bf16_f32 v52, v58, v59
	v_cvt_pk_bf16_f32 v53, v60, v61
	global_store_dwordx4 v[66:67], v[50:53], off offset:256 sc1
	s_mov_b64 s[0:1], 0x240000
	s_nop 0
	v_mov_b32_e32 v52, v71
	v_pk_mul_f32 v[42:43], v[42:43], v[52:53] op_sel_hi:[1,0]
; __device__ __forceinline__ unsigned cvt_pk_bf16(float lo, float hi) { f32x2 v = {lo, hi}; bf16x2_t b = __builtin_convertvector(v, bf16x2_t); return __builtin_bit_cast(unsigned, b); }
;     __device__ __forceinline__ void operator()(const f32x4 (&acc)[2][2][4][2], const Unit& u, int wr, int wc, int fr, int fq, int buf) const {
;     ...
;             for (int m = 0; m < 4; ++m) { const int row = row0 + ai * HALF + m * 16;
;                 const float sc = rtab[buf * BM + wr * 64 + fr + ai * HALF + m * 16];
;                 int prow = row;
;                 if (PERMROWS && u.pn >= 24) { const int sh = 2 * ((u.pn - 24) / 6), t = row & 8191; prow = (row & ~8191) + ((t & ((1 << sh) - 1)) << (13 - sh)) + (t >> sh); }
;                 bf16_t* rowp = BLK ? O + ((size_t)(2 * u.pn) * ldc + prow) * 128 + wc * 32 + 8 * fq : O + (size_t)row * ldc + col0;
; #pragma unroll
;                 for (int bj = 0; bj < 2; ++bj) { f32x4 v0 = acc[ai][bj][m][0] * sc, v1 = acc[ai][bj][m][1] * sc;
;                     if (ACT == 1) {
; #pragma unroll
;                         for (int e = 0; e < 4; ++e) { float a = v0[e] > 0.f ? v0[e] : 0.f; v0[e] = a * a; float b = v1[e] > 0.f ? v1[e] : 0.f; v1[e] = b * b; } }
;                     u32x4 w; w.x = cvt_pk_bf16(v0[0], v0[1]); w.y = cvt_pk_bf16(v0[2], v0[3]); w.z = cvt_pk_bf16(v1[0], v1[1]); w.w = cvt_pk_bf16(v1[2], v1[3]);
;                     *(u32x4*)(rowp + (BLK ? (size_t)bj * ldc * 128 : (size_t)bj * HALF)) = w; } }
	v_pk_mul_f32 v[48:49], v[48:49], v[52:53] op_sel_hi:[1,0]
	v_pk_mul_f32 v[46:47], v[46:47], v[52:53] op_sel_hi:[1,0]
	v_max_f32_e32 v43, 0, v43
	v_max_f32_e32 v42, 0, v42
	v_pk_mul_f32 v[44:45], v[44:45], v[52:53] op_sel_hi:[1,0]
	v_max_f32_e32 v47, 0, v47
	v_max_f32_e32 v46, 0, v46
	v_pk_mul_f32 v[54:55], v[42:43], v[42:43]
	v_max_f32_e32 v43, 0, v49
	v_max_f32_e32 v42, 0, v48
	v_lshl_add_u64 v[50:51], v[140:141], 0, s[0:1]
	v_pk_mul_f32 v[46:47], v[46:47], v[46:47]
	v_pk_mul_f32 v[48:49], v[42:43], v[42:43]
	v_max_f32_e32 v43, 0, v45
	v_max_f32_e32 v42, 0, v44
	s_mov_b32 s0, 0x240000
	v_pk_mul_f32 v[56:57], v[42:43], v[42:43]
	v_cvt_pk_bf16_f32 v42, v46, v47
	v_add_co_u32_e32 v46, vcc, s0, v140
	v_pk_mul_f32 v[34:35], v[34:35], v[52:53] op_sel_hi:[1,0]
	v_cvt_pk_bf16_f32 v43, v48, v49
	v_cvt_pk_bf16_f32 v44, v54, v55
	v_cvt_pk_bf16_f32 v45, v56, v57
	v_addc_co_u32_e32 v47, vcc, 0, v141, vcc
	v_pk_mul_f32 v[40:41], v[40:41], v[52:53] op_sel_hi:[1,0]
	v_pk_mul_f32 v[38:39], v[38:39], v[52:53] op_sel_hi:[1,0]
	v_max_f32_e32 v35, 0, v35
	v_max_f32_e32 v34, 0, v34
	global_store_dwordx4 v[46:47], v[42:45], off sc1
	v_pk_mul_f32 v[36:37], v[36:37], v[52:53] op_sel_hi:[1,0]
	v_max_f32_e32 v39, 0, v39
	v_max_f32_e32 v38, 0, v38
	v_pk_mul_f32 v[42:43], v[34:35], v[34:35]
	v_max_f32_e32 v35, 0, v41
	v_max_f32_e32 v34, 0, v40
	v_pk_mul_f32 v[38:39], v[38:39], v[38:39]
	v_pk_mul_f32 v[40:41], v[34:35], v[34:35]
	v_max_f32_e32 v35, 0, v37
	v_max_f32_e32 v34, 0, v36
	v_pk_mul_f32 v[44:45], v[34:35], v[34:35]
	v_cvt_pk_bf16_f32 v34, v38, v39
	ds_read2_b32 v[38:39], v151 offset0:160 offset1:176
	v_cvt_pk_bf16_f32 v35, v40, v41
	v_cvt_pk_bf16_f32 v36, v42, v43
	v_cvt_pk_bf16_f32 v37, v44, v45
	global_store_dwordx4 v[50:51], v[34:37], off offset:256 sc1
	s_waitcnt lgkmcnt(0)
	v_pk_mul_f32 v[26:27], v[26:27], v[38:39] op_sel_hi:[1,0]
	v_pk_mul_f32 v[32:33], v[32:33], v[38:39] op_sel_hi:[1,0]
	v_pk_mul_f32 v[30:31], v[30:31], v[38:39] op_sel_hi:[1,0]
	v_max_f32_e32 v27, 0, v27
	v_max_f32_e32 v26, 0, v26
	s_mov_b64 s[0:1], 0x280000
	v_pk_mul_f32 v[28:29], v[28:29], v[38:39] op_sel_hi:[1,0]
	v_max_f32_e32 v31, 0, v31
	v_max_f32_e32 v30, 0, v30
	v_pk_mul_f32 v[36:37], v[26:27], v[26:27]
	v_max_f32_e32 v27, 0, v33
	v_max_f32_e32 v26, 0, v32
	v_lshl_add_u64 v[34:35], v[140:141], 0, s[0:1]
	v_pk_mul_f32 v[30:31], v[30:31], v[30:31]
	v_pk_mul_f32 v[32:33], v[26:27], v[26:27]
	v_max_f32_e32 v27, 0, v29
	v_max_f32_e32 v26, 0, v28
	s_mov_b32 s0, 0x280000
	v_pk_mul_f32 v[40:41], v[26:27], v[26:27]
	v_cvt_pk_bf16_f32 v26, v30, v31
	v_add_co_u32_e32 v30, vcc, s0, v140
	v_pk_mul_f32 v[18:19], v[18:19], v[38:39] op_sel_hi:[1,0]
	v_cvt_pk_bf16_f32 v27, v32, v33
	v_cvt_pk_bf16_f32 v28, v36, v37
	v_cvt_pk_bf16_f32 v29, v40, v41
	v_addc_co_u32_e32 v31, vcc, 0, v141, vcc
	v_pk_mul_f32 v[24:25], v[24:25], v[38:39] op_sel_hi:[1,0]
	v_max_f32_e32 v19, 0, v19
	v_max_f32_e32 v18, 0, v18
	global_store_dwordx4 v[30:31], v[26:29], off sc1
	v_pk_mul_f32 v[22:23], v[22:23], v[38:39] op_sel_hi:[1,0]
	v_pk_mul_f32 v[20:21], v[20:21], v[38:39] op_sel_hi:[1,0]
	v_pk_mul_f32 v[26:27], v[18:19], v[18:19]
	v_max_f32_e32 v19, 0, v25
	v_max_f32_e32 v18, 0, v24
	v_max_f32_e32 v23, 0, v23
	v_max_f32_e32 v22, 0, v22
	v_pk_mul_f32 v[24:25], v[18:19], v[18:19]
	v_max_f32_e32 v19, 0, v21
	v_max_f32_e32 v18, 0, v20
	v_pk_mul_f32 v[22:23], v[22:23], v[22:23]
	v_pk_mul_f32 v[28:29], v[18:19], v[18:19]
	v_cvt_pk_bf16_f32 v18, v22, v23
	v_cvt_pk_bf16_f32 v19, v24, v25
	v_cvt_pk_bf16_f32 v20, v26, v27
	v_cvt_pk_bf16_f32 v21, v28, v29
	global_store_dwordx4 v[34:35], v[18:21], off offset:256 sc1
	s_mov_b64 s[0:1], 0x2c0000
	s_nop 0
	v_mov_b32_e32 v20, v39
	v_pk_mul_f32 v[10:11], v[10:11], v[20:21] op_sel_hi:[1,0]
	v_pk_mul_f32 v[16:17], v[16:17], v[20:21] op_sel_hi:[1,0]
	v_pk_mul_f32 v[14:15], v[14:15], v[20:21] op_sel_hi:[1,0]
	v_max_f32_e32 v11, 0, v11
	v_max_f32_e32 v10, 0, v10
	v_pk_mul_f32 v[12:13], v[12:13], v[20:21] op_sel_hi:[1,0]
	v_max_f32_e32 v15, 0, v15
	v_max_f32_e32 v14, 0, v14
	v_pk_mul_f32 v[22:23], v[10:11], v[10:11]
	v_max_f32_e32 v11, 0, v17
	v_max_f32_e32 v10, 0, v16
	v_lshl_add_u64 v[18:19], v[140:141], 0, s[0:1]
	v_pk_mul_f32 v[14:15], v[14:15], v[14:15]
	v_pk_mul_f32 v[16:17], v[10:11], v[10:11]
	v_max_f32_e32 v11, 0, v13
	v_max_f32_e32 v10, 0, v12
	s_mov_b32 s0, 0x2c0000
	v_pk_mul_f32 v[24:25], v[10:11], v[10:11]
	v_cvt_pk_bf16_f32 v10, v14, v15
	v_add_co_u32_e32 v14, vcc, s0, v140
	v_pk_mul_f32 v[2:3], v[2:3], v[20:21] op_sel_hi:[1,0]
	v_cvt_pk_bf16_f32 v11, v16, v17
	v_cvt_pk_bf16_f32 v12, v22, v23
	v_cvt_pk_bf16_f32 v13, v24, v25
	v_addc_co_u32_e32 v15, vcc, 0, v141, vcc
	v_pk_mul_f32 v[8:9], v[8:9], v[20:21] op_sel_hi:[1,0]
	v_max_f32_e32 v3, 0, v3
	v_max_f32_e32 v2, 0, v2
	global_store_dwordx4 v[14:15], v[10:13], off sc1
	v_pk_mul_f32 v[6:7], v[6:7], v[20:21] op_sel_hi:[1,0]
	v_pk_mul_f32 v[4:5], v[4:5], v[20:21] op_sel_hi:[1,0]
	v_pk_mul_f32 v[10:11], v[2:3], v[2:3]
	v_max_f32_e32 v3, 0, v9
	v_max_f32_e32 v2, 0, v8
	v_max_f32_e32 v7, 0, v7
	v_max_f32_e32 v6, 0, v6
	v_pk_mul_f32 v[8:9], v[2:3], v[2:3]
	v_max_f32_e32 v3, 0, v5
	v_max_f32_e32 v2, 0, v4
	v_pk_mul_f32 v[6:7], v[6:7], v[6:7]
	v_pk_mul_f32 v[12:13], v[2:3], v[2:3]
	v_cvt_pk_bf16_f32 v2, v6, v7
	v_cvt_pk_bf16_f32 v3, v8, v9
	v_cvt_pk_bf16_f32 v4, v10, v11
	v_cvt_pk_bf16_f32 v5, v12, v13
	s_andn2_b64 vcc, exec, s[44:45]
	s_mov_b64 s[0:1], -1
	global_store_dwordx4 v[18:19], v[2:5], off offset:256 sc1
	s_cbranch_vccnz .LBB0_754
;     __device__ __forceinline__ void prep(const Unit& u, int tid, int buf) const {
;         if (tid < BM) { const float* p = ss + (size_t)(u.pm * BM + tid) * 32; float sq = 0.f;
; #pragma unroll
;             for (int i = 0; i < 8; ++i) { const f32x4 v = *(const f32x4*)(p + 4 * i); sq += (v[0] + v[1]) + (v[2] + v[3]); }
;             rtab[buf * BM + tid] = __builtin_amdgcn_rsqf(sq * (1.0f / 2048.0f) + 1e-6f); }
; template <class Epi, class Sched, bool ALIGN_EPI = false, bool SP2 = false>
; __device__ __forceinline__ void gemm_phase(PG8_LAS unsigned char* lds, const Gemm g, const Sched& S, const Epi& E) {
;     ...
;                     for (int n = 0; n < 2; ++n) acc[a][b][m][n] = (f32x4){0.f, 0.f, 0.f, 0.f};
;         cur = nxt; cA = nA; cB = nB; ++ui;
;         if constexpr (Epi::HAS_PREP) { if (cur.pm != prep_pm) { ++prep_gen; E.prep(cur, tid, prep_gen & 1); prep_pm = cur.pm; } }
	s_cmp_eq_u32 s22, s57
	s_cbranch_scc1 .LBB0_770
	s_add_i32 s55, s55, 1
	s_and_saveexec_b64 s[0:1], s[42:43]
	s_cbranch_execz .LBB0_769
	v_lshl_add_u32 v2, s22, 8, v144
	v_ashrrev_i32_e32 v3, 31, v2
	v_lshlrev_b64 v[2:3], 7, v[2:3]
	v_lshl_add_u64 v[18:19], s[4:5], 0, v[2:3]
	global_load_dwordx4 v[2:5], v[18:19], off offset:48
	global_load_dwordx4 v[6:9], v[18:19], off offset:32
	global_load_dwordx4 v[10:13], v[18:19], off
	global_load_dwordx4 v[14:17], v[18:19], off offset:16
	s_lshl_b32 s19, s55, 10
	s_and_b32 s19, s19, 0x400
	s_waitcnt vmcnt(0)
	v_add_f32_e32 v24, v2, v3
	v_add_f32_e32 v26, v4, v5
	v_mov_b32_e32 v20, v10
	v_mov_b32_e32 v21, v14
	v_mov_b32_e32 v14, v11
	v_pk_add_f32 v[10:11], v[20:21], v[14:15]
	v_mov_b32_e32 v14, v12
	v_mov_b32_e32 v15, v16
	v_mov_b32_e32 v16, v13
	v_pk_add_f32 v[12:13], v[14:15], v[16:17]
	s_nop 0
	v_pk_add_f32 v[10:11], v[10:11], v[12:13]
	s_nop 0
	v_add_f32_e32 v10, 0, v10
	v_add_f32_e32 v20, v10, v11
	v_mov_b32_e32 v10, v7
	v_mov_b32_e32 v11, v8
	v_mov_b32_e32 v7, v9
	v_pk_add_f32 v[6:7], v[10:11], v[6:7]
	s_nop 0
	v_pk_add_f32 v[22:23], v[6:7], v[6:7] op_sel:[0,1] op_sel_hi:[1,0]
	global_load_dwordx4 v[2:5], v[18:19], off offset:112
	global_load_dwordx4 v[6:9], v[18:19], off offset:96
	global_load_dwordx4 v[10:13], v[18:19], off offset:80
	global_load_dwordx4 v[14:17], v[18:19], off offset:64
	s_waitcnt vmcnt(2)
	v_add_f32_e32 v6, v6, v7
	v_add_f32_e32 v8, v8, v9
	s_waitcnt vmcnt(0)
	v_mov_b32_e32 v21, v14
	v_mov_b32_e32 v23, v15
	v_mov_b32_e32 v25, v16
	v_mov_b32_e32 v27, v17
	v_pk_add_f32 v[14:15], v[20:21], v[22:23]
	v_pk_add_f32 v[16:17], v[24:25], v[26:27]
	v_mov_b32_e32 v7, v4
	v_pk_add_f32 v[14:15], v[14:15], v[16:17]
	v_mov_b32_e32 v16, v11
	v_mov_b32_e32 v17, v12
	v_mov_b32_e32 v11, v13
	v_pk_add_f32 v[10:11], v[16:17], v[10:11]
	v_pk_add_f32 v[14:15], v[14:15], v[14:15] op_sel:[0,1] op_sel_hi:[1,0]
	v_pk_add_f32 v[10:11], v[10:11], v[10:11] op_sel:[0,1] op_sel_hi:[1,0]
	v_mov_b32_e32 v15, v2
	v_mov_b32_e32 v11, v3
	v_mov_b32_e32 v9, v5
	v_pk_add_f32 v[2:3], v[14:15], v[10:11]
	v_pk_add_f32 v[4:5], v[6:7], v[8:9]
	s_nop 0
	v_pk_add_f32 v[2:3], v[2:3], v[4:5]
	s_nop 0
	v_add_f32_e32 v2, v2, v3
	v_fmamk_f32 v2, v2, 0x3a000000, v1
	v_rsq_f32_e32 v2, v2
	v_add_u32_e32 v3, s19, v148
	ds_write_b32 v3, v2

; __device__ __forceinline__ unsigned cvt_pk_bf16(float lo, float hi) { f32x2 v = {lo, hi}; bf16x2_t b = __builtin_convertvector(v, bf16x2_t); return __builtin_bit_cast(unsigned, b); }
;     __device__ __forceinline__ void operator()(const f32x4 (&acc)[2][2][4][2], const Unit& u, int wr, int wc, int fr, int fq) const {
;     ...
;         for (int ai = 0; ai < 2; ++ai) {
;             u32x4 xr[4][2];
; #pragma unroll
;             for (int m = 0; m < 4; ++m)
; #pragma unroll
;                 for (int bj = 0; bj < 2; ++bj) xr[m][bj] = *(const u32x4*)(xb + (size_t)(u.pm * BM + ai * HALF + wr * 64 + m * 16 + fr) * 2048 + col0 + bj * HALF);
; #pragma unroll
;             for (int m = 0; m < 4; ++m) { const int row = u.pm * BM + ai * HALF + wr * 64 + m * 16 + fr; const size_t off = (size_t)row * 2048 + col0; float sq = 0.f;
; #pragma unroll
;                 for (int bj = 0; bj < 2; ++bj) { const size_t o2 = off + bj * HALF; const u32x4 xw = xr[m][bj];
;                     f32x4 x0, x1; x0[0] = __uint_as_float(xw.x << 16); x0[1] = __uint_as_float(xw.x & 0xffff0000u); x0[2] = __uint_as_float(xw.y << 16); x0[3] = __uint_as_float(xw.y & 0xffff0000u);
;                     x1[0] = __uint_as_float(xw.z << 16); x1[1] = __uint_as_float(xw.z & 0xffff0000u); x1[2] = __uint_as_float(xw.w << 16); x1[3] = __uint_as_float(xw.w & 0xffff0000u);
;                     x0 = x0 + acc[ai][bj][m][0]; x1 = x1 + acc[ai][bj][m][1];
;                     if (FINAL) { *(f32x4*)(out + o2) = x0; *(f32x4*)(out + o2 + 4) = x1; }
;                     else { u32x4 w; w.x = cvt_pk_bf16(x0[0], x0[1]); w.y = cvt_pk_bf16(x0[2], x0[3]); w.z = cvt_pk_bf16(x1[0], x1[1]); w.w = cvt_pk_bf16(x1[2], x1[3]); *(u32x4*)(xb + o2) = w; }
;                     sq += ((x0[0] * x0[0] + x0[1] * x0[1]) + (x0[2] * x0[2] + x0[3] * x0[3])) + ((x1[0] * x1[0] + x1[1] * x1[1]) + (x1[2] * x1[2] + x1[3] * x1[3])); }
;                 sq += __shfl_xor(sq, 16); sq += __shfl_xor(sq, 32);
;                 if (!FINAL && fq == 0) ssn[(size_t)row * 32 + u.pn * 4 + wc] = sq; }
.LBB0_845:
	v_and_b32_e32 v131, 64, v195
	v_xor_b32_e32 v130, 16, v195
	v_add_u32_e32 v131, 64, v131
	v_cmp_lt_i32_e32 vcc, v130, v131
	v_lshl_or_b32 v176, s34, 8, v200
	v_lshl_add_u32 v178, s60, 8, v161
	v_cndmask_b32_e32 v130, v195, v130, vcc
	v_ashrrev_i32_e32 v177, 31, v176
	v_lshlrev_b32_e32 v203, 2, v130
	v_xor_b32_e32 v130, 32, v195
	v_cmp_lt_i32_e32 vcc, v130, v131
	v_lshlrev_b64 v[204:205], 1, v[176:177]
	v_ashrrev_i32_e32 v179, 31, v178
	v_cndmask_b32_e32 v130, v195, v130, vcc
	v_lshl_add_u64 v[180:181], s[46:47], 0, v[204:205]
	v_lshlrev_b64 v[206:207], 12, v[178:179]
	v_lshlrev_b32_e32 v202, 2, v130
	v_lshl_add_u64 v[130:131], v[180:181], 0, v[206:207]
	global_load_dwordx4 v[162:165], v[130:131], off
	global_load_dwordx4 v[154:157], v[130:131], off offset:256
	v_or_b32_e32 v190, 16, v178
	v_ashrrev_i32_e32 v191, 31, v190
	v_or_b32_e32 v186, 32, v178
	v_lshlrev_b64 v[192:193], 12, v[190:191]
	v_ashrrev_i32_e32 v187, 31, v186
	v_or_b32_e32 v182, 48, v178
	v_lshl_add_u64 v[130:131], v[180:181], 0, v[192:193]
	v_lshlrev_b64 v[188:189], 12, v[186:187]
	v_ashrrev_i32_e32 v183, 31, v182
	global_load_dwordx4 v[150:153], v[130:131], off
	global_load_dwordx4 v[146:149], v[130:131], off offset:256
	v_lshl_add_u64 v[130:131], v[180:181], 0, v[188:189]
	v_lshlrev_b64 v[184:185], 12, v[182:183]
	global_load_dwordx4 v[142:145], v[130:131], off
	global_load_dwordx4 v[138:141], v[130:131], off offset:256
	v_lshl_add_u64 v[130:131], v[180:181], 0, v[184:185]
	global_load_dwordx4 v[134:137], v[130:131], off
	s_nop 0
	global_load_dwordx4 v[130:133], v[130:131], off offset:256
	v_lshl_add_u64 v[206:207], s[46:47], 0, v[206:207]
	v_lshl_add_u64 v[204:205], v[206:207], 0, v[204:205]
	s_lshl_b32 s0, s34, 2
	s_ashr_i32 s1, s0, 31
	s_waitcnt vmcnt(0)
	v_lshlrev_b32_e32 v208, 16, v162
	v_and_b32_e32 v209, 0xffff0000, v162
	v_lshlrev_b32_e32 v162, 16, v163
	v_and_b32_e32 v163, 0xffff0000, v163
	v_lshlrev_b32_e32 v210, 16, v164
	v_and_b32_e32 v211, 0xffff0000, v164
	v_lshlrev_b32_e32 v164, 16, v165
	v_and_b32_e32 v165, 0xffff0000, v165
	v_pk_add_f32 v[128:129], v[128:129], v[162:163]
	v_pk_add_f32 v[126:127], v[126:127], v[208:209]
	v_pk_add_f32 v[162:163], v[124:125], v[164:165]
	v_pk_add_f32 v[164:165], v[122:123], v[210:211]
	v_cvt_pk_bf16_f32 v122, v126, v127
	v_cvt_pk_bf16_f32 v123, v128, v129
	v_cvt_pk_bf16_f32 v124, v164, v165
	v_cvt_pk_bf16_f32 v125, v162, v163
	global_store_dwordx4 v[204:205], v[122:125], off sc1
	s_nop 1
	v_mul_f32_e32 v122, v127, v127
	v_mul_f32_e32 v123, v129, v129
	v_fmac_f32_e32 v122, v126, v126
	v_fmac_f32_e32 v123, v128, v128
	v_add_f32_e32 v122, v122, v123
	v_mul_f32_e32 v123, v165, v165
	v_mul_f32_e32 v124, v163, v163
	v_fmac_f32_e32 v123, v164, v164
	v_fmac_f32_e32 v124, v162, v162
	v_add_f32_e32 v123, v123, v124
	v_add_f32_e32 v162, v122, v123
	v_lshlrev_b32_e32 v122, 16, v154
	v_and_b32_e32 v123, 0xffff0000, v154
	v_lshlrev_b32_e32 v124, 16, v155
	v_and_b32_e32 v125, 0xffff0000, v155
	v_lshlrev_b32_e32 v126, 16, v156
	v_and_b32_e32 v127, 0xffff0000, v156
	v_lshlrev_b32_e32 v128, 16, v157
	v_and_b32_e32 v129, 0xffff0000, v157
	v_pk_add_f32 v[120:121], v[120:121], v[124:125]
	v_pk_add_f32 v[118:119], v[118:119], v[122:123]
	v_pk_add_f32 v[122:123], v[116:117], v[128:129]
	v_pk_add_f32 v[124:125], v[114:115], v[126:127]
	v_cvt_pk_bf16_f32 v114, v118, v119
	v_cvt_pk_bf16_f32 v115, v120, v121
	v_cvt_pk_bf16_f32 v116, v124, v125
	v_cvt_pk_bf16_f32 v117, v122, v123
	global_store_dwordx4 v[204:205], v[114:117], off offset:256 sc1
	s_nop 1
	v_mul_f32_e32 v114, v119, v119
	v_mul_f32_e32 v115, v121, v121
	v_fmac_f32_e32 v114, v118, v118
	v_fmac_f32_e32 v115, v120, v120
	v_add_f32_e32 v114, v114, v115
	v_mul_f32_e32 v115, v125, v125
	v_mul_f32_e32 v116, v123, v123
	v_fmac_f32_e32 v115, v124, v124
	v_fmac_f32_e32 v116, v122, v122
	v_add_f32_e32 v115, v115, v116
	v_add_f32_e32 v114, v114, v115
	v_add_f32_e32 v114, v162, v114
	ds_bpermute_b32 v115, v203, v114
	s_waitcnt lgkmcnt(0)
	v_add_f32_e32 v114, v114, v115
	ds_bpermute_b32 v115, v202, v114
	s_and_saveexec_b64 s[30:31], s[42:43]
	s_mov_b64 s[62:63], s[88:89]
	s_cbranch_execz .LBB0_847
	s_waitcnt lgkmcnt(0)
	v_add_f32_e32 v116, v114, v115
	v_lshlrev_b64 v[114:115], 7, v[178:179]
	v_lshl_add_u64 v[114:115], s[14:15], 0, v[114:115]
	v_lshl_add_u64 v[114:115], s[0:1], 2, v[114:115]
	s_lshl_b32 s34, s55, 2
	v_lshl_add_u64 v[114:115], v[114:115], 0, s[34:35]
	global_store_dword v[114:115], v116, off sc1
; __device__ __forceinline__ unsigned cvt_pk_bf16(float lo, float hi) { f32x2 v = {lo, hi}; bf16x2_t b = __builtin_convertvector(v, bf16x2_t); return __builtin_bit_cast(unsigned, b); }
;     __device__ __forceinline__ void operator()(const f32x4 (&acc)[2][2][4][2], const Unit& u, int wr, int wc, int fr, int fq) const {
;     ...
;             for (int m = 0; m < 4; ++m) { const int row = u.pm * BM + ai * HALF + wr * 64 + m * 16 + fr; const size_t off = (size_t)row * 2048 + col0; float sq = 0.f;
; #pragma unroll
;                 for (int bj = 0; bj < 2; ++bj) { const size_t o2 = off + bj * HALF; const u32x4 xw = xr[m][bj];
;                     f32x4 x0, x1; x0[0] = __uint_as_float(xw.x << 16); x0[1] = __uint_as_float(xw.x & 0xffff0000u); x0[2] = __uint_as_float(xw.y << 16); x0[3] = __uint_as_float(xw.y & 0xffff0000u);
;                     x1[0] = __uint_as_float(xw.z << 16); x1[1] = __uint_as_float(xw.z & 0xffff0000u); x1[2] = __uint_as_float(xw.w << 16); x1[3] = __uint_as_float(xw.w & 0xffff0000u);
;                     x0 = x0 + acc[ai][bj][m][0]; x1 = x1 + acc[ai][bj][m][1];
;                     if (FINAL) { *(f32x4*)(out + o2) = x0; *(f32x4*)(out + o2 + 4) = x1; }
;                     else { u32x4 w; w.x = cvt_pk_bf16(x0[0], x0[1]); w.y = cvt_pk_bf16(x0[2], x0[3]); w.z = cvt_pk_bf16(x1[0], x1[1]); w.w = cvt_pk_bf16(x1[2], x1[3]); *(u32x4*)(xb + o2) = w; }
;                     sq += ((x0[0] * x0[0] + x0[1] * x0[1]) + (x0[2] * x0[2] + x0[3] * x0[3])) + ((x1[0] * x1[0] + x1[1] * x1[1]) + (x1[2] * x1[2] + x1[3] * x1[3])); }
;                 sq += __shfl_xor(sq, 16); sq += __shfl_xor(sq, 32);
;                 if (!FINAL && fq == 0) ssn[(size_t)row * 32 + u.pn * 4 + wc] = sq; }
.LBB0_847:
	s_or_b64 exec, exec, s[30:31]
	v_lshlrev_b32_e32 v114, 16, v150
	s_waitcnt lgkmcnt(0)
	v_and_b32_e32 v115, 0xffff0000, v150
	v_lshlrev_b32_e32 v116, 16, v151
	v_and_b32_e32 v117, 0xffff0000, v151
	v_lshlrev_b32_e32 v118, 16, v152
	v_and_b32_e32 v119, 0xffff0000, v152
	v_pk_add_f32 v[110:111], v[110:111], v[114:115]
	v_pk_add_f32 v[112:113], v[112:113], v[116:117]
	v_pk_add_f32 v[116:117], v[106:107], v[118:119]
	v_cvt_pk_bf16_f32 v106, v110, v111
	v_mul_f32_e32 v111, v111, v111
	v_lshlrev_b32_e32 v120, 16, v153
	v_and_b32_e32 v121, 0xffff0000, v153
	v_fmac_f32_e32 v111, v110, v110
	v_mul_f32_e32 v110, v113, v113
	v_pk_add_f32 v[114:115], v[108:109], v[120:121]
	v_fmac_f32_e32 v110, v112, v112
	v_cvt_pk_bf16_f32 v107, v112, v113
	v_add_f32_e32 v110, v111, v110
	v_mul_f32_e32 v111, v117, v117
	v_mul_f32_e32 v112, v115, v115
	v_fmac_f32_e32 v111, v116, v116
	v_fmac_f32_e32 v112, v114, v114
	v_add_f32_e32 v111, v111, v112
	v_add_f32_e32 v118, v110, v111
	v_lshlrev_b32_e32 v110, 16, v146
	v_and_b32_e32 v111, 0xffff0000, v146
	v_lshlrev_b32_e32 v112, 16, v147
	v_and_b32_e32 v113, 0xffff0000, v147
	v_cvt_pk_bf16_f32 v109, v114, v115
	v_lshlrev_b32_e32 v114, 16, v148
	v_and_b32_e32 v115, 0xffff0000, v148
	v_pk_add_f32 v[104:105], v[104:105], v[112:113]
	v_pk_add_f32 v[102:103], v[102:103], v[110:111]
	v_cvt_pk_bf16_f32 v108, v116, v117
	v_lshlrev_b32_e32 v116, 16, v149
	v_and_b32_e32 v117, 0xffff0000, v149
	v_pk_add_f32 v[112:113], v[98:99], v[114:115]
	v_mul_f32_e32 v98, v103, v103
	v_mul_f32_e32 v99, v105, v105
	v_pk_add_f32 v[110:111], v[100:101], v[116:117]
	v_fmac_f32_e32 v98, v102, v102
	v_fmac_f32_e32 v99, v104, v104
	v_add_f32_e32 v98, v98, v99
	v_mul_f32_e32 v99, v113, v113
	v_mul_f32_e32 v100, v111, v111
	v_fmac_f32_e32 v99, v112, v112
	v_fmac_f32_e32 v100, v110, v110
	v_add_f32_e32 v99, v99, v100
	v_add_f32_e32 v98, v98, v99
	v_add_f32_e32 v101, v118, v98
	ds_bpermute_b32 v116, v203, v101
	v_lshl_add_u64 v[98:99], s[46:47], 0, v[192:193]
	v_lshl_add_u64 v[114:115], v[176:177], 1, v[98:99]
	v_cvt_pk_bf16_f32 v100, v102, v103
	v_cvt_pk_bf16_f32 v102, v112, v113
	s_waitcnt lgkmcnt(0)
	v_add_f32_e32 v98, v101, v116
	ds_bpermute_b32 v99, v202, v98
	v_cvt_pk_bf16_f32 v101, v104, v105
	v_cvt_pk_bf16_f32 v103, v110, v111
	global_store_dwordx4 v[114:115], v[106:109], off sc1
	global_store_dwordx4 v[114:115], v[100:103], off offset:256 sc1
	s_and_saveexec_b64 s[30:31], s[42:43]
	s_cbranch_execz .LBB0_849
	s_waitcnt lgkmcnt(0)
	v_add_f32_e32 v100, v98, v99
	v_lshlrev_b64 v[98:99], 7, v[190:191]
	v_lshl_add_u64 v[98:99], s[14:15], 0, v[98:99]
	v_lshl_add_u64 v[98:99], s[0:1], 2, v[98:99]
	s_lshl_b32 s34, s55, 2
	v_lshl_add_u64 v[98:99], v[98:99], 0, s[34:35]
	global_store_dword v[98:99], v100, off sc1
.LBB0_849:
	s_or_b64 exec, exec, s[30:31]
	v_lshlrev_b32_e32 v98, 16, v142
	s_waitcnt lgkmcnt(0)
	v_and_b32_e32 v99, 0xffff0000, v142
	v_lshlrev_b32_e32 v100, 16, v143
	v_and_b32_e32 v101, 0xffff0000, v143
	v_lshlrev_b32_e32 v102, 16, v144
	v_and_b32_e32 v103, 0xffff0000, v144
	v_pk_add_f32 v[94:95], v[94:95], v[98:99]
	v_pk_add_f32 v[96:97], v[96:97], v[100:101]
	v_pk_add_f32 v[100:101], v[90:91], v[102:103]
	v_cvt_pk_bf16_f32 v90, v94, v95
	v_mul_f32_e32 v95, v95, v95
	v_lshlrev_b32_e32 v104, 16, v145
	v_and_b32_e32 v105, 0xffff0000, v145
	v_fmac_f32_e32 v95, v94, v94
	v_mul_f32_e32 v94, v97, v97
	v_pk_add_f32 v[98:99], v[92:93], v[104:105]
	v_fmac_f32_e32 v94, v96, v96
	v_cvt_pk_bf16_f32 v91, v96, v97
	v_add_f32_e32 v94, v95, v94
	v_mul_f32_e32 v95, v101, v101
	v_mul_f32_e32 v96, v99, v99
	v_fmac_f32_e32 v95, v100, v100
	v_fmac_f32_e32 v96, v98, v98
	v_add_f32_e32 v95, v95, v96
	v_add_f32_e32 v102, v94, v95
	v_lshlrev_b32_e32 v94, 16, v138
	v_and_b32_e32 v95, 0xffff0000, v138
	v_lshlrev_b32_e32 v96, 16, v139
	v_and_b32_e32 v97, 0xffff0000, v139
	v_cvt_pk_bf16_f32 v93, v98, v99
	v_lshlrev_b32_e32 v98, 16, v140
	v_and_b32_e32 v99, 0xffff0000, v140
	v_pk_add_f32 v[88:89], v[88:89], v[96:97]
	v_pk_add_f32 v[86:87], v[86:87], v[94:95]
	v_cvt_pk_bf16_f32 v92, v100, v101
	v_lshlrev_b32_e32 v100, 16, v141
	v_and_b32_e32 v101, 0xffff0000, v141
	v_pk_add_f32 v[96:97], v[82:83], v[98:99]
	v_mul_f32_e32 v82, v87, v87
	v_mul_f32_e32 v83, v89, v89
	v_pk_add_f32 v[94:95], v[84:85], v[100:101]
	v_fmac_f32_e32 v82, v86, v86
	v_fmac_f32_e32 v83, v88, v88
	v_add_f32_e32 v82, v82, v83
	v_mul_f32_e32 v83, v97, v97
	v_mul_f32_e32 v84, v95, v95
	v_fmac_f32_e32 v83, v96, v96
	v_fmac_f32_e32 v84, v94, v94
	v_add_f32_e32 v83, v83, v84
	v_add_f32_e32 v82, v82, v83
	v_add_f32_e32 v85, v102, v82
	ds_bpermute_b32 v100, v203, v85
	v_lshl_add_u64 v[82:83], s[46:47], 0, v[188:189]
	v_lshl_add_u64 v[98:99], v[176:177], 1, v[82:83]
	v_cvt_pk_bf16_f32 v84, v86, v87
	v_cvt_pk_bf16_f32 v86, v96, v97
	s_waitcnt lgkmcnt(0)
	v_add_f32_e32 v82, v85, v100
	ds_bpermute_b32 v83, v202, v82
	v_cvt_pk_bf16_f32 v85, v88, v89
	v_cvt_pk_bf16_f32 v87, v94, v95
	global_store_dwordx4 v[98:99], v[90:93], off sc1
	global_store_dwordx4 v[98:99], v[84:87], off offset:256 sc1
	s_and_saveexec_b64 s[30:31], s[42:43]
	s_cbranch_execz .LBB0_851
	s_waitcnt lgkmcnt(0)
	v_add_f32_e32 v84, v82, v83
	v_lshlrev_b64 v[82:83], 7, v[186:187]
	v_lshl_add_u64 v[82:83], s[14:15], 0, v[82:83]
	v_lshl_add_u64 v[82:83], s[0:1], 2, v[82:83]
	s_lshl_b32 s34, s55, 2
	v_lshl_add_u64 v[82:83], v[82:83], 0, s[34:35]
	global_store_dword v[82:83], v84, off sc1
; __device__ __forceinline__ unsigned cvt_pk_bf16(float lo, float hi) { f32x2 v = {lo, hi}; bf16x2_t b = __builtin_convertvector(v, bf16x2_t); return __builtin_bit_cast(unsigned, b); }
;     __device__ __forceinline__ void operator()(const f32x4 (&acc)[2][2][4][2], const Unit& u, int wr, int wc, int fr, int fq) const {
;     ...
;         for (int ai = 0; ai < 2; ++ai) {
;             u32x4 xr[4][2];
; #pragma unroll
;             for (int m = 0; m < 4; ++m)
; #pragma unroll
;                 for (int bj = 0; bj < 2; ++bj) xr[m][bj] = *(const u32x4*)(xb + (size_t)(u.pm * BM + ai * HALF + wr * 64 + m * 16 + fr) * 2048 + col0 + bj * HALF);
; #pragma unroll
;             for (int m = 0; m < 4; ++m) { const int row = u.pm * BM + ai * HALF + wr * 64 + m * 16 + fr; const size_t off = (size_t)row * 2048 + col0; float sq = 0.f;
; #pragma unroll
;                 for (int bj = 0; bj < 2; ++bj) { const size_t o2 = off + bj * HALF; const u32x4 xw = xr[m][bj];
;                     f32x4 x0, x1; x0[0] = __uint_as_float(xw.x << 16); x0[1] = __uint_as_float(xw.x & 0xffff0000u); x0[2] = __uint_as_float(xw.y << 16); x0[3] = __uint_as_float(xw.y & 0xffff0000u);
;                     x1[0] = __uint_as_float(xw.z << 16); x1[1] = __uint_as_float(xw.z & 0xffff0000u); x1[2] = __uint_as_float(xw.w << 16); x1[3] = __uint_as_float(xw.w & 0xffff0000u);
;                     x0 = x0 + acc[ai][bj][m][0]; x1 = x1 + acc[ai][bj][m][1];
;                     if (FINAL) { *(f32x4*)(out + o2) = x0; *(f32x4*)(out + o2 + 4) = x1; }
;                     else { u32x4 w; w.x = cvt_pk_bf16(x0[0], x0[1]); w.y = cvt_pk_bf16(x0[2], x0[3]); w.z = cvt_pk_bf16(x1[0], x1[1]); w.w = cvt_pk_bf16(x1[2], x1[3]); *(u32x4*)(xb + o2) = w; }
;                     sq += ((x0[0] * x0[0] + x0[1] * x0[1]) + (x0[2] * x0[2] + x0[3] * x0[3])) + ((x1[0] * x1[0] + x1[1] * x1[1]) + (x1[2] * x1[2] + x1[3] * x1[3])); }
;                 sq += __shfl_xor(sq, 16); sq += __shfl_xor(sq, 32);
;                 if (!FINAL && fq == 0) ssn[(size_t)row * 32 + u.pn * 4 + wc] = sq; }
.LBB0_851:
	s_or_b64 exec, exec, s[30:31]
	v_lshlrev_b32_e32 v82, 16, v134
	s_waitcnt lgkmcnt(0)
	v_and_b32_e32 v83, 0xffff0000, v134
	v_lshlrev_b32_e32 v84, 16, v135
	v_and_b32_e32 v85, 0xffff0000, v135
	v_lshlrev_b32_e32 v86, 16, v136
	v_and_b32_e32 v87, 0xffff0000, v136
	v_pk_add_f32 v[78:79], v[78:79], v[82:83]
	v_pk_add_f32 v[80:81], v[80:81], v[84:85]
	v_pk_add_f32 v[84:85], v[74:75], v[86:87]
	v_cvt_pk_bf16_f32 v74, v78, v79
	v_mul_f32_e32 v79, v79, v79
	v_lshlrev_b32_e32 v88, 16, v137
	v_and_b32_e32 v89, 0xffff0000, v137
	v_fmac_f32_e32 v79, v78, v78
	v_mul_f32_e32 v78, v81, v81
	v_pk_add_f32 v[82:83], v[76:77], v[88:89]
	v_fmac_f32_e32 v78, v80, v80
	v_cvt_pk_bf16_f32 v75, v80, v81
	v_add_f32_e32 v78, v79, v78
	v_mul_f32_e32 v79, v85, v85
	v_mul_f32_e32 v80, v83, v83
	v_fmac_f32_e32 v79, v84, v84
	v_fmac_f32_e32 v80, v82, v82
	v_add_f32_e32 v79, v79, v80
	v_add_f32_e32 v86, v78, v79
	v_lshlrev_b32_e32 v78, 16, v130
	v_and_b32_e32 v79, 0xffff0000, v130
	v_lshlrev_b32_e32 v80, 16, v131
	v_and_b32_e32 v81, 0xffff0000, v131
	v_cvt_pk_bf16_f32 v77, v82, v83
	v_lshlrev_b32_e32 v82, 16, v132
	v_and_b32_e32 v83, 0xffff0000, v132
	v_pk_add_f32 v[72:73], v[72:73], v[80:81]
	v_pk_add_f32 v[70:71], v[70:71], v[78:79]
	v_cvt_pk_bf16_f32 v76, v84, v85
	v_lshlrev_b32_e32 v84, 16, v133
	v_and_b32_e32 v85, 0xffff0000, v133
	v_pk_add_f32 v[80:81], v[66:67], v[82:83]
	v_mul_f32_e32 v66, v71, v71
	v_mul_f32_e32 v67, v73, v73
	v_pk_add_f32 v[78:79], v[68:69], v[84:85]
	v_fmac_f32_e32 v66, v70, v70
	v_fmac_f32_e32 v67, v72, v72
	v_add_f32_e32 v66, v66, v67
	v_mul_f32_e32 v67, v81, v81
	v_mul_f32_e32 v68, v79, v79
	v_fmac_f32_e32 v67, v80, v80
	v_fmac_f32_e32 v68, v78, v78
	v_add_f32_e32 v67, v67, v68
	v_add_f32_e32 v66, v66, v67
	v_add_f32_e32 v69, v86, v66
	ds_bpermute_b32 v84, v203, v69
	v_lshl_add_u64 v[66:67], s[46:47], 0, v[184:185]
	v_lshl_add_u64 v[82:83], v[176:177], 1, v[66:67]
	v_cvt_pk_bf16_f32 v68, v70, v71
	v_cvt_pk_bf16_f32 v70, v80, v81
	s_waitcnt lgkmcnt(0)
	v_add_f32_e32 v66, v69, v84
	ds_bpermute_b32 v67, v202, v66
	v_cvt_pk_bf16_f32 v69, v72, v73
	v_cvt_pk_bf16_f32 v71, v78, v79
	global_store_dwordx4 v[82:83], v[74:77], off sc1
	global_store_dwordx4 v[82:83], v[68:71], off offset:256 sc1
	s_and_saveexec_b64 s[30:31], s[42:43]
	s_cbranch_execz .LBB0_853
	s_waitcnt lgkmcnt(0)
	v_add_f32_e32 v68, v66, v67
	v_lshlrev_b64 v[66:67], 7, v[182:183]
	v_lshl_add_u64 v[66:67], s[14:15], 0, v[66:67]
	v_lshl_add_u64 v[66:67], s[0:1], 2, v[66:67]
	s_lshl_b32 s34, s55, 2
	v_lshl_add_u64 v[66:67], v[66:67], 0, s[34:35]
	global_store_dword v[66:67], v68, off sc1
.LBB0_853:
	s_or_b64 exec, exec, s[30:31]
	v_add_u32_e32 v102, 0x80, v178
	v_ashrrev_i32_e32 v103, 31, v102
	v_lshlrev_b64 v[112:113], 12, v[102:103]
	s_waitcnt lgkmcnt(0)
	v_lshl_add_u64 v[66:67], v[180:181], 0, v[112:113]
	global_load_dwordx4 v[104:107], v[66:67], off
	global_load_dwordx4 v[108:111], v[66:67], off offset:256
	v_add_u32_e32 v98, 0x90, v178
	v_ashrrev_i32_e32 v99, 31, v98
	v_add_u32_e32 v94, 0xa0, v178
	v_lshlrev_b64 v[100:101], 12, v[98:99]
	v_ashrrev_i32_e32 v95, 31, v94
	v_add_u32_e32 v90, 0xb0, v178
	v_lshl_add_u64 v[66:67], v[180:181], 0, v[100:101]
	v_lshlrev_b64 v[96:97], 12, v[94:95]
	v_ashrrev_i32_e32 v91, 31, v90
	global_load_dwordx4 v[86:89], v[66:67], off
	global_load_dwordx4 v[82:85], v[66:67], off offset:256
	v_lshl_add_u64 v[66:67], v[180:181], 0, v[96:97]
	v_lshlrev_b64 v[92:93], 12, v[90:91]
	global_load_dwordx4 v[78:81], v[66:67], off
	global_load_dwordx4 v[74:77], v[66:67], off offset:256
	v_lshl_add_u64 v[66:67], v[180:181], 0, v[92:93]
	global_load_dwordx4 v[70:73], v[66:67], off
	s_nop 0
	global_load_dwordx4 v[66:69], v[66:67], off offset:256
	v_lshl_add_u64 v[112:113], s[46:47], 0, v[112:113]
	v_lshl_add_u64 v[112:113], v[176:177], 1, v[112:113]
	s_waitcnt vmcnt(7)
	v_lshlrev_b32_e32 v114, 16, v104
	v_and_b32_e32 v115, 0xffff0000, v104
	v_lshlrev_b32_e32 v104, 16, v105
	v_and_b32_e32 v105, 0xffff0000, v105
	v_lshlrev_b32_e32 v116, 16, v106
	v_and_b32_e32 v117, 0xffff0000, v106
	v_lshlrev_b32_e32 v106, 16, v107
	v_and_b32_e32 v107, 0xffff0000, v107
	v_pk_add_f32 v[64:65], v[64:65], v[104:105]
	v_pk_add_f32 v[62:63], v[62:63], v[114:115]
	v_pk_add_f32 v[104:105], v[60:61], v[106:107]
	v_pk_add_f32 v[106:107], v[58:59], v[116:117]
	v_cvt_pk_bf16_f32 v58, v62, v63
	v_cvt_pk_bf16_f32 v59, v64, v65
	v_cvt_pk_bf16_f32 v60, v106, v107
	v_cvt_pk_bf16_f32 v61, v104, v105
	global_store_dwordx4 v[112:113], v[58:61], off sc1
	s_nop 1
	v_mul_f32_e32 v58, v63, v63
	v_mul_f32_e32 v59, v65, v65
	v_fmac_f32_e32 v58, v62, v62
	v_fmac_f32_e32 v59, v64, v64
	v_add_f32_e32 v58, v58, v59
	v_mul_f32_e32 v59, v107, v107
	v_mul_f32_e32 v60, v105, v105
	v_fmac_f32_e32 v59, v106, v106
	v_fmac_f32_e32 v60, v104, v104
	v_add_f32_e32 v59, v59, v60
	v_add_f32_e32 v104, v58, v59
	s_waitcnt vmcnt(7)
	v_lshlrev_b32_e32 v58, 16, v108
	v_and_b32_e32 v59, 0xffff0000, v108
	v_lshlrev_b32_e32 v60, 16, v109
	v_and_b32_e32 v61, 0xffff0000, v109
	v_lshlrev_b32_e32 v62, 16, v110
	v_and_b32_e32 v63, 0xffff0000, v110
	v_lshlrev_b32_e32 v64, 16, v111
	v_and_b32_e32 v65, 0xffff0000, v111
	v_pk_add_f32 v[56:57], v[56:57], v[60:61]
	v_pk_add_f32 v[54:55], v[54:55], v[58:59]
	v_pk_add_f32 v[58:59], v[52:53], v[64:65]
	v_pk_add_f32 v[60:61], v[50:51], v[62:63]
	v_cvt_pk_bf16_f32 v50, v54, v55
	v_cvt_pk_bf16_f32 v51, v56, v57
	v_cvt_pk_bf16_f32 v52, v60, v61
	v_cvt_pk_bf16_f32 v53, v58, v59
	global_store_dwordx4 v[112:113], v[50:53], off offset:256 sc1
	s_nop 1
	v_mul_f32_e32 v50, v55, v55
	v_mul_f32_e32 v51, v57, v57
	v_fmac_f32_e32 v50, v54, v54
	v_fmac_f32_e32 v51, v56, v56
	v_add_f32_e32 v50, v50, v51
	v_mul_f32_e32 v51, v61, v61
	v_mul_f32_e32 v52, v59, v59
	v_fmac_f32_e32 v51, v60, v60
	v_fmac_f32_e32 v52, v58, v58
	v_add_f32_e32 v51, v51, v52
	v_add_f32_e32 v50, v50, v51
	v_add_f32_e32 v50, v104, v50
	ds_bpermute_b32 v51, v203, v50
	s_waitcnt lgkmcnt(0)
	v_add_f32_e32 v50, v50, v51
	ds_bpermute_b32 v51, v202, v50
	s_and_saveexec_b64 s[30:31], s[42:43]
	s_cbranch_execz .LBB0_855
	s_waitcnt lgkmcnt(0)
	v_add_f32_e32 v52, v50, v51
	v_lshlrev_b64 v[50:51], 7, v[102:103]
	v_lshl_add_u64 v[50:51], s[14:15], 0, v[50:51]
	v_lshl_add_u64 v[50:51], s[0:1], 2, v[50:51]
	s_lshl_b32 s34, s55, 2
	v_lshl_add_u64 v[50:51], v[50:51], 0, s[34:35]
	global_store_dword v[50:51], v52, off sc1
; __device__ __forceinline__ unsigned cvt_pk_bf16(float lo, float hi) { f32x2 v = {lo, hi}; bf16x2_t b = __builtin_convertvector(v, bf16x2_t); return __builtin_bit_cast(unsigned, b); }
;     __device__ __forceinline__ void operator()(const f32x4 (&acc)[2][2][4][2], const Unit& u, int wr, int wc, int fr, int fq) const {
;     ...
;             for (int m = 0; m < 4; ++m) { const int row = u.pm * BM + ai * HALF + wr * 64 + m * 16 + fr; const size_t off = (size_t)row * 2048 + col0; float sq = 0.f;
; #pragma unroll
;                 for (int bj = 0; bj < 2; ++bj) { const size_t o2 = off + bj * HALF; const u32x4 xw = xr[m][bj];
;                     f32x4 x0, x1; x0[0] = __uint_as_float(xw.x << 16); x0[1] = __uint_as_float(xw.x & 0xffff0000u); x0[2] = __uint_as_float(xw.y << 16); x0[3] = __uint_as_float(xw.y & 0xffff0000u);
;                     x1[0] = __uint_as_float(xw.z << 16); x1[1] = __uint_as_float(xw.z & 0xffff0000u); x1[2] = __uint_as_float(xw.w << 16); x1[3] = __uint_as_float(xw.w & 0xffff0000u);
;                     x0 = x0 + acc[ai][bj][m][0]; x1 = x1 + acc[ai][bj][m][1];
;                     if (FINAL) { *(f32x4*)(out + o2) = x0; *(f32x4*)(out + o2 + 4) = x1; }
;                     else { u32x4 w; w.x = cvt_pk_bf16(x0[0], x0[1]); w.y = cvt_pk_bf16(x0[2], x0[3]); w.z = cvt_pk_bf16(x1[0], x1[1]); w.w = cvt_pk_bf16(x1[2], x1[3]); *(u32x4*)(xb + o2) = w; }
;                     sq += ((x0[0] * x0[0] + x0[1] * x0[1]) + (x0[2] * x0[2] + x0[3] * x0[3])) + ((x1[0] * x1[0] + x1[1] * x1[1]) + (x1[2] * x1[2] + x1[3] * x1[3])); }
;                 sq += __shfl_xor(sq, 16); sq += __shfl_xor(sq, 32);
;                 if (!FINAL && fq == 0) ssn[(size_t)row * 32 + u.pn * 4 + wc] = sq; }
.LBB0_855:
	s_or_b64 exec, exec, s[30:31]
	s_waitcnt vmcnt(7)
	v_lshlrev_b32_e32 v50, 16, v86
	s_waitcnt lgkmcnt(0)
	v_and_b32_e32 v51, 0xffff0000, v86
	v_lshlrev_b32_e32 v52, 16, v87
	v_and_b32_e32 v53, 0xffff0000, v87
	v_lshlrev_b32_e32 v54, 16, v88
	v_and_b32_e32 v55, 0xffff0000, v88
	v_pk_add_f32 v[46:47], v[46:47], v[50:51]
	v_pk_add_f32 v[48:49], v[48:49], v[52:53]
	v_pk_add_f32 v[52:53], v[42:43], v[54:55]
	v_cvt_pk_bf16_f32 v42, v46, v47
	v_mul_f32_e32 v47, v47, v47
	v_lshlrev_b32_e32 v56, 16, v89
	v_and_b32_e32 v57, 0xffff0000, v89
	v_fmac_f32_e32 v47, v46, v46
	v_mul_f32_e32 v46, v49, v49
	v_pk_add_f32 v[50:51], v[44:45], v[56:57]
	v_fmac_f32_e32 v46, v48, v48
	v_cvt_pk_bf16_f32 v43, v48, v49
	v_add_f32_e32 v46, v47, v46
	v_mul_f32_e32 v47, v53, v53
	v_mul_f32_e32 v48, v51, v51
	v_fmac_f32_e32 v47, v52, v52
	v_fmac_f32_e32 v48, v50, v50
	v_add_f32_e32 v47, v47, v48
	v_add_f32_e32 v54, v46, v47
	s_waitcnt vmcnt(6)
	v_lshlrev_b32_e32 v46, 16, v82
	v_and_b32_e32 v47, 0xffff0000, v82
	v_lshlrev_b32_e32 v48, 16, v83
	v_and_b32_e32 v49, 0xffff0000, v83
	v_cvt_pk_bf16_f32 v45, v50, v51
	v_lshlrev_b32_e32 v50, 16, v84
	v_and_b32_e32 v51, 0xffff0000, v84
	v_pk_add_f32 v[40:41], v[40:41], v[48:49]
	v_pk_add_f32 v[38:39], v[38:39], v[46:47]
	v_cvt_pk_bf16_f32 v44, v52, v53
	v_lshlrev_b32_e32 v52, 16, v85
	v_and_b32_e32 v53, 0xffff0000, v85
	v_pk_add_f32 v[48:49], v[34:35], v[50:51]
	v_mul_f32_e32 v34, v39, v39
	v_mul_f32_e32 v35, v41, v41
	v_pk_add_f32 v[46:47], v[36:37], v[52:53]
	v_fmac_f32_e32 v34, v38, v38
	v_fmac_f32_e32 v35, v40, v40
	v_add_f32_e32 v34, v34, v35
	v_mul_f32_e32 v35, v49, v49
	v_mul_f32_e32 v36, v47, v47
	v_fmac_f32_e32 v35, v48, v48
	v_fmac_f32_e32 v36, v46, v46
	v_add_f32_e32 v35, v35, v36
	v_add_f32_e32 v34, v34, v35
	v_add_f32_e32 v37, v54, v34
	ds_bpermute_b32 v52, v203, v37
	v_lshl_add_u64 v[34:35], s[46:47], 0, v[100:101]
	v_lshl_add_u64 v[50:51], v[176:177], 1, v[34:35]
	v_cvt_pk_bf16_f32 v36, v38, v39
	v_cvt_pk_bf16_f32 v38, v48, v49
	s_waitcnt lgkmcnt(0)
	v_add_f32_e32 v34, v37, v52
	ds_bpermute_b32 v35, v202, v34
	v_cvt_pk_bf16_f32 v37, v40, v41
	v_cvt_pk_bf16_f32 v39, v46, v47
	global_store_dwordx4 v[50:51], v[42:45], off sc1
	global_store_dwordx4 v[50:51], v[36:39], off offset:256 sc1
	s_and_saveexec_b64 s[30:31], s[42:43]
	s_cbranch_execz .LBB0_857
	s_waitcnt lgkmcnt(0)
	v_add_f32_e32 v36, v34, v35
	v_lshlrev_b64 v[34:35], 7, v[98:99]
	v_lshl_add_u64 v[34:35], s[14:15], 0, v[34:35]
	v_lshl_add_u64 v[34:35], s[0:1], 2, v[34:35]
	s_lshl_b32 s34, s55, 2
	v_lshl_add_u64 v[34:35], v[34:35], 0, s[34:35]
	global_store_dword v[34:35], v36, off sc1
; __device__ __forceinline__ unsigned cvt_pk_bf16(float lo, float hi) { f32x2 v = {lo, hi}; bf16x2_t b = __builtin_convertvector(v, bf16x2_t); return __builtin_bit_cast(unsigned, b); }
;     __device__ __forceinline__ void operator()(const f32x4 (&acc)[2][2][4][2], const Unit& u, int wr, int wc, int fr, int fq) const {
;     ...
;             for (int m = 0; m < 4; ++m) { const int row = u.pm * BM + ai * HALF + wr * 64 + m * 16 + fr; const size_t off = (size_t)row * 2048 + col0; float sq = 0.f;
; #pragma unroll
;                 for (int bj = 0; bj < 2; ++bj) { const size_t o2 = off + bj * HALF; const u32x4 xw = xr[m][bj];
;                     f32x4 x0, x1; x0[0] = __uint_as_float(xw.x << 16); x0[1] = __uint_as_float(xw.x & 0xffff0000u); x0[2] = __uint_as_float(xw.y << 16); x0[3] = __uint_as_float(xw.y & 0xffff0000u);
;                     x1[0] = __uint_as_float(xw.z << 16); x1[1] = __uint_as_float(xw.z & 0xffff0000u); x1[2] = __uint_as_float(xw.w << 16); x1[3] = __uint_as_float(xw.w & 0xffff0000u);
;                     x0 = x0 + acc[ai][bj][m][0]; x1 = x1 + acc[ai][bj][m][1];
;                     if (FINAL) { *(f32x4*)(out + o2) = x0; *(f32x4*)(out + o2 + 4) = x1; }
;                     else { u32x4 w; w.x = cvt_pk_bf16(x0[0], x0[1]); w.y = cvt_pk_bf16(x0[2], x0[3]); w.z = cvt_pk_bf16(x1[0], x1[1]); w.w = cvt_pk_bf16(x1[2], x1[3]); *(u32x4*)(xb + o2) = w; }
;                     sq += ((x0[0] * x0[0] + x0[1] * x0[1]) + (x0[2] * x0[2] + x0[3] * x0[3])) + ((x1[0] * x1[0] + x1[1] * x1[1]) + (x1[2] * x1[2] + x1[3] * x1[3])); }
;                 sq += __shfl_xor(sq, 16); sq += __shfl_xor(sq, 32);
;                 if (!FINAL && fq == 0) ssn[(size_t)row * 32 + u.pn * 4 + wc] = sq; }
.LBB0_857:
	s_or_b64 exec, exec, s[30:31]
	s_waitcnt vmcnt(7)
	v_lshlrev_b32_e32 v34, 16, v78
	s_waitcnt lgkmcnt(0)
	v_and_b32_e32 v35, 0xffff0000, v78
	v_lshlrev_b32_e32 v36, 16, v79
	v_and_b32_e32 v37, 0xffff0000, v79
	v_lshlrev_b32_e32 v38, 16, v80
	v_and_b32_e32 v39, 0xffff0000, v80
	v_pk_add_f32 v[30:31], v[30:31], v[34:35]
	v_pk_add_f32 v[32:33], v[32:33], v[36:37]
	v_pk_add_f32 v[36:37], v[26:27], v[38:39]
	v_cvt_pk_bf16_f32 v26, v30, v31
	v_mul_f32_e32 v31, v31, v31
	v_lshlrev_b32_e32 v40, 16, v81
	v_and_b32_e32 v41, 0xffff0000, v81
	v_fmac_f32_e32 v31, v30, v30
	v_mul_f32_e32 v30, v33, v33
	v_pk_add_f32 v[34:35], v[28:29], v[40:41]
	v_fmac_f32_e32 v30, v32, v32
	v_cvt_pk_bf16_f32 v27, v32, v33
	v_add_f32_e32 v30, v31, v30
	v_mul_f32_e32 v31, v37, v37
	v_mul_f32_e32 v32, v35, v35
	v_fmac_f32_e32 v31, v36, v36
	v_fmac_f32_e32 v32, v34, v34
	v_add_f32_e32 v31, v31, v32
	v_add_f32_e32 v38, v30, v31
	s_waitcnt vmcnt(6)
	v_lshlrev_b32_e32 v30, 16, v74
	v_and_b32_e32 v31, 0xffff0000, v74
	v_lshlrev_b32_e32 v32, 16, v75
	v_and_b32_e32 v33, 0xffff0000, v75
	v_cvt_pk_bf16_f32 v29, v34, v35
	v_lshlrev_b32_e32 v34, 16, v76
	v_and_b32_e32 v35, 0xffff0000, v76
	v_pk_add_f32 v[24:25], v[24:25], v[32:33]
	v_pk_add_f32 v[22:23], v[22:23], v[30:31]
	v_cvt_pk_bf16_f32 v28, v36, v37
	v_lshlrev_b32_e32 v36, 16, v77
	v_and_b32_e32 v37, 0xffff0000, v77
	v_pk_add_f32 v[32:33], v[18:19], v[34:35]
	v_mul_f32_e32 v18, v23, v23
	v_mul_f32_e32 v19, v25, v25
	v_pk_add_f32 v[30:31], v[20:21], v[36:37]
	v_fmac_f32_e32 v18, v22, v22
	v_fmac_f32_e32 v19, v24, v24
	v_add_f32_e32 v18, v18, v19
	v_mul_f32_e32 v19, v33, v33
	v_mul_f32_e32 v20, v31, v31
	v_fmac_f32_e32 v19, v32, v32
	v_fmac_f32_e32 v20, v30, v30
	v_add_f32_e32 v19, v19, v20
	v_add_f32_e32 v18, v18, v19
	v_add_f32_e32 v21, v38, v18
	ds_bpermute_b32 v36, v203, v21
	v_lshl_add_u64 v[18:19], s[46:47], 0, v[96:97]
	v_lshl_add_u64 v[34:35], v[176:177], 1, v[18:19]
	v_cvt_pk_bf16_f32 v20, v22, v23
	v_cvt_pk_bf16_f32 v22, v32, v33
	s_waitcnt lgkmcnt(0)
	v_add_f32_e32 v18, v21, v36
	ds_bpermute_b32 v19, v202, v18
	v_cvt_pk_bf16_f32 v21, v24, v25
	v_cvt_pk_bf16_f32 v23, v30, v31
	global_store_dwordx4 v[34:35], v[26:29], off sc1
	global_store_dwordx4 v[34:35], v[20:23], off offset:256 sc1
	s_and_saveexec_b64 s[30:31], s[42:43]
	s_cbranch_execz .LBB0_859
	s_waitcnt lgkmcnt(0)
	v_add_f32_e32 v20, v18, v19
	v_lshlrev_b64 v[18:19], 7, v[94:95]
	v_lshl_add_u64 v[18:19], s[14:15], 0, v[18:19]
	v_lshl_add_u64 v[18:19], s[0:1], 2, v[18:19]
	s_lshl_b32 s34, s55, 2
	v_lshl_add_u64 v[18:19], v[18:19], 0, s[34:35]
	global_store_dword v[18:19], v20, off sc1
.LBB0_859:
	s_or_b64 exec, exec, s[30:31]
	s_waitcnt vmcnt(7)
	v_lshlrev_b32_e32 v18, 16, v70
	s_waitcnt lgkmcnt(0)
	v_and_b32_e32 v19, 0xffff0000, v70
	v_lshlrev_b32_e32 v20, 16, v71
	v_and_b32_e32 v21, 0xffff0000, v71
	v_lshlrev_b32_e32 v22, 16, v72
	v_and_b32_e32 v23, 0xffff0000, v72
	v_pk_add_f32 v[14:15], v[14:15], v[18:19]
	v_pk_add_f32 v[16:17], v[16:17], v[20:21]
	v_pk_add_f32 v[20:21], v[10:11], v[22:23]
	v_cvt_pk_bf16_f32 v10, v14, v15
	v_mul_f32_e32 v15, v15, v15
	v_lshlrev_b32_e32 v24, 16, v73
	v_and_b32_e32 v25, 0xffff0000, v73
	v_fmac_f32_e32 v15, v14, v14
	v_mul_f32_e32 v14, v17, v17
	v_pk_add_f32 v[18:19], v[12:13], v[24:25]
	v_fmac_f32_e32 v14, v16, v16
	v_cvt_pk_bf16_f32 v11, v16, v17
	v_add_f32_e32 v14, v15, v14
	v_mul_f32_e32 v15, v21, v21
	v_mul_f32_e32 v16, v19, v19
	v_fmac_f32_e32 v15, v20, v20
	v_fmac_f32_e32 v16, v18, v18
	v_add_f32_e32 v15, v15, v16
	v_add_f32_e32 v22, v14, v15
	s_waitcnt vmcnt(6)
	v_lshlrev_b32_e32 v14, 16, v66
	v_and_b32_e32 v15, 0xffff0000, v66
	v_lshlrev_b32_e32 v16, 16, v67
	v_and_b32_e32 v17, 0xffff0000, v67
	v_cvt_pk_bf16_f32 v13, v18, v19
	v_lshlrev_b32_e32 v18, 16, v68
	v_and_b32_e32 v19, 0xffff0000, v68
	v_pk_add_f32 v[8:9], v[8:9], v[16:17]
	v_pk_add_f32 v[6:7], v[6:7], v[14:15]
	v_cvt_pk_bf16_f32 v12, v20, v21
	v_lshlrev_b32_e32 v20, 16, v69
	v_and_b32_e32 v21, 0xffff0000, v69
	v_pk_add_f32 v[16:17], v[2:3], v[18:19]
	v_mul_f32_e32 v2, v7, v7
	v_mul_f32_e32 v3, v9, v9
	v_pk_add_f32 v[14:15], v[4:5], v[20:21]
	v_fmac_f32_e32 v2, v6, v6
	v_fmac_f32_e32 v3, v8, v8
	v_add_f32_e32 v2, v2, v3
	v_mul_f32_e32 v3, v17, v17
	v_mul_f32_e32 v4, v15, v15
	v_fmac_f32_e32 v3, v16, v16
	v_fmac_f32_e32 v4, v14, v14
	v_add_f32_e32 v3, v3, v4
	v_add_f32_e32 v2, v2, v3
	v_add_f32_e32 v5, v22, v2
	ds_bpermute_b32 v20, v203, v5
	v_lshl_add_u64 v[2:3], s[46:47], 0, v[92:93]
	v_lshl_add_u64 v[18:19], v[176:177], 1, v[2:3]
	v_cvt_pk_bf16_f32 v4, v6, v7
	v_cvt_pk_bf16_f32 v6, v16, v17
	s_waitcnt lgkmcnt(0)
	v_add_f32_e32 v2, v5, v20
	ds_bpermute_b32 v3, v202, v2
	v_cvt_pk_bf16_f32 v5, v8, v9
	v_cvt_pk_bf16_f32 v7, v14, v15
	global_store_dwordx4 v[18:19], v[10:13], off sc1
	global_store_dwordx4 v[18:19], v[4:7], off offset:256 sc1
	s_and_saveexec_b64 s[30:31], s[42:43]
	s_cbranch_execz .LBB0_861
	s_waitcnt lgkmcnt(0)
	v_add_f32_e32 v4, v2, v3
	v_lshlrev_b64 v[2:3], 7, v[90:91]
	v_lshl_add_u64 v[2:3], s[14:15], 0, v[2:3]
	v_lshl_add_u64 v[2:3], s[0:1], 2, v[2:3]
	s_lshl_b32 s34, s55, 2
	v_lshl_add_u64 v[2:3], v[2:3], 0, s[34:35]
	global_store_dword v[2:3], v4, off sc1

; __device__ __forceinline__ unsigned cvt_pk_bf16(float lo, float hi) { f32x2 v = {lo, hi}; bf16x2_t b = __builtin_convertvector(v, bf16x2_t); return __builtin_bit_cast(unsigned, b); }
;     __device__ __forceinline__ void operator()(const f32x4 (&acc)[2][2][4][2], const Unit& u, int wr, int wc, int fr, int fq) const {
;     ...
;         for (int ai = 0; ai < 2; ++ai) {
;             u32x4 xr[4][2];
; #pragma unroll
;             for (int m = 0; m < 4; ++m)
; #pragma unroll
;                 for (int bj = 0; bj < 2; ++bj) xr[m][bj] = *(const u32x4*)(xb + (size_t)(u.pm * BM + ai * HALF + wr * 64 + m * 16 + fr) * 2048 + col0 + bj * HALF);
; #pragma unroll
;             for (int m = 0; m < 4; ++m) { const int row = u.pm * BM + ai * HALF + wr * 64 + m * 16 + fr; const size_t off = (size_t)row * 2048 + col0; float sq = 0.f;
; #pragma unroll
;                 for (int bj = 0; bj < 2; ++bj) { const size_t o2 = off + bj * HALF; const u32x4 xw = xr[m][bj];
;                     f32x4 x0, x1; x0[0] = __uint_as_float(xw.x << 16); x0[1] = __uint_as_float(xw.x & 0xffff0000u); x0[2] = __uint_as_float(xw.y << 16); x0[3] = __uint_as_float(xw.y & 0xffff0000u);
;                     x1[0] = __uint_as_float(xw.z << 16); x1[1] = __uint_as_float(xw.z & 0xffff0000u); x1[2] = __uint_as_float(xw.w << 16); x1[3] = __uint_as_float(xw.w & 0xffff0000u);
;                     x0 = x0 + acc[ai][bj][m][0]; x1 = x1 + acc[ai][bj][m][1];
;                     if (FINAL) { *(f32x4*)(out + o2) = x0; *(f32x4*)(out + o2 + 4) = x1; }
;                     else { u32x4 w; w.x = cvt_pk_bf16(x0[0], x0[1]); w.y = cvt_pk_bf16(x0[2], x0[3]); w.z = cvt_pk_bf16(x1[0], x1[1]); w.w = cvt_pk_bf16(x1[2], x1[3]); *(u32x4*)(xb + o2) = w; }
;                     sq += ((x0[0] * x0[0] + x0[1] * x0[1]) + (x0[2] * x0[2] + x0[3] * x0[3])) + ((x1[0] * x1[0] + x1[1] * x1[1]) + (x1[2] * x1[2] + x1[3] * x1[3])); }
.LBB0_883:
	v_lshl_or_b32 v190, s52, 8, v179
	v_lshl_add_u32 v170, s53, 8, v161
	v_ashrrev_i32_e32 v191, 31, v190
	v_ashrrev_i32_e32 v171, 31, v170
	v_lshl_add_u64 v[168:169], v[190:191], 1, s[46:47]
	v_lshlrev_b64 v[130:131], 12, v[170:171]
	v_lshl_add_u64 v[130:131], v[168:169], 0, v[130:131]
	global_load_dwordx4 v[162:165], v[130:131], off
	global_load_dwordx4 v[182:185], v[130:131], off offset:256
	v_or_b32_e32 v176, 16, v170
	v_ashrrev_i32_e32 v177, 31, v176
	v_lshlrev_b64 v[130:131], 12, v[176:177]
	v_lshl_add_u64 v[130:131], v[168:169], 0, v[130:131]
	global_load_dwordx4 v[186:189], v[130:131], off
	global_load_dwordx4 v[146:149], v[130:131], off offset:256
	v_or_b32_e32 v174, 32, v170
	v_ashrrev_i32_e32 v175, 31, v174
	v_lshlrev_b64 v[130:131], 12, v[174:175]
	v_lshl_add_u64 v[130:131], v[168:169], 0, v[130:131]
	global_load_dwordx4 v[142:145], v[130:131], off
	global_load_dwordx4 v[138:141], v[130:131], off offset:256
	v_or_b32_e32 v172, 48, v170
	v_ashrrev_i32_e32 v173, 31, v172
	v_lshlrev_b64 v[130:131], 12, v[172:173]
	v_lshl_add_u64 v[130:131], v[168:169], 0, v[130:131]
	global_load_dwordx4 v[134:137], v[130:131], off
	s_nop 0
	global_load_dwordx4 v[130:133], v[130:131], off offset:256
	s_mov_b64 s[0:1], -1
	s_andn2_b64 vcc, exec, s[40:41]
	s_mov_b64 s[60:61], s[90:91]
	s_mov_b64 s[62:63], s[88:89]
	s_waitcnt vmcnt(0)
	v_lshlrev_b32_e32 v192, 16, v162
	v_and_b32_e32 v193, 0xffff0000, v162
	v_lshlrev_b32_e32 v162, 16, v163
	v_and_b32_e32 v163, 0xffff0000, v163
	v_lshlrev_b32_e32 v200, 16, v164
	v_and_b32_e32 v201, 0xffff0000, v164
	v_lshlrev_b32_e32 v164, 16, v165
	v_and_b32_e32 v165, 0xffff0000, v165
	v_pk_add_f32 v[128:129], v[128:129], v[162:163]
	v_pk_add_f32 v[162:163], v[122:123], v[200:201]
	v_lshlrev_b64 v[122:123], 13, v[170:171]
	v_pk_add_f32 v[164:165], v[124:125], v[164:165]
	v_lshl_add_u64 v[124:125], s[4:5], 0, v[122:123]
	v_lshlrev_b64 v[122:123], 2, v[190:191]
	v_pk_add_f32 v[126:127], v[126:127], v[192:193]
	v_lshl_add_u64 v[124:125], v[124:125], 0, v[122:123]
	global_store_dwordx4 v[124:125], v[126:129], off sc1
	global_store_dwordx4 v[124:125], v[162:165], off offset:16 sc1
	s_nop 0
	v_lshlrev_b32_e32 v126, 16, v182
	v_and_b32_e32 v127, 0xffff0000, v182
	v_lshlrev_b32_e32 v128, 16, v183
	v_and_b32_e32 v129, 0xffff0000, v183
	v_lshlrev_b32_e32 v162, 16, v184
	v_and_b32_e32 v163, 0xffff0000, v184
	v_lshlrev_b32_e32 v164, 16, v185
	v_and_b32_e32 v165, 0xffff0000, v185
	v_pk_add_f32 v[112:113], v[112:113], v[128:129]
	v_pk_add_f32 v[110:111], v[110:111], v[126:127]
	v_pk_add_f32 v[108:109], v[108:109], v[164:165]
	v_pk_add_f32 v[106:107], v[106:107], v[162:163]
	global_store_dwordx4 v[124:125], v[110:113], off offset:512 sc1
	global_store_dwordx4 v[124:125], v[106:109], off offset:528 sc1
	s_nop 0
	v_lshlrev_b32_e32 v110, 16, v188
	v_and_b32_e32 v111, 0xffff0000, v188
	v_pk_add_f32 v[110:111], v[114:115], v[110:111]
	v_lshlrev_b64 v[114:115], 13, v[176:177]
	v_lshlrev_b32_e32 v106, 16, v186
	v_and_b32_e32 v107, 0xffff0000, v186
	v_lshlrev_b32_e32 v108, 16, v187
	v_and_b32_e32 v109, 0xffff0000, v187
	v_lshl_add_u64 v[114:115], s[4:5], 0, v[114:115]
	v_lshlrev_b32_e32 v112, 16, v189
	v_and_b32_e32 v113, 0xffff0000, v189
	v_pk_add_f32 v[108:109], v[120:121], v[108:109]
	v_pk_add_f32 v[106:107], v[118:119], v[106:107]
	v_lshl_add_u64 v[114:115], v[114:115], 0, v[122:123]
	v_pk_add_f32 v[112:113], v[116:117], v[112:113]
	global_store_dwordx4 v[114:115], v[106:109], off sc1
	global_store_dwordx4 v[114:115], v[110:113], off offset:16 sc1
	s_nop 0
	v_lshlrev_b32_e32 v106, 16, v146
	v_and_b32_e32 v107, 0xffff0000, v146
	v_lshlrev_b32_e32 v108, 16, v147
	v_and_b32_e32 v109, 0xffff0000, v147
	v_lshlrev_b32_e32 v110, 16, v148
	v_and_b32_e32 v111, 0xffff0000, v148
	v_lshlrev_b32_e32 v112, 16, v149
	v_and_b32_e32 v113, 0xffff0000, v149
	v_pk_add_f32 v[104:105], v[104:105], v[108:109]
	v_pk_add_f32 v[102:103], v[102:103], v[106:107]
	v_pk_add_f32 v[98:99], v[98:99], v[110:111]
	v_pk_add_f32 v[100:101], v[100:101], v[112:113]
	global_store_dwordx4 v[114:115], v[102:105], off offset:512 sc1
	global_store_dwordx4 v[114:115], v[98:101], off offset:528 sc1
	s_nop 0
	v_lshlrev_b32_e32 v102, 16, v144
	v_lshlrev_b32_e32 v98, 16, v142
	v_and_b32_e32 v99, 0xffff0000, v142
	v_pk_add_f32 v[94:95], v[94:95], v[98:99]
	v_lshlrev_b64 v[98:99], 13, v[174:175]
	v_lshlrev_b32_e32 v100, 16, v143
	v_and_b32_e32 v101, 0xffff0000, v143
	v_and_b32_e32 v103, 0xffff0000, v144
	v_lshlrev_b32_e32 v104, 16, v145
	v_and_b32_e32 v105, 0xffff0000, v145
	v_lshl_add_u64 v[98:99], s[4:5], 0, v[98:99]
	v_pk_add_f32 v[96:97], v[96:97], v[100:101]
	v_pk_add_f32 v[92:93], v[92:93], v[104:105]
	v_pk_add_f32 v[90:91], v[90:91], v[102:103]
	v_lshl_add_u64 v[98:99], v[98:99], 0, v[122:123]
	global_store_dwordx4 v[98:99], v[94:97], off sc1
	global_store_dwordx4 v[98:99], v[90:93], off offset:16 sc1
	v_add_u32_e32 v100, 0x90, v170
	v_lshlrev_b32_e32 v94, 16, v140
	v_lshlrev_b32_e32 v90, 16, v138
	v_and_b32_e32 v91, 0xffff0000, v138
	v_lshlrev_b32_e32 v92, 16, v139
	v_and_b32_e32 v93, 0xffff0000, v139
	v_and_b32_e32 v95, 0xffff0000, v140
	v_lshlrev_b32_e32 v96, 16, v141
	v_and_b32_e32 v97, 0xffff0000, v141
	v_pk_add_f32 v[88:89], v[88:89], v[92:93]
	v_pk_add_f32 v[86:87], v[86:87], v[90:91]
	v_pk_add_f32 v[78:79], v[78:79], v[94:95]
	v_pk_add_f32 v[80:81], v[80:81], v[96:97]
	global_store_dwordx4 v[98:99], v[86:89], off offset:512 sc1
	global_store_dwordx4 v[98:99], v[78:81], off offset:528 sc1
	v_add_u32_e32 v98, 0x80, v170
	v_lshlrev_b32_e32 v86, 16, v136
	v_lshlrev_b32_e32 v78, 16, v134
	v_and_b32_e32 v79, 0xffff0000, v134
	v_pk_add_f32 v[78:79], v[82:83], v[78:79]
; __device__ __forceinline__ unsigned cvt_pk_bf16(float lo, float hi) { f32x2 v = {lo, hi}; bf16x2_t b = __builtin_convertvector(v, bf16x2_t); return __builtin_bit_cast(unsigned, b); }
;     __device__ __forceinline__ void operator()(const f32x4 (&acc)[2][2][4][2], const Unit& u, int wr, int wc, int fr, int fq) const {
;     ...
;         for (int ai = 0; ai < 2; ++ai) {
;             u32x4 xr[4][2];
; #pragma unroll
;             for (int m = 0; m < 4; ++m)
; #pragma unroll
;                 for (int bj = 0; bj < 2; ++bj) xr[m][bj] = *(const u32x4*)(xb + (size_t)(u.pm * BM + ai * HALF + wr * 64 + m * 16 + fr) * 2048 + col0 + bj * HALF);
; #pragma unroll
;             for (int m = 0; m < 4; ++m) { const int row = u.pm * BM + ai * HALF + wr * 64 + m * 16 + fr; const size_t off = (size_t)row * 2048 + col0; float sq = 0.f;
; #pragma unroll
;                 for (int bj = 0; bj < 2; ++bj) { const size_t o2 = off + bj * HALF; const u32x4 xw = xr[m][bj];
;                     f32x4 x0, x1; x0[0] = __uint_as_float(xw.x << 16); x0[1] = __uint_as_float(xw.x & 0xffff0000u); x0[2] = __uint_as_float(xw.y << 16); x0[3] = __uint_as_float(xw.y & 0xffff0000u);
;                     x1[0] = __uint_as_float(xw.z << 16); x1[1] = __uint_as_float(xw.z & 0xffff0000u); x1[2] = __uint_as_float(xw.w << 16); x1[3] = __uint_as_float(xw.w & 0xffff0000u);
;                     x0 = x0 + acc[ai][bj][m][0]; x1 = x1 + acc[ai][bj][m][1];
;                     if (FINAL) { *(f32x4*)(out + o2) = x0; *(f32x4*)(out + o2 + 4) = x1; }
;                     else { u32x4 w; w.x = cvt_pk_bf16(x0[0], x0[1]); w.y = cvt_pk_bf16(x0[2], x0[3]); w.z = cvt_pk_bf16(x1[0], x1[1]); w.w = cvt_pk_bf16(x1[2], x1[3]); *(u32x4*)(xb + o2) = w; }
;                     sq += ((x0[0] * x0[0] + x0[1] * x0[1]) + (x0[2] * x0[2] + x0[3] * x0[3])) + ((x1[0] * x1[0] + x1[1] * x1[1]) + (x1[2] * x1[2] + x1[3] * x1[3])); }
	v_lshlrev_b64 v[82:83], 13, v[172:173]
	v_lshlrev_b32_e32 v80, 16, v135
	v_and_b32_e32 v81, 0xffff0000, v135
	v_and_b32_e32 v87, 0xffff0000, v136
	v_lshlrev_b32_e32 v88, 16, v137
	v_and_b32_e32 v89, 0xffff0000, v137
	v_lshl_add_u64 v[82:83], s[4:5], 0, v[82:83]
	v_pk_add_f32 v[80:81], v[84:85], v[80:81]
	v_pk_add_f32 v[76:77], v[76:77], v[88:89]
	v_pk_add_f32 v[74:75], v[74:75], v[86:87]
	v_lshl_add_u64 v[82:83], v[82:83], 0, v[122:123]
	global_store_dwordx4 v[82:83], v[78:81], off sc1
	global_store_dwordx4 v[82:83], v[74:77], off offset:16 sc1
	v_ashrrev_i32_e32 v99, 31, v98
	v_lshlrev_b32_e32 v78, 16, v132
	v_lshlrev_b32_e32 v74, 16, v130
	v_and_b32_e32 v75, 0xffff0000, v130
	v_lshlrev_b32_e32 v76, 16, v131
	v_and_b32_e32 v77, 0xffff0000, v131
	v_and_b32_e32 v79, 0xffff0000, v132
	v_lshlrev_b32_e32 v80, 16, v133
	v_and_b32_e32 v81, 0xffff0000, v133
	v_pk_add_f32 v[72:73], v[72:73], v[76:77]
	v_pk_add_f32 v[70:71], v[70:71], v[74:75]
	v_pk_add_f32 v[66:67], v[66:67], v[78:79]
	v_pk_add_f32 v[68:69], v[68:69], v[80:81]
	global_store_dwordx4 v[82:83], v[70:73], off offset:512 sc1
	global_store_dwordx4 v[82:83], v[66:69], off offset:528 sc1
	v_ashrrev_i32_e32 v101, 31, v100
	v_add_u32_e32 v102, 0xa0, v170
	v_lshlrev_b64 v[66:67], 12, v[98:99]
	v_lshl_add_u64 v[66:67], v[168:169], 0, v[66:67]
	global_load_dwordx4 v[70:73], v[66:67], off
	global_load_dwordx4 v[74:77], v[66:67], off offset:256
	v_lshlrev_b64 v[66:67], 12, v[100:101]
	v_lshl_add_u64 v[66:67], v[168:169], 0, v[66:67]
	global_load_dwordx4 v[78:81], v[66:67], off
	global_load_dwordx4 v[82:85], v[66:67], off offset:256
	v_ashrrev_i32_e32 v103, 31, v102
	v_lshlrev_b64 v[66:67], 12, v[102:103]
	v_lshl_add_u64 v[66:67], v[168:169], 0, v[66:67]
	global_load_dwordx4 v[86:89], v[66:67], off
	global_load_dwordx4 v[90:93], v[66:67], off offset:256
	v_add_u32_e32 v104, 0xb0, v170
	v_ashrrev_i32_e32 v105, 31, v104
	v_lshlrev_b64 v[66:67], 12, v[104:105]
	v_lshl_add_u64 v[66:67], v[168:169], 0, v[66:67]
	global_load_dwordx4 v[94:97], v[66:67], off
	s_nop 0
	global_load_dwordx4 v[66:69], v[66:67], off offset:256
	s_waitcnt vmcnt(7)
	v_lshlrev_b32_e32 v106, 16, v70
	v_and_b32_e32 v107, 0xffff0000, v70
	v_lshlrev_b32_e32 v70, 16, v71
	v_and_b32_e32 v71, 0xffff0000, v71
	v_pk_add_f32 v[64:65], v[64:65], v[70:71]
	v_lshlrev_b64 v[70:71], 13, v[98:99]
	v_lshlrev_b32_e32 v108, 16, v72
	v_and_b32_e32 v109, 0xffff0000, v72
	v_lshlrev_b32_e32 v72, 16, v73
	v_and_b32_e32 v73, 0xffff0000, v73
	v_lshl_add_u64 v[70:71], s[4:5], 0, v[70:71]
	v_pk_add_f32 v[62:63], v[62:63], v[106:107]
	v_pk_add_f32 v[60:61], v[60:61], v[72:73]
	v_pk_add_f32 v[58:59], v[58:59], v[108:109]
	v_lshl_add_u64 v[70:71], v[70:71], 0, v[122:123]
	global_store_dwordx4 v[70:71], v[62:65], off sc1
	global_store_dwordx4 v[70:71], v[58:61], off offset:16 sc1
	s_waitcnt vmcnt(8)
	v_lshlrev_b32_e32 v62, 16, v76
	v_lshlrev_b32_e32 v58, 16, v74
	v_and_b32_e32 v59, 0xffff0000, v74
	v_lshlrev_b32_e32 v60, 16, v75
	v_and_b32_e32 v61, 0xffff0000, v75
	v_and_b32_e32 v63, 0xffff0000, v76
	v_lshlrev_b32_e32 v64, 16, v77
	v_and_b32_e32 v65, 0xffff0000, v77
	v_pk_add_f32 v[56:57], v[56:57], v[60:61]
	v_pk_add_f32 v[54:55], v[54:55], v[58:59]
	v_pk_add_f32 v[46:47], v[46:47], v[62:63]
	v_pk_add_f32 v[48:49], v[48:49], v[64:65]
	global_store_dwordx4 v[70:71], v[54:57], off offset:512 sc1
	global_store_dwordx4 v[70:71], v[46:49], off offset:528 sc1
	s_waitcnt vmcnt(9)
; #define PG8_BAR __builtin_amdgcn_s_barrier()
;     __device__ __forceinline__ void operator()(const f32x4 (&acc)[2][2][4][2], const Unit& u, int wr, int wc, int fr, int fq) const {
;     ...
;         for (int ai = 0; ai < 2; ++ai) {
;             u32x4 xr[4][2];
; #pragma unroll
;             for (int m = 0; m < 4; ++m)
; #pragma unroll
;                 for (int bj = 0; bj < 2; ++bj) xr[m][bj] = *(const u32x4*)(xb + (size_t)(u.pm * BM + ai * HALF + wr * 64 + m * 16 + fr) * 2048 + col0 + bj * HALF);
; #pragma unroll
;             for (int m = 0; m < 4; ++m) { const int row = u.pm * BM + ai * HALF + wr * 64 + m * 16 + fr; const size_t off = (size_t)row * 2048 + col0; float sq = 0.f;
; #pragma unroll
;                 for (int bj = 0; bj < 2; ++bj) { const size_t o2 = off + bj * HALF; const u32x4 xw = xr[m][bj];
;                     f32x4 x0, x1; x0[0] = __uint_as_float(xw.x << 16); x0[1] = __uint_as_float(xw.x & 0xffff0000u); x0[2] = __uint_as_float(xw.y << 16); x0[3] = __uint_as_float(xw.y & 0xffff0000u);
;                     x1[0] = __uint_as_float(xw.z << 16); x1[1] = __uint_as_float(xw.z & 0xffff0000u); x1[2] = __uint_as_float(xw.w << 16); x1[3] = __uint_as_float(xw.w & 0xffff0000u);
;                     x0 = x0 + acc[ai][bj][m][0]; x1 = x1 + acc[ai][bj][m][1];
;                     if (FINAL) { *(f32x4*)(out + o2) = x0; *(f32x4*)(out + o2 + 4) = x1; }
;                     else { u32x4 w; w.x = cvt_pk_bf16(x0[0], x0[1]); w.y = cvt_pk_bf16(x0[2], x0[3]); w.z = cvt_pk_bf16(x1[0], x1[1]); w.w = cvt_pk_bf16(x1[2], x1[3]); *(u32x4*)(xb + o2) = w; }
;                     sq += ((x0[0] * x0[0] + x0[1] * x0[1]) + (x0[2] * x0[2] + x0[3] * x0[3])) + ((x1[0] * x1[0] + x1[1] * x1[1]) + (x1[2] * x1[2] + x1[3] * x1[3])); }
; template <class Epi, class Sched, bool ALIGN_EPI = false, bool SP2 = false>
; __device__ __forceinline__ void gemm_phase(PG8_LAS unsigned char* lds, const Gemm g, const Sched& S, const Epi& E) {
;     ...
;         if constexpr (ALIGN_EPI) { if (wr == 0) PG8_BAR; }
;         if constexpr (!Epi::AFTER_DRAIN) { if constexpr (Epi::HAS_PREP) E(acc, cur, wr, wc, fr, fq, prep_gen & 1); else E(acc, cur, wr, wc, fr, fq); S.done(cur); }
;         if (!has_next) break;
; #pragma unroll
;         for (int a = 0; a < 2; ++a)
; #pragma unroll
;             for (int b = 0; b < 2; ++b)
; #pragma unroll
;                 for (int m = 0; m < 4; ++m)
; #pragma unroll
	v_lshlrev_b32_e32 v54, 16, v80
	v_lshlrev_b32_e32 v46, 16, v78
	v_and_b32_e32 v47, 0xffff0000, v78
	v_pk_add_f32 v[46:47], v[50:51], v[46:47]
	v_lshlrev_b64 v[50:51], 13, v[100:101]
	v_lshlrev_b32_e32 v48, 16, v79
	v_and_b32_e32 v49, 0xffff0000, v79
	v_and_b32_e32 v55, 0xffff0000, v80
	v_lshlrev_b32_e32 v56, 16, v81
	v_and_b32_e32 v57, 0xffff0000, v81
	v_lshl_add_u64 v[50:51], s[4:5], 0, v[50:51]
	v_pk_add_f32 v[48:49], v[52:53], v[48:49]
	v_pk_add_f32 v[44:45], v[44:45], v[56:57]
	v_pk_add_f32 v[42:43], v[42:43], v[54:55]
	v_lshl_add_u64 v[50:51], v[50:51], 0, v[122:123]
	global_store_dwordx4 v[50:51], v[46:49], off sc1
	global_store_dwordx4 v[50:51], v[42:45], off offset:16 sc1
	s_waitcnt vmcnt(10)
	v_lshlrev_b32_e32 v46, 16, v84
	v_lshlrev_b32_e32 v42, 16, v82
	v_and_b32_e32 v43, 0xffff0000, v82
	v_lshlrev_b32_e32 v44, 16, v83
	v_and_b32_e32 v45, 0xffff0000, v83
	v_and_b32_e32 v47, 0xffff0000, v84
	v_lshlrev_b32_e32 v48, 16, v85
	v_and_b32_e32 v49, 0xffff0000, v85
	v_pk_add_f32 v[40:41], v[40:41], v[44:45]
	v_pk_add_f32 v[38:39], v[38:39], v[42:43]
	v_pk_add_f32 v[30:31], v[30:31], v[46:47]
	v_pk_add_f32 v[32:33], v[32:33], v[48:49]
	global_store_dwordx4 v[50:51], v[38:41], off offset:512 sc1
	global_store_dwordx4 v[50:51], v[30:33], off offset:528 sc1
	s_waitcnt vmcnt(11)
	v_lshlrev_b32_e32 v38, 16, v88
	v_lshlrev_b32_e32 v30, 16, v86
	v_and_b32_e32 v31, 0xffff0000, v86
	v_pk_add_f32 v[30:31], v[34:35], v[30:31]
	v_lshlrev_b64 v[34:35], 13, v[102:103]
	v_lshlrev_b32_e32 v32, 16, v87
	v_and_b32_e32 v33, 0xffff0000, v87
	v_and_b32_e32 v39, 0xffff0000, v88
	v_lshlrev_b32_e32 v40, 16, v89
	v_and_b32_e32 v41, 0xffff0000, v89
	v_lshl_add_u64 v[34:35], s[4:5], 0, v[34:35]
	v_pk_add_f32 v[32:33], v[36:37], v[32:33]
	v_pk_add_f32 v[28:29], v[28:29], v[40:41]
	v_pk_add_f32 v[26:27], v[26:27], v[38:39]
	v_lshl_add_u64 v[34:35], v[34:35], 0, v[122:123]
	global_store_dwordx4 v[34:35], v[30:33], off sc1
	global_store_dwordx4 v[34:35], v[26:29], off offset:16 sc1
	s_waitcnt vmcnt(12)
	v_lshlrev_b32_e32 v30, 16, v92
	v_lshlrev_b32_e32 v26, 16, v90
	v_and_b32_e32 v27, 0xffff0000, v90
	v_lshlrev_b32_e32 v28, 16, v91
	v_and_b32_e32 v29, 0xffff0000, v91
	v_and_b32_e32 v31, 0xffff0000, v92
	v_lshlrev_b32_e32 v32, 16, v93
	v_and_b32_e32 v33, 0xffff0000, v93
	v_pk_add_f32 v[24:25], v[24:25], v[28:29]
	v_pk_add_f32 v[22:23], v[22:23], v[26:27]
	v_pk_add_f32 v[14:15], v[14:15], v[30:31]
	v_pk_add_f32 v[16:17], v[16:17], v[32:33]
	global_store_dwordx4 v[34:35], v[22:25], off offset:512 sc1
	global_store_dwordx4 v[34:35], v[14:17], off offset:528 sc1
	s_waitcnt vmcnt(13)
	v_lshlrev_b32_e32 v22, 16, v96
	v_lshlrev_b32_e32 v14, 16, v94
	v_and_b32_e32 v15, 0xffff0000, v94
	v_pk_add_f32 v[14:15], v[18:19], v[14:15]
	v_lshlrev_b64 v[18:19], 13, v[104:105]
	v_lshlrev_b32_e32 v16, 16, v95
	v_and_b32_e32 v17, 0xffff0000, v95
	v_and_b32_e32 v23, 0xffff0000, v96
	v_lshlrev_b32_e32 v24, 16, v97
	v_and_b32_e32 v25, 0xffff0000, v97
	v_lshl_add_u64 v[18:19], s[4:5], 0, v[18:19]
	v_pk_add_f32 v[16:17], v[20:21], v[16:17]
	v_pk_add_f32 v[12:13], v[12:13], v[24:25]
	v_pk_add_f32 v[10:11], v[10:11], v[22:23]
	v_lshl_add_u64 v[18:19], v[18:19], 0, v[122:123]
	global_store_dwordx4 v[18:19], v[14:17], off sc1
	global_store_dwordx4 v[18:19], v[10:13], off offset:16 sc1
	s_waitcnt vmcnt(14)
	v_lshlrev_b32_e32 v14, 16, v68
	v_lshlrev_b32_e32 v10, 16, v66
	v_and_b32_e32 v11, 0xffff0000, v66
	v_lshlrev_b32_e32 v12, 16, v67
	v_and_b32_e32 v13, 0xffff0000, v67
	v_and_b32_e32 v15, 0xffff0000, v68
	v_lshlrev_b32_e32 v16, 16, v69
	v_and_b32_e32 v17, 0xffff0000, v69
	v_pk_add_f32 v[8:9], v[8:9], v[12:13]
	v_pk_add_f32 v[6:7], v[6:7], v[10:11]
	v_pk_add_f32 v[4:5], v[4:5], v[16:17]
	v_pk_add_f32 v[2:3], v[2:3], v[14:15]
	global_store_dwordx4 v[18:19], v[6:9], off offset:512 sc1
	global_store_dwordx4 v[18:19], v[2:5], off offset:528 sc1
	s_cbranch_vccnz .LBB0_872
	s_andn2_b64 vcc, exec, s[12:13]
	s_cbranch_vccnz .LBB0_871
	s_barrier
	s_branch .LBB0_871
